# SSM: each lane owns one complex state (re/im chains in-lane, plain fmac instead of DPP, tables loaded in natural order), 7-op gelu; chunk epilogue hoist kept
# speedup vs baseline: 1.0050x; 1.0031x over previous
.LBB0_340:
	s_cmp_lt_i32 s96, 4
	s_cselect_b64 s[0:1], -1, 0
	s_and_b64 s[8:9], s[0:1], s[4:5]
	s_andn2_b64 vcc, exec, s[8:9]
	s_cbranch_vccnz .LBB0_393
	v_cmp_gt_u32_e32 vcc, 2, v190
	s_and_saveexec_b64 s[0:1], vcc
	v_lshlrev_b32_e32 v2, 2, v190
	v_add_u32_e32 v2, 0x21000, v2
	v_mov_b32_e32 v3, 0
	ds_write_b32 v2, v3
	s_mov_b64 exec, s[0:1]
	v_and_b32_e32 v172, 31, v191
	v_lshrrev_b32_e32 v173, 5, v191
	v_and_b32_e32 v174, 1, v191
	v_and_b32_e32 v175, 15, v191
	v_lshrrev_b32_e32 v176, 4, v191
	s_mul_i32 s20, s89, 0x3200
	v_lshl_add_u32 v151, v191, 2, s20
	v_mul_u32_u24_e32 v182, 0x110, v175
	v_lshl_add_u32 v182, v176, 4, v182
	v_add_u32_e32 v152, s20, v182
	v_lshlrev_b32_e32 v182, 5, v172
	v_lshl_add_u32 v150, v173, 4, v182
	v_xor_b32_e32 v193, 0x80, v150
	s_mov_b32 s66, 0x0f0f0f0f
	s_mov_b32 s67, 0x0f0f0f0f
	s_mov_b32 s68, 0xf0f0f0f0
	s_mov_b32 s69, 0xf0f0f0f0
	v_lshlrev_b32_e32 v182, 5, v172
	v_lshl_add_u32 v182, v173, 4, v182
	s_add_u32 s22, s20, 0x2200
	v_add_u32_e32 v162, s22, v182
	v_lshlrev_b32_e32 v182, 5, v175
	v_lshl_add_u32 v182, v176, 3, v182
	v_add_u32_e32 v163, s22, v182
	v_mul_u32_u24_e32 v182, 0x1800, v175
	v_lshl_add_u32 v154, v176, 3, v182
	v_add_u32_e32 v158, 0x18000, v154
	v_lshlrev_b32_e32 v182, 12, v175
	v_lshlrev_b32_e32 v182, 6, v175
	v_lshl_add_u32 v153, v176, 4, v182
	v_add_u32_e32 v157, 0x400, v153
	v_lshlrev_b32_e32 v182, 11, v175
	v_lshl_add_u32 v156, v176, 3, v182
	v_add_u32_e32 v159, 0x8000, v156
	s_and_b32 s21, s89, 3
	s_lshl_b32 s21, s21, 13
	s_add_u32 s21, s21, 0x19000
	v_lshlrev_b32_e32 v182, 5, v175
	v_lshl_add_u32 v182, v176, 3, v182
	v_add_u32_e32 v155, s21, v182
	v_lshrrev_b32_e32 v182, 3, v172
	v_lshlrev_b32_e32 v182, 10, v182
	v_and_b32_e32 v183, 7, v172
	v_lshl_add_u32 v182, v183, 5, v182
	v_lshl_add_u32 v177, v173, 8, v182
	v_lshlrev_b32_e32 v178, 4, v191
	v_lshlrev_b32_e32 v179, 3, v191
	v_lshlrev_b32_e32 v180, 2, v191
	v_add_u32_e32 v170, 0x4000, v180
	v_lshlrev_b32_e32 v181, 4, v176
	v_mov_b32_e32 v1, 0x3dd2d3e8
	s_waitcnt vmcnt(0) lgkmcnt(0)
	s_barrier
	s_cmp_lt_u32 s89, 4
	s_cbranch_scc0 .Lssm_ctx
	s_lshr_b32 s21, s89, 1
	s_and_b32 s22, s2, 7
	s_lshl_b32 s22, s22, 6
	s_lshr_b32 s26, s2, 3
	s_lshl_b32 s26, s26, 1
	s_add_u32 s22, s22, s26
	s_add_u32 s22, s22, s21
	s_lshr_b32 s23, s22, 6
	s_and_b32 s24, s22, 63
	s_lshl_b32 s25, s23, 10
	s_add_u32 s25, s25, 0x2000
	s_and_b32 s26, s89, 1
	s_cmp_eq_u32 s26, 0
	s_cbranch_scc0 .Lssm_lat_bwd
	s_add_u32 s28, s24, 0
	s_lshl_b32 s29, s28, 13
	s_add_u32 s29, s29, 0x200000
	s_add_u32 s10, s62, s29
	s_addc_u32 s11, s63, 0
	global_load_dwordx4 v[84:87], v177, s[10:11]
	global_load_dwordx4 v[88:91], v177, s[10:11] offset:16
	s_add_u32 s12, s10, 0x1000
	s_addc_u32 s13, s11, 0
	global_load_dwordx4 v[92:95], v177, s[12:13]
	global_load_dwordx4 v[96:99], v177, s[12:13] offset:16
	s_lshl_b32 s29, s28, 12
	s_add_u32 s29, s29, 0x300000
	s_add_u32 s16, s62, s29
	s_addc_u32 s17, s63, 0
	global_load_dwordx4 v[100:103], v178, s[16:17]
	global_load_dwordx4 v[104:107], v178, s[16:17] offset:1024
	global_load_dwordx4 v[108:111], v178, s[16:17] offset:2048
	global_load_dwordx4 v[112:115], v178, s[16:17] offset:3072
	s_lshl_b32 s29, s28, 9
	s_add_u32 s29, s29, 0x100000
	s_add_u32 s18, s62, s29
	s_addc_u32 s19, s63, 0
	global_load_dwordx2 v[116:117], v179, s[18:19]
	s_lshl_b32 s30, s23, 1
	s_lshl_b32 s30, s30, 15
	s_lshl_b32 s31, s24, 8
	s_add_u32 s30, s30, s31
	v_readlane_b32 s34, v254, 10
	v_readlane_b32 s35, v254, 11
	s_nop 3
	s_add_u32 s34, s34, s30
	s_addc_u32 s35, s35, 0
	global_load_dword v120, v180, s[34:35]
	global_load_dword v121, v170, s[34:35]
	v_readlane_b32 s34, v254, 28
	v_readlane_b32 s35, v254, 29
	s_nop 3
	s_lshl_b32 s31, s24, 6
	s_add_u32 s34, s34, s31
	s_addc_u32 s35, s35, 0
	global_load_dwordx4 v[164:167], v181, s[34:35]
	s_lshl_b32 s31, s25, 5
	s_lshl_b32 s29, s24, 19
	s_add_u32 s31, s31, s29
	s_add_u32 s31, s31, 0x16800000
	s_add_u32 s4, s62, s31
	s_addc_u32 s5, s63, 0
	s_lshl_b32 s31, s22, 1
	s_lshl_b32 s31, s31, 15
	s_add_u32 s31, s31, 0x4800000
	s_add_u32 s6, s62, s31
	s_addc_u32 s7, s63, 0
	s_add_u32 s34, s4, 0
	s_addc_u32 s35, s5, 0
	global_load_dwordx4 v[80:83], v150, s[34:35]
	global_load_dwordx4 v[194:197], v193, s[34:35]
	s_mov_b64 s[10:11], s[34:35]
	s_add_u32 s10, s10, 1024
	s_addc_u32 s11, s11, 0
	global_load_dwordx4 v[144:147], v150, s[10:11]
	global_load_dwordx4 v[168:171], v193, s[10:11]
	s_mov_b64 s[34:35], s[10:11]
	s_add_u32 s10, s10, 1024
	s_addc_u32 s11, s11, 0
	s_add_u32 s12, s6, 0
	s_addc_u32 s13, s7, 0
	s_mov_b32 s14, 0
	s_mov_b32 s40, 0xffff0000
	s_waitcnt vmcnt(0)
	v_xor_b32_e32 v118, 0x80000000, v117
.Lssm_tileA_d0m0:
	s_waitcnt vmcnt(6)
	v_cndmask_b32_e64 v124, 0, v80, s[66:67]
	v_cndmask_b32_e64 v125, 0, v81, s[66:67]
	v_cndmask_b32_e64 v126, 0, v82, s[66:67]
	v_cndmask_b32_e64 v127, 0, v83, s[66:67]
	v_cndmask_b32_e64 v132, 0, v194, s[66:67]
	v_cndmask_b32_e64 v133, 0, v195, s[66:67]
	v_cndmask_b32_e64 v134, 0, v196, s[66:67]
	v_cndmask_b32_e64 v135, 0, v197, s[66:67]
	v_mfma_f32_32x32x16_bf16 v[16:31], v[124:127], v[84:87], 0
	v_cndmask_b32_e64 v128, 0, v194, s[68:69]
	v_cndmask_b32_e64 v129, 0, v195, s[68:69]
	v_cndmask_b32_e64 v130, 0, v196, s[68:69]
	v_cndmask_b32_e64 v131, 0, v197, s[68:69]
	v_mfma_f32_32x32x16_bf16 v[32:47], v[124:127], v[88:91], 0
	v_cndmask_b32_e64 v136, 0, v80, s[68:69]
	v_cndmask_b32_e64 v137, 0, v81, s[68:69]
	v_cndmask_b32_e64 v138, 0, v82, s[68:69]
	v_cndmask_b32_e64 v139, 0, v83, s[68:69]
	v_mfma_f32_32x32x16_bf16 v[48:63], v[132:135], v[84:87], 0
	v_mfma_f32_32x32x16_bf16 v[64:79], v[132:135], v[88:91], 0
	v_mfma_f32_32x32x16_bf16 v[16:31], v[128:131], v[92:95], v[16:31]
	v_mfma_f32_32x32x16_bf16 v[32:47], v[128:131], v[96:99], v[32:47]
	v_mfma_f32_32x32x16_bf16 v[48:63], v[136:139], v[92:95], v[48:63]
	v_mfma_f32_32x32x16_bf16 v[64:79], v[136:139], v[96:99], v[64:79]
	s_nop 11
	global_load_dwordx4 v[80:83], v150, s[10:11]
	global_load_dwordx4 v[194:197], v193, s[10:11]
	s_add_u32 s34, s34, 1024
	s_addc_u32 s35, s35, 0
	s_add_u32 s10, s10, 1024
	s_addc_u32 s11, s11, 0
	v_fmac_f32_e32 v16, v116, v120
	v_fmac_f32_e32 v32, v116, v121
	v_fmac_f32_e32 v16, v118, v121
	v_fmac_f32_e32 v32, v117, v120
	v_cvt_pk_bf16_f32 v148, v16, v32
	ds_write_b32 v151, v148
	v_fmac_f32_e32 v17, v116, v16
	v_fmac_f32_e32 v33, v116, v32
	v_fmac_f32_e32 v17, v118, v32
	v_fmac_f32_e32 v33, v117, v16
	v_cvt_pk_bf16_f32 v149, v17, v33
	ds_write_b32 v151, v149 offset:272
	v_fmac_f32_e32 v18, v116, v17
	v_fmac_f32_e32 v34, v116, v33
	v_fmac_f32_e32 v18, v118, v33
	v_fmac_f32_e32 v34, v117, v17
	v_cvt_pk_bf16_f32 v148, v18, v34
	ds_write_b32 v151, v148 offset:544
	v_fmac_f32_e32 v19, v116, v18
	v_fmac_f32_e32 v35, v116, v34
	v_fmac_f32_e32 v19, v118, v34
	v_fmac_f32_e32 v35, v117, v18
	v_cvt_pk_bf16_f32 v149, v19, v35
	ds_write_b32 v151, v149 offset:816
	v_fmac_f32_e32 v48, v116, v19
	v_fmac_f32_e32 v64, v116, v35
	v_fmac_f32_e32 v48, v118, v35
	v_fmac_f32_e32 v64, v117, v19
	v_cvt_pk_bf16_f32 v148, v48, v64
	ds_write_b32 v151, v148 offset:1088
	v_fmac_f32_e32 v49, v116, v48
	v_fmac_f32_e32 v65, v116, v64
	v_fmac_f32_e32 v49, v118, v64
	v_fmac_f32_e32 v65, v117, v48
	v_cvt_pk_bf16_f32 v149, v49, v65
	ds_write_b32 v151, v149 offset:1360
	v_fmac_f32_e32 v50, v116, v49
	v_fmac_f32_e32 v66, v116, v65
	v_fmac_f32_e32 v50, v118, v65
	v_fmac_f32_e32 v66, v117, v49
	v_cvt_pk_bf16_f32 v148, v50, v66
	ds_write_b32 v151, v148 offset:1632
	v_fmac_f32_e32 v51, v116, v50
	v_fmac_f32_e32 v67, v116, v66
	v_fmac_f32_e32 v51, v118, v66
	v_fmac_f32_e32 v67, v117, v50
	v_cvt_pk_bf16_f32 v149, v51, v67
	ds_write_b32 v151, v149 offset:1904
	v_fmac_f32_e32 v20, v116, v51
	v_fmac_f32_e32 v36, v116, v67
	v_fmac_f32_e32 v20, v118, v67
	v_fmac_f32_e32 v36, v117, v51
	v_cvt_pk_bf16_f32 v148, v20, v36
	ds_write_b32 v151, v148 offset:2176
	v_fmac_f32_e32 v21, v116, v20
	v_fmac_f32_e32 v37, v116, v36
	v_fmac_f32_e32 v21, v118, v36
	v_fmac_f32_e32 v37, v117, v20
	v_cvt_pk_bf16_f32 v149, v21, v37
	ds_write_b32 v151, v149 offset:2448
	v_fmac_f32_e32 v22, v116, v21
	v_fmac_f32_e32 v38, v116, v37
	v_fmac_f32_e32 v22, v118, v37
	v_fmac_f32_e32 v38, v117, v21
	v_cvt_pk_bf16_f32 v148, v22, v38
	ds_write_b32 v151, v148 offset:2720
	v_fmac_f32_e32 v23, v116, v22
	v_fmac_f32_e32 v39, v116, v38
	v_fmac_f32_e32 v23, v118, v38
	v_fmac_f32_e32 v39, v117, v22
	v_cvt_pk_bf16_f32 v149, v23, v39
	ds_write_b32 v151, v149 offset:2992
	v_fmac_f32_e32 v52, v116, v23
	v_fmac_f32_e32 v68, v116, v39
	v_fmac_f32_e32 v52, v118, v39
	v_fmac_f32_e32 v68, v117, v23
	v_cvt_pk_bf16_f32 v148, v52, v68
	ds_write_b32 v151, v148 offset:3264
	v_fmac_f32_e32 v53, v116, v52
	v_fmac_f32_e32 v69, v116, v68
	v_fmac_f32_e32 v53, v118, v68
	v_fmac_f32_e32 v69, v117, v52
	v_cvt_pk_bf16_f32 v149, v53, v69
	ds_write_b32 v151, v149 offset:3536
	v_fmac_f32_e32 v54, v116, v53
	v_fmac_f32_e32 v70, v116, v69
	v_fmac_f32_e32 v54, v118, v69
	v_fmac_f32_e32 v70, v117, v53
	v_cvt_pk_bf16_f32 v148, v54, v70
	ds_write_b32 v151, v148 offset:3808
	v_fmac_f32_e32 v55, v116, v54
	v_fmac_f32_e32 v71, v116, v70
	v_fmac_f32_e32 v55, v118, v70
	v_fmac_f32_e32 v71, v117, v54
	v_cvt_pk_bf16_f32 v149, v55, v71
	ds_write_b32 v151, v149 offset:4080
	v_fmac_f32_e32 v24, v116, v55
	v_fmac_f32_e32 v40, v116, v71
	v_fmac_f32_e32 v24, v118, v71
	v_fmac_f32_e32 v40, v117, v55
	v_cvt_pk_bf16_f32 v148, v24, v40
	ds_write_b32 v151, v148 offset:4352
	v_fmac_f32_e32 v25, v116, v24
	v_fmac_f32_e32 v41, v116, v40
	v_fmac_f32_e32 v25, v118, v40
	v_fmac_f32_e32 v41, v117, v24
	v_cvt_pk_bf16_f32 v149, v25, v41
	ds_write_b32 v151, v149 offset:4624
	v_fmac_f32_e32 v26, v116, v25
	v_fmac_f32_e32 v42, v116, v41
	v_fmac_f32_e32 v26, v118, v41
	v_fmac_f32_e32 v42, v117, v25
	v_cvt_pk_bf16_f32 v148, v26, v42
	ds_write_b32 v151, v148 offset:4896
	v_fmac_f32_e32 v27, v116, v26
	v_fmac_f32_e32 v43, v116, v42
	v_fmac_f32_e32 v27, v118, v42
	v_fmac_f32_e32 v43, v117, v26
	v_cvt_pk_bf16_f32 v149, v27, v43
	ds_write_b32 v151, v149 offset:5168
	v_fmac_f32_e32 v56, v116, v27
	v_fmac_f32_e32 v72, v116, v43
	v_fmac_f32_e32 v56, v118, v43
	v_fmac_f32_e32 v72, v117, v27
	v_cvt_pk_bf16_f32 v148, v56, v72
	ds_write_b32 v151, v148 offset:5440
	v_fmac_f32_e32 v57, v116, v56
	v_fmac_f32_e32 v73, v116, v72
	v_fmac_f32_e32 v57, v118, v72
	v_fmac_f32_e32 v73, v117, v56
	v_cvt_pk_bf16_f32 v149, v57, v73
	ds_write_b32 v151, v149 offset:5712
	v_fmac_f32_e32 v58, v116, v57
	v_fmac_f32_e32 v74, v116, v73
	v_fmac_f32_e32 v58, v118, v73
	v_fmac_f32_e32 v74, v117, v57
	v_cvt_pk_bf16_f32 v148, v58, v74
	ds_write_b32 v151, v148 offset:5984
	v_fmac_f32_e32 v59, v116, v58
	v_fmac_f32_e32 v75, v116, v74
	v_fmac_f32_e32 v59, v118, v74
	v_fmac_f32_e32 v75, v117, v58
	v_cvt_pk_bf16_f32 v149, v59, v75
	ds_write_b32 v151, v149 offset:6256
	v_fmac_f32_e32 v28, v116, v59
	v_fmac_f32_e32 v44, v116, v75
	v_fmac_f32_e32 v28, v118, v75
	v_fmac_f32_e32 v44, v117, v59
	v_cvt_pk_bf16_f32 v148, v28, v44
	ds_write_b32 v151, v148 offset:6528
	v_fmac_f32_e32 v29, v116, v28
	v_fmac_f32_e32 v45, v116, v44
	v_fmac_f32_e32 v29, v118, v44
	v_fmac_f32_e32 v45, v117, v28
	v_cvt_pk_bf16_f32 v149, v29, v45
	ds_write_b32 v151, v149 offset:6800
	v_fmac_f32_e32 v30, v116, v29
	v_fmac_f32_e32 v46, v116, v45
	v_fmac_f32_e32 v30, v118, v45
	v_fmac_f32_e32 v46, v117, v29
	v_cvt_pk_bf16_f32 v148, v30, v46
	ds_write_b32 v151, v148 offset:7072
	v_fmac_f32_e32 v31, v116, v30
	v_fmac_f32_e32 v47, v116, v46
	v_fmac_f32_e32 v31, v118, v46
	v_fmac_f32_e32 v47, v117, v30
	v_cvt_pk_bf16_f32 v149, v31, v47
	ds_write_b32 v151, v149 offset:7344
	v_fmac_f32_e32 v60, v116, v31
	v_fmac_f32_e32 v76, v116, v47
	v_fmac_f32_e32 v60, v118, v47
	v_fmac_f32_e32 v76, v117, v31
	v_cvt_pk_bf16_f32 v148, v60, v76
	ds_write_b32 v151, v148 offset:7616
	v_fmac_f32_e32 v61, v116, v60
	v_fmac_f32_e32 v77, v116, v76
	v_fmac_f32_e32 v61, v118, v76
	v_fmac_f32_e32 v77, v117, v60
	v_cvt_pk_bf16_f32 v149, v61, v77
	ds_write_b32 v151, v149 offset:7888
	v_fmac_f32_e32 v62, v116, v61
	v_fmac_f32_e32 v78, v116, v77
	v_fmac_f32_e32 v62, v118, v77
	v_fmac_f32_e32 v78, v117, v61
	v_cvt_pk_bf16_f32 v148, v62, v78
	ds_write_b32 v151, v148 offset:8160
	v_fmac_f32_e32 v63, v116, v62
	v_fmac_f32_e32 v79, v116, v78
	v_fmac_f32_e32 v63, v118, v78
	v_fmac_f32_e32 v79, v117, v62
	v_cvt_pk_bf16_f32 v149, v63, v79
	ds_write_b32 v151, v149 offset:8432
	v_mov_b32_e32 v120, v63
	v_mov_b32_e32 v121, v79
	ds_read_b128 v[124:127], v152
	ds_read_b128 v[128:131], v152 offset:64
	ds_read_b128 v[132:135], v152 offset:128
	ds_read_b128 v[136:139], v152 offset:192
	s_waitcnt lgkmcnt(3)
	v_mfma_f32_16x16x32_bf16 v[140:143], v[100:103], v[124:127], 0
	s_waitcnt lgkmcnt(2)
	v_mfma_f32_16x16x32_bf16 v[140:143], v[104:107], v[128:131], v[140:143]
	s_waitcnt lgkmcnt(1)
	v_mfma_f32_16x16x32_bf16 v[140:143], v[108:111], v[132:135], v[140:143]
	s_waitcnt lgkmcnt(0)
	v_mfma_f32_16x16x32_bf16 v[140:143], v[112:115], v[136:139], v[140:143]
	s_nop 9
	global_store_dwordx4 v153, v[140:143], s[12:13]
	s_nop 1
	ds_read_b128 v[124:127], v152 offset:4352
	ds_read_b128 v[128:131], v152 offset:4416
	ds_read_b128 v[132:135], v152 offset:4480
	ds_read_b128 v[136:139], v152 offset:4544
	s_waitcnt lgkmcnt(3)
	v_mfma_f32_16x16x32_bf16 v[140:143], v[100:103], v[124:127], 0
	s_waitcnt lgkmcnt(2)
	v_mfma_f32_16x16x32_bf16 v[140:143], v[104:107], v[128:131], v[140:143]
	s_waitcnt lgkmcnt(1)
	v_mfma_f32_16x16x32_bf16 v[140:143], v[108:111], v[132:135], v[140:143]
	s_waitcnt lgkmcnt(0)
	v_mfma_f32_16x16x32_bf16 v[140:143], v[112:115], v[136:139], v[140:143]
	s_nop 9
	global_store_dwordx4 v157, v[140:143], s[12:13]
	s_nop 1
	s_add_u32 s12, s12, 2048
	s_addc_u32 s13, s13, 0
	s_waitcnt vmcnt(6)
	v_cndmask_b32_e64 v124, 0, v144, s[66:67]
	v_cndmask_b32_e64 v125, 0, v145, s[66:67]
	v_cndmask_b32_e64 v126, 0, v146, s[66:67]
	v_cndmask_b32_e64 v127, 0, v147, s[66:67]
	v_cndmask_b32_e64 v132, 0, v168, s[66:67]
	v_cndmask_b32_e64 v133, 0, v169, s[66:67]
	v_cndmask_b32_e64 v134, 0, v170, s[66:67]
	v_cndmask_b32_e64 v135, 0, v171, s[66:67]
	v_mfma_f32_32x32x16_bf16 v[16:31], v[124:127], v[84:87], 0
	v_cndmask_b32_e64 v128, 0, v168, s[68:69]
	v_cndmask_b32_e64 v129, 0, v169, s[68:69]
	v_cndmask_b32_e64 v130, 0, v170, s[68:69]
	v_cndmask_b32_e64 v131, 0, v171, s[68:69]
	v_mfma_f32_32x32x16_bf16 v[32:47], v[124:127], v[88:91], 0
	v_cndmask_b32_e64 v136, 0, v144, s[68:69]
	v_cndmask_b32_e64 v137, 0, v145, s[68:69]
	v_cndmask_b32_e64 v138, 0, v146, s[68:69]
	v_cndmask_b32_e64 v139, 0, v147, s[68:69]
	v_mfma_f32_32x32x16_bf16 v[48:63], v[132:135], v[84:87], 0
	v_mfma_f32_32x32x16_bf16 v[64:79], v[132:135], v[88:91], 0
	v_mfma_f32_32x32x16_bf16 v[16:31], v[128:131], v[92:95], v[16:31]
	v_mfma_f32_32x32x16_bf16 v[32:47], v[128:131], v[96:99], v[32:47]
	v_mfma_f32_32x32x16_bf16 v[48:63], v[136:139], v[92:95], v[48:63]
	v_mfma_f32_32x32x16_bf16 v[64:79], v[136:139], v[96:99], v[64:79]
	s_nop 11
	global_load_dwordx4 v[144:147], v150, s[10:11]
	global_load_dwordx4 v[168:171], v193, s[10:11]
	s_add_u32 s34, s34, 1024
	s_addc_u32 s35, s35, 0
	s_add_u32 s10, s10, 1024
	s_addc_u32 s11, s11, 0
	v_fmac_f32_e32 v16, v116, v120
	v_fmac_f32_e32 v32, v116, v121
	v_fmac_f32_e32 v16, v118, v121
	v_fmac_f32_e32 v32, v117, v120
	v_cvt_pk_bf16_f32 v148, v16, v32
	ds_write_b32 v151, v148
	v_fmac_f32_e32 v17, v116, v16
	v_fmac_f32_e32 v33, v116, v32
	v_fmac_f32_e32 v17, v118, v32
	v_fmac_f32_e32 v33, v117, v16
	v_cvt_pk_bf16_f32 v149, v17, v33
	ds_write_b32 v151, v149 offset:272
	v_fmac_f32_e32 v18, v116, v17
	v_fmac_f32_e32 v34, v116, v33
	v_fmac_f32_e32 v18, v118, v33
	v_fmac_f32_e32 v34, v117, v17
	v_cvt_pk_bf16_f32 v148, v18, v34
	ds_write_b32 v151, v148 offset:544
	v_fmac_f32_e32 v19, v116, v18
	v_fmac_f32_e32 v35, v116, v34
	v_fmac_f32_e32 v19, v118, v34
	v_fmac_f32_e32 v35, v117, v18
	v_cvt_pk_bf16_f32 v149, v19, v35
	ds_write_b32 v151, v149 offset:816
	v_fmac_f32_e32 v48, v116, v19
	v_fmac_f32_e32 v64, v116, v35
	v_fmac_f32_e32 v48, v118, v35
	v_fmac_f32_e32 v64, v117, v19
	v_cvt_pk_bf16_f32 v148, v48, v64
	ds_write_b32 v151, v148 offset:1088
	v_fmac_f32_e32 v49, v116, v48
	v_fmac_f32_e32 v65, v116, v64
	v_fmac_f32_e32 v49, v118, v64
	v_fmac_f32_e32 v65, v117, v48
	v_cvt_pk_bf16_f32 v149, v49, v65
	ds_write_b32 v151, v149 offset:1360
	v_fmac_f32_e32 v50, v116, v49
	v_fmac_f32_e32 v66, v116, v65
	v_fmac_f32_e32 v50, v118, v65
	v_fmac_f32_e32 v66, v117, v49
	v_cvt_pk_bf16_f32 v148, v50, v66
	ds_write_b32 v151, v148 offset:1632
	v_fmac_f32_e32 v51, v116, v50
	v_fmac_f32_e32 v67, v116, v66
	v_fmac_f32_e32 v51, v118, v66
	v_fmac_f32_e32 v67, v117, v50
	v_cvt_pk_bf16_f32 v149, v51, v67
	ds_write_b32 v151, v149 offset:1904
	v_fmac_f32_e32 v20, v116, v51
	v_fmac_f32_e32 v36, v116, v67
	v_fmac_f32_e32 v20, v118, v67
	v_fmac_f32_e32 v36, v117, v51
	v_cvt_pk_bf16_f32 v148, v20, v36
	ds_write_b32 v151, v148 offset:2176
	v_fmac_f32_e32 v21, v116, v20
	v_fmac_f32_e32 v37, v116, v36
	v_fmac_f32_e32 v21, v118, v36
	v_fmac_f32_e32 v37, v117, v20
	v_cvt_pk_bf16_f32 v149, v21, v37
	ds_write_b32 v151, v149 offset:2448
	v_fmac_f32_e32 v22, v116, v21
	v_fmac_f32_e32 v38, v116, v37
	v_fmac_f32_e32 v22, v118, v37
	v_fmac_f32_e32 v38, v117, v21
	v_cvt_pk_bf16_f32 v148, v22, v38
	ds_write_b32 v151, v148 offset:2720
	v_fmac_f32_e32 v23, v116, v22
	v_fmac_f32_e32 v39, v116, v38
	v_fmac_f32_e32 v23, v118, v38
	v_fmac_f32_e32 v39, v117, v22
	v_cvt_pk_bf16_f32 v149, v23, v39
	ds_write_b32 v151, v149 offset:2992
	v_fmac_f32_e32 v52, v116, v23
	v_fmac_f32_e32 v68, v116, v39
	v_fmac_f32_e32 v52, v118, v39
	v_fmac_f32_e32 v68, v117, v23
	v_cvt_pk_bf16_f32 v148, v52, v68
	ds_write_b32 v151, v148 offset:3264
	v_fmac_f32_e32 v53, v116, v52
	v_fmac_f32_e32 v69, v116, v68
	v_fmac_f32_e32 v53, v118, v68
	v_fmac_f32_e32 v69, v117, v52
	v_cvt_pk_bf16_f32 v149, v53, v69
	ds_write_b32 v151, v149 offset:3536
	v_fmac_f32_e32 v54, v116, v53
	v_fmac_f32_e32 v70, v116, v69
	v_fmac_f32_e32 v54, v118, v69
	v_fmac_f32_e32 v70, v117, v53
	v_cvt_pk_bf16_f32 v148, v54, v70
	ds_write_b32 v151, v148 offset:3808
	v_fmac_f32_e32 v55, v116, v54
	v_fmac_f32_e32 v71, v116, v70
	v_fmac_f32_e32 v55, v118, v70
	v_fmac_f32_e32 v71, v117, v54
	v_cvt_pk_bf16_f32 v149, v55, v71
	ds_write_b32 v151, v149 offset:4080
	v_fmac_f32_e32 v24, v116, v55
	v_fmac_f32_e32 v40, v116, v71
	v_fmac_f32_e32 v24, v118, v71
	v_fmac_f32_e32 v40, v117, v55
	v_cvt_pk_bf16_f32 v148, v24, v40
	ds_write_b32 v151, v148 offset:4352
	v_fmac_f32_e32 v25, v116, v24
	v_fmac_f32_e32 v41, v116, v40
	v_fmac_f32_e32 v25, v118, v40
	v_fmac_f32_e32 v41, v117, v24
	v_cvt_pk_bf16_f32 v149, v25, v41
	ds_write_b32 v151, v149 offset:4624
	v_fmac_f32_e32 v26, v116, v25
	v_fmac_f32_e32 v42, v116, v41
	v_fmac_f32_e32 v26, v118, v41
	v_fmac_f32_e32 v42, v117, v25
	v_cvt_pk_bf16_f32 v148, v26, v42
	ds_write_b32 v151, v148 offset:4896
	v_fmac_f32_e32 v27, v116, v26
	v_fmac_f32_e32 v43, v116, v42
	v_fmac_f32_e32 v27, v118, v42
	v_fmac_f32_e32 v43, v117, v26
	v_cvt_pk_bf16_f32 v149, v27, v43
	ds_write_b32 v151, v149 offset:5168
	v_fmac_f32_e32 v56, v116, v27
	v_fmac_f32_e32 v72, v116, v43
	v_fmac_f32_e32 v56, v118, v43
	v_fmac_f32_e32 v72, v117, v27
	v_cvt_pk_bf16_f32 v148, v56, v72
	ds_write_b32 v151, v148 offset:5440
	v_fmac_f32_e32 v57, v116, v56
	v_fmac_f32_e32 v73, v116, v72
	v_fmac_f32_e32 v57, v118, v72
	v_fmac_f32_e32 v73, v117, v56
	v_cvt_pk_bf16_f32 v149, v57, v73
	ds_write_b32 v151, v149 offset:5712
	v_fmac_f32_e32 v58, v116, v57
	v_fmac_f32_e32 v74, v116, v73
	v_fmac_f32_e32 v58, v118, v73
	v_fmac_f32_e32 v74, v117, v57
	v_cvt_pk_bf16_f32 v148, v58, v74
	ds_write_b32 v151, v148 offset:5984
	v_fmac_f32_e32 v59, v116, v58
	v_fmac_f32_e32 v75, v116, v74
	v_fmac_f32_e32 v59, v118, v74
	v_fmac_f32_e32 v75, v117, v58
	v_cvt_pk_bf16_f32 v149, v59, v75
	ds_write_b32 v151, v149 offset:6256
	v_fmac_f32_e32 v28, v116, v59
	v_fmac_f32_e32 v44, v116, v75
	v_fmac_f32_e32 v28, v118, v75
	v_fmac_f32_e32 v44, v117, v59
	v_cvt_pk_bf16_f32 v148, v28, v44
	ds_write_b32 v151, v148 offset:6528
	v_fmac_f32_e32 v29, v116, v28
	v_fmac_f32_e32 v45, v116, v44
	v_fmac_f32_e32 v29, v118, v44
	v_fmac_f32_e32 v45, v117, v28
	v_cvt_pk_bf16_f32 v149, v29, v45
	ds_write_b32 v151, v149 offset:6800
	v_fmac_f32_e32 v30, v116, v29
	v_fmac_f32_e32 v46, v116, v45
	v_fmac_f32_e32 v30, v118, v45
	v_fmac_f32_e32 v46, v117, v29
	v_cvt_pk_bf16_f32 v148, v30, v46
	ds_write_b32 v151, v148 offset:7072
	v_fmac_f32_e32 v31, v116, v30
	v_fmac_f32_e32 v47, v116, v46
	v_fmac_f32_e32 v31, v118, v46
	v_fmac_f32_e32 v47, v117, v30
	v_cvt_pk_bf16_f32 v149, v31, v47
	ds_write_b32 v151, v149 offset:7344
	v_fmac_f32_e32 v60, v116, v31
	v_fmac_f32_e32 v76, v116, v47
	v_fmac_f32_e32 v60, v118, v47
	v_fmac_f32_e32 v76, v117, v31
	v_cvt_pk_bf16_f32 v148, v60, v76
	ds_write_b32 v151, v148 offset:7616
	v_fmac_f32_e32 v61, v116, v60
	v_fmac_f32_e32 v77, v116, v76
	v_fmac_f32_e32 v61, v118, v76
	v_fmac_f32_e32 v77, v117, v60
	v_cvt_pk_bf16_f32 v149, v61, v77
	ds_write_b32 v151, v149 offset:7888
	v_fmac_f32_e32 v62, v116, v61
	v_fmac_f32_e32 v78, v116, v77
	v_fmac_f32_e32 v62, v118, v77
	v_fmac_f32_e32 v78, v117, v61
	v_cvt_pk_bf16_f32 v148, v62, v78
	ds_write_b32 v151, v148 offset:8160
	v_fmac_f32_e32 v63, v116, v62
	v_fmac_f32_e32 v79, v116, v78
	v_fmac_f32_e32 v63, v118, v78
	v_fmac_f32_e32 v79, v117, v62
	v_cvt_pk_bf16_f32 v149, v63, v79
	ds_write_b32 v151, v149 offset:8432
	v_mov_b32_e32 v120, v63
	v_mov_b32_e32 v121, v79
	ds_read_b128 v[124:127], v152
	ds_read_b128 v[128:131], v152 offset:64
	ds_read_b128 v[132:135], v152 offset:128
	ds_read_b128 v[136:139], v152 offset:192
	s_waitcnt lgkmcnt(3)
	v_mfma_f32_16x16x32_bf16 v[140:143], v[100:103], v[124:127], 0
	s_waitcnt lgkmcnt(2)
	v_mfma_f32_16x16x32_bf16 v[140:143], v[104:107], v[128:131], v[140:143]
	s_waitcnt lgkmcnt(1)
	v_mfma_f32_16x16x32_bf16 v[140:143], v[108:111], v[132:135], v[140:143]
	s_waitcnt lgkmcnt(0)
	v_mfma_f32_16x16x32_bf16 v[140:143], v[112:115], v[136:139], v[140:143]
	s_nop 9
	global_store_dwordx4 v153, v[140:143], s[12:13]
	s_nop 1
	ds_read_b128 v[124:127], v152 offset:4352
	ds_read_b128 v[128:131], v152 offset:4416
	ds_read_b128 v[132:135], v152 offset:4480
	ds_read_b128 v[136:139], v152 offset:4544
	s_waitcnt lgkmcnt(3)
	v_mfma_f32_16x16x32_bf16 v[140:143], v[100:103], v[124:127], 0
	s_waitcnt lgkmcnt(2)
	v_mfma_f32_16x16x32_bf16 v[140:143], v[104:107], v[128:131], v[140:143]
	s_waitcnt lgkmcnt(1)
	v_mfma_f32_16x16x32_bf16 v[140:143], v[108:111], v[132:135], v[140:143]
	s_waitcnt lgkmcnt(0)
	v_mfma_f32_16x16x32_bf16 v[140:143], v[112:115], v[136:139], v[140:143]
	s_nop 9
	global_store_dwordx4 v157, v[140:143], s[12:13]
	s_nop 1
	s_add_u32 s12, s12, 2048
	s_addc_u32 s13, s13, 0
	s_add_u32 s14, s14, 2
	s_cmp_lt_u32 s14, 16
	s_cbranch_scc1 .Lssm_tileA_d0m0
	s_waitcnt vmcnt(0) lgkmcnt(0)
	s_lshr_b32 s21, s89, 1
	s_lshl_b32 s21, s21, 2
	s_add_u32 s37, s21, 0x21000
	v_mov_b32_e32 v182, s37
	v_mov_b32_e32 v183, 1
	v_cmp_eq_u32_e32 vcc, 0, v191
	s_and_saveexec_b64 s[0:1], vcc
	ds_add_u32 v182, v183
	s_mov_b64 exec, s[0:1]
	s_waitcnt lgkmcnt(0)
	s_mov_b32 s38, 0

.Lssm_tileB_d0m0:
	s_waitcnt vmcnt(8)
	v_cndmask_b32_e64 v124, 0, v80, s[66:67]
	v_cndmask_b32_e64 v125, 0, v81, s[66:67]
	v_cndmask_b32_e64 v126, 0, v82, s[66:67]
	v_cndmask_b32_e64 v127, 0, v83, s[66:67]
	v_cndmask_b32_e64 v132, 0, v194, s[66:67]
	v_cndmask_b32_e64 v133, 0, v195, s[66:67]
	v_cndmask_b32_e64 v134, 0, v196, s[66:67]
	v_cndmask_b32_e64 v135, 0, v197, s[66:67]
	v_mfma_f32_32x32x16_bf16 v[16:31], v[124:127], v[84:87], 0
	v_cndmask_b32_e64 v128, 0, v194, s[68:69]
	v_cndmask_b32_e64 v129, 0, v195, s[68:69]
	v_cndmask_b32_e64 v130, 0, v196, s[68:69]
	v_cndmask_b32_e64 v131, 0, v197, s[68:69]
	v_mfma_f32_32x32x16_bf16 v[32:47], v[124:127], v[88:91], 0
	v_cndmask_b32_e64 v136, 0, v80, s[68:69]
	v_cndmask_b32_e64 v137, 0, v81, s[68:69]
	v_cndmask_b32_e64 v138, 0, v82, s[68:69]
	v_cndmask_b32_e64 v139, 0, v83, s[68:69]
	v_mfma_f32_32x32x16_bf16 v[48:63], v[132:135], v[84:87], 0
	v_mfma_f32_32x32x16_bf16 v[64:79], v[132:135], v[88:91], 0
	v_mfma_f32_32x32x16_bf16 v[16:31], v[128:131], v[92:95], v[16:31]
	v_mfma_f32_32x32x16_bf16 v[32:47], v[128:131], v[96:99], v[32:47]
	v_mfma_f32_32x32x16_bf16 v[48:63], v[136:139], v[92:95], v[48:63]
	v_mfma_f32_32x32x16_bf16 v[64:79], v[136:139], v[96:99], v[64:79]
	ds_write_b128 v162, v[80:83]
	global_load_dwordx4 v[172:175], v153, s[42:43]
	global_load_dwordx4 v[176:179], v157, s[42:43]
	s_add_u32 s42, s42, 2048
	s_addc_u32 s43, s43, 0
	s_nop 11
	global_load_dwordx4 v[80:83], v150, s[10:11]
	global_load_dwordx4 v[194:197], v193, s[10:11]
	s_add_u32 s34, s34, 1024
	s_addc_u32 s35, s35, 0
	s_add_u32 s10, s10, 1024
	s_addc_u32 s11, s11, 0
	v_fmac_f32_e32 v16, v116, v120
	v_fmac_f32_e32 v32, v116, v121
	v_fmac_f32_e32 v16, v118, v121
	v_fmac_f32_e32 v32, v117, v120
	v_cvt_pk_bf16_f32 v148, v16, v32
	ds_write_b32 v151, v148
	v_fmac_f32_e32 v17, v116, v16
	v_fmac_f32_e32 v33, v116, v32
	v_fmac_f32_e32 v17, v118, v32
	v_fmac_f32_e32 v33, v117, v16
	v_cvt_pk_bf16_f32 v149, v17, v33
	ds_write_b32 v151, v149 offset:272
	v_fmac_f32_e32 v18, v116, v17
	v_fmac_f32_e32 v34, v116, v33
	v_fmac_f32_e32 v18, v118, v33
	v_fmac_f32_e32 v34, v117, v17
	v_cvt_pk_bf16_f32 v148, v18, v34
	ds_write_b32 v151, v148 offset:544
	v_fmac_f32_e32 v19, v116, v18
	v_fmac_f32_e32 v35, v116, v34
	v_fmac_f32_e32 v19, v118, v34
	v_fmac_f32_e32 v35, v117, v18
	v_cvt_pk_bf16_f32 v149, v19, v35
	ds_write_b32 v151, v149 offset:816
	v_fmac_f32_e32 v48, v116, v19
	v_fmac_f32_e32 v64, v116, v35
	v_fmac_f32_e32 v48, v118, v35
	v_fmac_f32_e32 v64, v117, v19
	v_cvt_pk_bf16_f32 v148, v48, v64
	ds_write_b32 v151, v148 offset:1088
	v_fmac_f32_e32 v49, v116, v48
	v_fmac_f32_e32 v65, v116, v64
	v_fmac_f32_e32 v49, v118, v64
	v_fmac_f32_e32 v65, v117, v48
	v_cvt_pk_bf16_f32 v149, v49, v65
	ds_write_b32 v151, v149 offset:1360
	v_fmac_f32_e32 v50, v116, v49
	v_fmac_f32_e32 v66, v116, v65
	v_fmac_f32_e32 v50, v118, v65
	v_fmac_f32_e32 v66, v117, v49
	v_cvt_pk_bf16_f32 v148, v50, v66
	ds_write_b32 v151, v148 offset:1632
	v_fmac_f32_e32 v51, v116, v50
	v_fmac_f32_e32 v67, v116, v66
	v_fmac_f32_e32 v51, v118, v66
	v_fmac_f32_e32 v67, v117, v50
	v_cvt_pk_bf16_f32 v149, v51, v67
	ds_write_b32 v151, v149 offset:1904
	v_fmac_f32_e32 v20, v116, v51
	v_fmac_f32_e32 v36, v116, v67
	v_fmac_f32_e32 v20, v118, v67
	v_fmac_f32_e32 v36, v117, v51
	v_cvt_pk_bf16_f32 v148, v20, v36
	ds_write_b32 v151, v148 offset:2176
	v_fmac_f32_e32 v21, v116, v20
	v_fmac_f32_e32 v37, v116, v36
	v_fmac_f32_e32 v21, v118, v36
	v_fmac_f32_e32 v37, v117, v20
	v_cvt_pk_bf16_f32 v149, v21, v37
	ds_write_b32 v151, v149 offset:2448
	v_fmac_f32_e32 v22, v116, v21
	v_fmac_f32_e32 v38, v116, v37
	v_fmac_f32_e32 v22, v118, v37
	v_fmac_f32_e32 v38, v117, v21
	v_cvt_pk_bf16_f32 v148, v22, v38
	ds_write_b32 v151, v148 offset:2720
	v_fmac_f32_e32 v23, v116, v22
	v_fmac_f32_e32 v39, v116, v38
	v_fmac_f32_e32 v23, v118, v38
	v_fmac_f32_e32 v39, v117, v22
	v_cvt_pk_bf16_f32 v149, v23, v39
	ds_write_b32 v151, v149 offset:2992
	v_fmac_f32_e32 v52, v116, v23
	v_fmac_f32_e32 v68, v116, v39
	v_fmac_f32_e32 v52, v118, v39
	v_fmac_f32_e32 v68, v117, v23
	v_cvt_pk_bf16_f32 v148, v52, v68
	ds_write_b32 v151, v148 offset:3264
	v_fmac_f32_e32 v53, v116, v52
	v_fmac_f32_e32 v69, v116, v68
	v_fmac_f32_e32 v53, v118, v68
	v_fmac_f32_e32 v69, v117, v52
	v_cvt_pk_bf16_f32 v149, v53, v69
	ds_write_b32 v151, v149 offset:3536
	v_fmac_f32_e32 v54, v116, v53
	v_fmac_f32_e32 v70, v116, v69
	v_fmac_f32_e32 v54, v118, v69
	v_fmac_f32_e32 v70, v117, v53
	v_cvt_pk_bf16_f32 v148, v54, v70
	ds_write_b32 v151, v148 offset:3808
	v_fmac_f32_e32 v55, v116, v54
	v_fmac_f32_e32 v71, v116, v70
	v_fmac_f32_e32 v55, v118, v70
	v_fmac_f32_e32 v71, v117, v54
	v_cvt_pk_bf16_f32 v149, v55, v71
	ds_write_b32 v151, v149 offset:4080
	v_fmac_f32_e32 v24, v116, v55
	v_fmac_f32_e32 v40, v116, v71
	v_fmac_f32_e32 v24, v118, v71
	v_fmac_f32_e32 v40, v117, v55
	v_cvt_pk_bf16_f32 v148, v24, v40
	ds_write_b32 v151, v148 offset:4352
	v_fmac_f32_e32 v25, v116, v24
	v_fmac_f32_e32 v41, v116, v40
	v_fmac_f32_e32 v25, v118, v40
	v_fmac_f32_e32 v41, v117, v24
	v_cvt_pk_bf16_f32 v149, v25, v41
	ds_write_b32 v151, v149 offset:4624
	v_fmac_f32_e32 v26, v116, v25
	v_fmac_f32_e32 v42, v116, v41
	v_fmac_f32_e32 v26, v118, v41
	v_fmac_f32_e32 v42, v117, v25
	v_cvt_pk_bf16_f32 v148, v26, v42
	ds_write_b32 v151, v148 offset:4896
	v_fmac_f32_e32 v27, v116, v26
	v_fmac_f32_e32 v43, v116, v42
	v_fmac_f32_e32 v27, v118, v42
	v_fmac_f32_e32 v43, v117, v26
	v_cvt_pk_bf16_f32 v149, v27, v43
	ds_write_b32 v151, v149 offset:5168
	v_fmac_f32_e32 v56, v116, v27
	v_fmac_f32_e32 v72, v116, v43
	v_fmac_f32_e32 v56, v118, v43
	v_fmac_f32_e32 v72, v117, v27
	v_cvt_pk_bf16_f32 v148, v56, v72
	ds_write_b32 v151, v148 offset:5440
	v_fmac_f32_e32 v57, v116, v56
	v_fmac_f32_e32 v73, v116, v72
	v_fmac_f32_e32 v57, v118, v72
	v_fmac_f32_e32 v73, v117, v56
	v_cvt_pk_bf16_f32 v149, v57, v73
	ds_write_b32 v151, v149 offset:5712
	v_fmac_f32_e32 v58, v116, v57
	v_fmac_f32_e32 v74, v116, v73
	v_fmac_f32_e32 v58, v118, v73
	v_fmac_f32_e32 v74, v117, v57
	v_cvt_pk_bf16_f32 v148, v58, v74
	ds_write_b32 v151, v148 offset:5984
	v_fmac_f32_e32 v59, v116, v58
	v_fmac_f32_e32 v75, v116, v74
	v_fmac_f32_e32 v59, v118, v74
	v_fmac_f32_e32 v75, v117, v58
	v_cvt_pk_bf16_f32 v149, v59, v75
	ds_write_b32 v151, v149 offset:6256
	v_fmac_f32_e32 v28, v116, v59
	v_fmac_f32_e32 v44, v116, v75
	v_fmac_f32_e32 v28, v118, v75
	v_fmac_f32_e32 v44, v117, v59
	v_cvt_pk_bf16_f32 v148, v28, v44
	ds_write_b32 v151, v148 offset:6528
	v_fmac_f32_e32 v29, v116, v28
	v_fmac_f32_e32 v45, v116, v44
	v_fmac_f32_e32 v29, v118, v44
	v_fmac_f32_e32 v45, v117, v28
	v_cvt_pk_bf16_f32 v149, v29, v45
	ds_write_b32 v151, v149 offset:6800
	v_fmac_f32_e32 v30, v116, v29
	v_fmac_f32_e32 v46, v116, v45
	v_fmac_f32_e32 v30, v118, v45
	v_fmac_f32_e32 v46, v117, v29
	v_cvt_pk_bf16_f32 v148, v30, v46
	ds_write_b32 v151, v148 offset:7072
	v_fmac_f32_e32 v31, v116, v30
	v_fmac_f32_e32 v47, v116, v46
	v_fmac_f32_e32 v31, v118, v46
	v_fmac_f32_e32 v47, v117, v30
	v_cvt_pk_bf16_f32 v149, v31, v47
	ds_write_b32 v151, v149 offset:7344
	v_fmac_f32_e32 v60, v116, v31
	v_fmac_f32_e32 v76, v116, v47
	v_fmac_f32_e32 v60, v118, v47
	v_fmac_f32_e32 v76, v117, v31
	v_cvt_pk_bf16_f32 v148, v60, v76
	ds_write_b32 v151, v148 offset:7616
	v_fmac_f32_e32 v61, v116, v60
	v_fmac_f32_e32 v77, v116, v76
	v_fmac_f32_e32 v61, v118, v76
	v_fmac_f32_e32 v77, v117, v60
	v_cvt_pk_bf16_f32 v149, v61, v77
	ds_write_b32 v151, v149 offset:7888
	v_fmac_f32_e32 v62, v116, v61
	v_fmac_f32_e32 v78, v116, v77
	v_fmac_f32_e32 v62, v118, v77
	v_fmac_f32_e32 v78, v117, v61
	v_cvt_pk_bf16_f32 v148, v62, v78
	ds_write_b32 v151, v148 offset:8160
	v_fmac_f32_e32 v63, v116, v62
	v_fmac_f32_e32 v79, v116, v78
	v_fmac_f32_e32 v63, v118, v78
	v_fmac_f32_e32 v79, v117, v62
	v_cvt_pk_bf16_f32 v149, v63, v79
	ds_write_b32 v151, v149 offset:8432
	v_mov_b32_e32 v120, v63
	v_mov_b32_e32 v121, v79
	ds_read_b128 v[124:127], v152
	ds_read_b128 v[128:131], v152 offset:64
	ds_read_b128 v[132:135], v152 offset:128
	ds_read_b128 v[136:139], v152 offset:192
	ds_read_b64 v[160:161], v163
	s_waitcnt lgkmcnt(4)
	v_mfma_f32_16x16x32_bf16 v[140:143], v[100:103], v[124:127], 0
	s_waitcnt lgkmcnt(3)
	v_mfma_f32_16x16x32_bf16 v[140:143], v[104:107], v[128:131], v[140:143]
	s_waitcnt lgkmcnt(2)
	v_mfma_f32_16x16x32_bf16 v[140:143], v[108:111], v[132:135], v[140:143]
	s_waitcnt lgkmcnt(1)
	v_mfma_f32_16x16x32_bf16 v[140:143], v[112:115], v[136:139], v[140:143]
	s_nop 9
	s_waitcnt vmcnt(9) lgkmcnt(0)
	v_add_f32_e32 v182, v6, v140
	v_add_f32_e32 v183, v7, v141
	v_add_f32_e32 v184, v8, v142
	v_add_f32_e32 v185, v9, v143
	v_lshlrev_b32_e32 v186, 16, v160
	v_and_b32_e32 v187, 0xffff0000, v160
	v_lshlrev_b32_e32 v188, 16, v161
	v_and_b32_e32 v189, 0xffff0000, v161
	v_fmac_f32_e32 v182, v164, v186
	v_fmac_f32_e32 v183, v165, v187
	v_fmac_f32_e32 v184, v166, v188
	v_fmac_f32_e32 v185, v167, v189
	v_mul_f32_e32 v186, v182, v182
	v_mul_f32_e32 v187, v183, v183
	v_mul_f32_e32 v188, v184, v184
	v_mul_f32_e32 v189, v185, v185
	v_fmaak_f32 v186, v1, v186, 0x40135761
	v_fmaak_f32 v187, v1, v187, 0x40135761
	v_fmaak_f32 v188, v1, v188, 0x40135761
	v_fmaak_f32 v189, v1, v189, 0x40135761
	v_mul_f32_e32 v186, v182, v186
	v_mul_f32_e32 v187, v183, v187
	v_mul_f32_e32 v188, v184, v188
	v_mul_f32_e32 v189, v185, v189
	v_exp_f32_e64 v186, -v186
	v_exp_f32_e64 v187, -v187
	v_exp_f32_e64 v188, -v188
	v_exp_f32_e64 v189, -v189
	v_add_f32_e32 v186, 1.0, v186
	v_add_f32_e32 v187, 1.0, v187
	v_add_f32_e32 v188, 1.0, v188
	v_add_f32_e32 v189, 1.0, v189
	v_rcp_f32_e32 v186, v186
	v_rcp_f32_e32 v187, v187
	v_rcp_f32_e32 v188, v188
	v_rcp_f32_e32 v189, v189
	v_mul_f32_e32 v182, v182, v186
	v_mul_f32_e32 v183, v183, v187
	v_mul_f32_e32 v184, v184, v188
	v_mul_f32_e32 v185, v185, v189
	v_cvt_pk_bf16_f32 v148, v182, v183
	v_cvt_pk_bf16_f32 v149, v184, v185
	global_store_dwordx2 v156, v[148:149], s[12:13]
	ds_read_b128 v[124:127], v152 offset:4352
	ds_read_b128 v[128:131], v152 offset:4416
	ds_read_b128 v[132:135], v152 offset:4480
	ds_read_b128 v[136:139], v152 offset:4544
	ds_read_b64 v[160:161], v163 offset:512
	s_waitcnt lgkmcnt(4)
	v_mfma_f32_16x16x32_bf16 v[140:143], v[100:103], v[124:127], 0
	s_waitcnt lgkmcnt(3)
	v_mfma_f32_16x16x32_bf16 v[140:143], v[104:107], v[128:131], v[140:143]
	s_waitcnt lgkmcnt(2)
	v_mfma_f32_16x16x32_bf16 v[140:143], v[108:111], v[132:135], v[140:143]
	s_waitcnt lgkmcnt(1)
	v_mfma_f32_16x16x32_bf16 v[140:143], v[112:115], v[136:139], v[140:143]
	s_nop 9
	s_waitcnt vmcnt(9) lgkmcnt(0)
	v_add_f32_e32 v182, v10, v140
	v_add_f32_e32 v183, v11, v141
	v_add_f32_e32 v184, v12, v142
	v_add_f32_e32 v185, v13, v143
	v_lshlrev_b32_e32 v186, 16, v160
	v_and_b32_e32 v187, 0xffff0000, v160
	v_lshlrev_b32_e32 v188, 16, v161
	v_and_b32_e32 v189, 0xffff0000, v161
	v_fmac_f32_e32 v182, v164, v186
	v_fmac_f32_e32 v183, v165, v187
	v_fmac_f32_e32 v184, v166, v188
	v_fmac_f32_e32 v185, v167, v189
	v_mul_f32_e32 v186, v182, v182
	v_mul_f32_e32 v187, v183, v183
	v_mul_f32_e32 v188, v184, v184
	v_mul_f32_e32 v189, v185, v185
	v_fmaak_f32 v186, v1, v186, 0x40135761
	v_fmaak_f32 v187, v1, v187, 0x40135761
	v_fmaak_f32 v188, v1, v188, 0x40135761
	v_fmaak_f32 v189, v1, v189, 0x40135761
	v_mul_f32_e32 v186, v182, v186
	v_mul_f32_e32 v187, v183, v187
	v_mul_f32_e32 v188, v184, v188
	v_mul_f32_e32 v189, v185, v189
	v_exp_f32_e64 v186, -v186
	v_exp_f32_e64 v187, -v187
	v_exp_f32_e64 v188, -v188
	v_exp_f32_e64 v189, -v189
	v_add_f32_e32 v186, 1.0, v186
	v_add_f32_e32 v187, 1.0, v187
	v_add_f32_e32 v188, 1.0, v188
	v_add_f32_e32 v189, 1.0, v189
	v_rcp_f32_e32 v186, v186
	v_rcp_f32_e32 v187, v187
	v_rcp_f32_e32 v188, v188
	v_rcp_f32_e32 v189, v189
	v_mul_f32_e32 v182, v182, v186
	v_mul_f32_e32 v183, v183, v187
	v_mul_f32_e32 v184, v184, v188
	v_mul_f32_e32 v185, v185, v189
	v_cvt_pk_bf16_f32 v148, v182, v183
	v_cvt_pk_bf16_f32 v149, v184, v185
	global_store_dwordx2 v159, v[148:149], s[12:13]
	s_add_u32 s12, s12, 65536
	s_addc_u32 s13, s13, 0
	s_waitcnt vmcnt(8)
	v_cndmask_b32_e64 v124, 0, v144, s[66:67]
	v_cndmask_b32_e64 v125, 0, v145, s[66:67]
	v_cndmask_b32_e64 v126, 0, v146, s[66:67]
	v_cndmask_b32_e64 v127, 0, v147, s[66:67]
	v_cndmask_b32_e64 v132, 0, v168, s[66:67]
	v_cndmask_b32_e64 v133, 0, v169, s[66:67]
	v_cndmask_b32_e64 v134, 0, v170, s[66:67]
	v_cndmask_b32_e64 v135, 0, v171, s[66:67]
	v_mfma_f32_32x32x16_bf16 v[16:31], v[124:127], v[84:87], 0
	v_cndmask_b32_e64 v128, 0, v168, s[68:69]
	v_cndmask_b32_e64 v129, 0, v169, s[68:69]
	v_cndmask_b32_e64 v130, 0, v170, s[68:69]
	v_cndmask_b32_e64 v131, 0, v171, s[68:69]
	v_mfma_f32_32x32x16_bf16 v[32:47], v[124:127], v[88:91], 0
	v_cndmask_b32_e64 v136, 0, v144, s[68:69]
	v_cndmask_b32_e64 v137, 0, v145, s[68:69]
	v_cndmask_b32_e64 v138, 0, v146, s[68:69]
	v_cndmask_b32_e64 v139, 0, v147, s[68:69]
	v_mfma_f32_32x32x16_bf16 v[48:63], v[132:135], v[84:87], 0
	v_mfma_f32_32x32x16_bf16 v[64:79], v[132:135], v[88:91], 0
	v_mfma_f32_32x32x16_bf16 v[16:31], v[128:131], v[92:95], v[16:31]
	v_mfma_f32_32x32x16_bf16 v[32:47], v[128:131], v[96:99], v[32:47]
	v_mfma_f32_32x32x16_bf16 v[48:63], v[136:139], v[92:95], v[48:63]
	v_mfma_f32_32x32x16_bf16 v[64:79], v[136:139], v[96:99], v[64:79]
	ds_write_b128 v162, v[144:147]
	global_load_dwordx4 v[6:9], v153, s[42:43]
	global_load_dwordx4 v[10:13], v157, s[42:43]
	s_add_u32 s42, s42, 2048
	s_addc_u32 s43, s43, 0
	s_nop 11
	global_load_dwordx4 v[144:147], v150, s[10:11]
	global_load_dwordx4 v[168:171], v193, s[10:11]
	s_add_u32 s34, s34, 1024
	s_addc_u32 s35, s35, 0
	s_add_u32 s10, s10, 1024
	s_addc_u32 s11, s11, 0
	v_fmac_f32_e32 v16, v116, v120
	v_fmac_f32_e32 v32, v116, v121
	v_fmac_f32_e32 v16, v118, v121
	v_fmac_f32_e32 v32, v117, v120
	v_cvt_pk_bf16_f32 v148, v16, v32
	ds_write_b32 v151, v148
	v_fmac_f32_e32 v17, v116, v16
	v_fmac_f32_e32 v33, v116, v32
	v_fmac_f32_e32 v17, v118, v32
	v_fmac_f32_e32 v33, v117, v16
	v_cvt_pk_bf16_f32 v149, v17, v33
	ds_write_b32 v151, v149 offset:272
	v_fmac_f32_e32 v18, v116, v17
	v_fmac_f32_e32 v34, v116, v33
	v_fmac_f32_e32 v18, v118, v33
	v_fmac_f32_e32 v34, v117, v17
	v_cvt_pk_bf16_f32 v148, v18, v34
	ds_write_b32 v151, v148 offset:544
	v_fmac_f32_e32 v19, v116, v18
	v_fmac_f32_e32 v35, v116, v34
	v_fmac_f32_e32 v19, v118, v34
	v_fmac_f32_e32 v35, v117, v18
	v_cvt_pk_bf16_f32 v149, v19, v35
	ds_write_b32 v151, v149 offset:816
	v_fmac_f32_e32 v48, v116, v19
	v_fmac_f32_e32 v64, v116, v35
	v_fmac_f32_e32 v48, v118, v35
	v_fmac_f32_e32 v64, v117, v19
	v_cvt_pk_bf16_f32 v148, v48, v64
	ds_write_b32 v151, v148 offset:1088
	v_fmac_f32_e32 v49, v116, v48
	v_fmac_f32_e32 v65, v116, v64
	v_fmac_f32_e32 v49, v118, v64
	v_fmac_f32_e32 v65, v117, v48
	v_cvt_pk_bf16_f32 v149, v49, v65
	ds_write_b32 v151, v149 offset:1360
	v_fmac_f32_e32 v50, v116, v49
	v_fmac_f32_e32 v66, v116, v65
	v_fmac_f32_e32 v50, v118, v65
	v_fmac_f32_e32 v66, v117, v49
	v_cvt_pk_bf16_f32 v148, v50, v66
	ds_write_b32 v151, v148 offset:1632
	v_fmac_f32_e32 v51, v116, v50
	v_fmac_f32_e32 v67, v116, v66
	v_fmac_f32_e32 v51, v118, v66
	v_fmac_f32_e32 v67, v117, v50
	v_cvt_pk_bf16_f32 v149, v51, v67
	ds_write_b32 v151, v149 offset:1904
	v_fmac_f32_e32 v20, v116, v51
	v_fmac_f32_e32 v36, v116, v67
	v_fmac_f32_e32 v20, v118, v67
	v_fmac_f32_e32 v36, v117, v51
	v_cvt_pk_bf16_f32 v148, v20, v36
	ds_write_b32 v151, v148 offset:2176
	v_fmac_f32_e32 v21, v116, v20
	v_fmac_f32_e32 v37, v116, v36
	v_fmac_f32_e32 v21, v118, v36
	v_fmac_f32_e32 v37, v117, v20
	v_cvt_pk_bf16_f32 v149, v21, v37
	ds_write_b32 v151, v149 offset:2448
	v_fmac_f32_e32 v22, v116, v21
	v_fmac_f32_e32 v38, v116, v37
	v_fmac_f32_e32 v22, v118, v37
	v_fmac_f32_e32 v38, v117, v21
	v_cvt_pk_bf16_f32 v148, v22, v38
	ds_write_b32 v151, v148 offset:2720
	v_fmac_f32_e32 v23, v116, v22
	v_fmac_f32_e32 v39, v116, v38
	v_fmac_f32_e32 v23, v118, v38
	v_fmac_f32_e32 v39, v117, v22
	v_cvt_pk_bf16_f32 v149, v23, v39
	ds_write_b32 v151, v149 offset:2992
	v_fmac_f32_e32 v52, v116, v23
	v_fmac_f32_e32 v68, v116, v39
	v_fmac_f32_e32 v52, v118, v39
	v_fmac_f32_e32 v68, v117, v23
	v_cvt_pk_bf16_f32 v148, v52, v68
	ds_write_b32 v151, v148 offset:3264
	v_fmac_f32_e32 v53, v116, v52
	v_fmac_f32_e32 v69, v116, v68
	v_fmac_f32_e32 v53, v118, v68
	v_fmac_f32_e32 v69, v117, v52
	v_cvt_pk_bf16_f32 v149, v53, v69
	ds_write_b32 v151, v149 offset:3536
	v_fmac_f32_e32 v54, v116, v53
	v_fmac_f32_e32 v70, v116, v69
	v_fmac_f32_e32 v54, v118, v69
	v_fmac_f32_e32 v70, v117, v53
	v_cvt_pk_bf16_f32 v148, v54, v70
	ds_write_b32 v151, v148 offset:3808
	v_fmac_f32_e32 v55, v116, v54
	v_fmac_f32_e32 v71, v116, v70
	v_fmac_f32_e32 v55, v118, v70
	v_fmac_f32_e32 v71, v117, v54
	v_cvt_pk_bf16_f32 v149, v55, v71
	ds_write_b32 v151, v149 offset:4080
	v_fmac_f32_e32 v24, v116, v55
	v_fmac_f32_e32 v40, v116, v71
	v_fmac_f32_e32 v24, v118, v71
	v_fmac_f32_e32 v40, v117, v55
	v_cvt_pk_bf16_f32 v148, v24, v40
	ds_write_b32 v151, v148 offset:4352
	v_fmac_f32_e32 v25, v116, v24
	v_fmac_f32_e32 v41, v116, v40
	v_fmac_f32_e32 v25, v118, v40
	v_fmac_f32_e32 v41, v117, v24
	v_cvt_pk_bf16_f32 v149, v25, v41
	ds_write_b32 v151, v149 offset:4624
	v_fmac_f32_e32 v26, v116, v25
	v_fmac_f32_e32 v42, v116, v41
	v_fmac_f32_e32 v26, v118, v41
	v_fmac_f32_e32 v42, v117, v25
	v_cvt_pk_bf16_f32 v148, v26, v42
	ds_write_b32 v151, v148 offset:4896
	v_fmac_f32_e32 v27, v116, v26
	v_fmac_f32_e32 v43, v116, v42
	v_fmac_f32_e32 v27, v118, v42
	v_fmac_f32_e32 v43, v117, v26
	v_cvt_pk_bf16_f32 v149, v27, v43
	ds_write_b32 v151, v149 offset:5168
	v_fmac_f32_e32 v56, v116, v27
	v_fmac_f32_e32 v72, v116, v43
	v_fmac_f32_e32 v56, v118, v43
	v_fmac_f32_e32 v72, v117, v27
	v_cvt_pk_bf16_f32 v148, v56, v72
	ds_write_b32 v151, v148 offset:5440
	v_fmac_f32_e32 v57, v116, v56
	v_fmac_f32_e32 v73, v116, v72
	v_fmac_f32_e32 v57, v118, v72
	v_fmac_f32_e32 v73, v117, v56
	v_cvt_pk_bf16_f32 v149, v57, v73
	ds_write_b32 v151, v149 offset:5712
	v_fmac_f32_e32 v58, v116, v57
	v_fmac_f32_e32 v74, v116, v73
	v_fmac_f32_e32 v58, v118, v73
	v_fmac_f32_e32 v74, v117, v57
	v_cvt_pk_bf16_f32 v148, v58, v74
	ds_write_b32 v151, v148 offset:5984
	v_fmac_f32_e32 v59, v116, v58
	v_fmac_f32_e32 v75, v116, v74
	v_fmac_f32_e32 v59, v118, v74
	v_fmac_f32_e32 v75, v117, v58
	v_cvt_pk_bf16_f32 v149, v59, v75
	ds_write_b32 v151, v149 offset:6256
	v_fmac_f32_e32 v28, v116, v59
	v_fmac_f32_e32 v44, v116, v75
	v_fmac_f32_e32 v28, v118, v75
	v_fmac_f32_e32 v44, v117, v59
	v_cvt_pk_bf16_f32 v148, v28, v44
	ds_write_b32 v151, v148 offset:6528
	v_fmac_f32_e32 v29, v116, v28
	v_fmac_f32_e32 v45, v116, v44
	v_fmac_f32_e32 v29, v118, v44
	v_fmac_f32_e32 v45, v117, v28
	v_cvt_pk_bf16_f32 v149, v29, v45
	ds_write_b32 v151, v149 offset:6800
	v_fmac_f32_e32 v30, v116, v29
	v_fmac_f32_e32 v46, v116, v45
	v_fmac_f32_e32 v30, v118, v45
	v_fmac_f32_e32 v46, v117, v29
	v_cvt_pk_bf16_f32 v148, v30, v46
	ds_write_b32 v151, v148 offset:7072
	v_fmac_f32_e32 v31, v116, v30
	v_fmac_f32_e32 v47, v116, v46
	v_fmac_f32_e32 v31, v118, v46
	v_fmac_f32_e32 v47, v117, v30
	v_cvt_pk_bf16_f32 v149, v31, v47
	ds_write_b32 v151, v149 offset:7344
	v_fmac_f32_e32 v60, v116, v31
	v_fmac_f32_e32 v76, v116, v47
	v_fmac_f32_e32 v60, v118, v47
	v_fmac_f32_e32 v76, v117, v31
	v_cvt_pk_bf16_f32 v148, v60, v76
	ds_write_b32 v151, v148 offset:7616
	v_fmac_f32_e32 v61, v116, v60
	v_fmac_f32_e32 v77, v116, v76
	v_fmac_f32_e32 v61, v118, v76
	v_fmac_f32_e32 v77, v117, v60
	v_cvt_pk_bf16_f32 v149, v61, v77
	ds_write_b32 v151, v149 offset:7888
	v_fmac_f32_e32 v62, v116, v61
	v_fmac_f32_e32 v78, v116, v77
	v_fmac_f32_e32 v62, v118, v77
	v_fmac_f32_e32 v78, v117, v61
	v_cvt_pk_bf16_f32 v148, v62, v78
	ds_write_b32 v151, v148 offset:8160
	v_fmac_f32_e32 v63, v116, v62
	v_fmac_f32_e32 v79, v116, v78
	v_fmac_f32_e32 v63, v118, v78
	v_fmac_f32_e32 v79, v117, v62
	v_cvt_pk_bf16_f32 v149, v63, v79
	ds_write_b32 v151, v149 offset:8432
	v_mov_b32_e32 v120, v63
	v_mov_b32_e32 v121, v79
	ds_read_b128 v[124:127], v152
	ds_read_b128 v[128:131], v152 offset:64
	ds_read_b128 v[132:135], v152 offset:128
	ds_read_b128 v[136:139], v152 offset:192
	ds_read_b64 v[160:161], v163
	s_waitcnt lgkmcnt(4)
	v_mfma_f32_16x16x32_bf16 v[140:143], v[100:103], v[124:127], 0
	s_waitcnt lgkmcnt(3)
	v_mfma_f32_16x16x32_bf16 v[140:143], v[104:107], v[128:131], v[140:143]
	s_waitcnt lgkmcnt(2)
	v_mfma_f32_16x16x32_bf16 v[140:143], v[108:111], v[132:135], v[140:143]
	s_waitcnt lgkmcnt(1)
	v_mfma_f32_16x16x32_bf16 v[140:143], v[112:115], v[136:139], v[140:143]
	s_nop 9
	s_waitcnt vmcnt(9) lgkmcnt(0)
	v_add_f32_e32 v182, v172, v140
	v_add_f32_e32 v183, v173, v141
	v_add_f32_e32 v184, v174, v142
	v_add_f32_e32 v185, v175, v143
	v_lshlrev_b32_e32 v186, 16, v160
	v_and_b32_e32 v187, 0xffff0000, v160
	v_lshlrev_b32_e32 v188, 16, v161
	v_and_b32_e32 v189, 0xffff0000, v161
	v_fmac_f32_e32 v182, v164, v186
	v_fmac_f32_e32 v183, v165, v187
	v_fmac_f32_e32 v184, v166, v188
	v_fmac_f32_e32 v185, v167, v189
	v_mul_f32_e32 v186, v182, v182
	v_mul_f32_e32 v187, v183, v183
	v_mul_f32_e32 v188, v184, v184
	v_mul_f32_e32 v189, v185, v185
	v_fmaak_f32 v186, v1, v186, 0x40135761
	v_fmaak_f32 v187, v1, v187, 0x40135761
	v_fmaak_f32 v188, v1, v188, 0x40135761
	v_fmaak_f32 v189, v1, v189, 0x40135761
	v_mul_f32_e32 v186, v182, v186
	v_mul_f32_e32 v187, v183, v187
	v_mul_f32_e32 v188, v184, v188
	v_mul_f32_e32 v189, v185, v189
	v_exp_f32_e64 v186, -v186
	v_exp_f32_e64 v187, -v187
	v_exp_f32_e64 v188, -v188
	v_exp_f32_e64 v189, -v189
	v_add_f32_e32 v186, 1.0, v186
	v_add_f32_e32 v187, 1.0, v187
	v_add_f32_e32 v188, 1.0, v188
	v_add_f32_e32 v189, 1.0, v189
	v_rcp_f32_e32 v186, v186
	v_rcp_f32_e32 v187, v187
	v_rcp_f32_e32 v188, v188
	v_rcp_f32_e32 v189, v189
	v_mul_f32_e32 v182, v182, v186
	v_mul_f32_e32 v183, v183, v187
	v_mul_f32_e32 v184, v184, v188
	v_mul_f32_e32 v185, v185, v189
	v_cvt_pk_bf16_f32 v148, v182, v183
	v_cvt_pk_bf16_f32 v149, v184, v185
	global_store_dwordx2 v156, v[148:149], s[12:13]
	ds_read_b128 v[124:127], v152 offset:4352
	ds_read_b128 v[128:131], v152 offset:4416
	ds_read_b128 v[132:135], v152 offset:4480
	ds_read_b128 v[136:139], v152 offset:4544
	ds_read_b64 v[160:161], v163 offset:512
	s_waitcnt lgkmcnt(4)
	v_mfma_f32_16x16x32_bf16 v[140:143], v[100:103], v[124:127], 0
	s_waitcnt lgkmcnt(3)
	v_mfma_f32_16x16x32_bf16 v[140:143], v[104:107], v[128:131], v[140:143]
	s_waitcnt lgkmcnt(2)
	v_mfma_f32_16x16x32_bf16 v[140:143], v[108:111], v[132:135], v[140:143]
	s_waitcnt lgkmcnt(1)
	v_mfma_f32_16x16x32_bf16 v[140:143], v[112:115], v[136:139], v[140:143]
	s_nop 9
	s_waitcnt vmcnt(9) lgkmcnt(0)
	v_add_f32_e32 v182, v176, v140
	v_add_f32_e32 v183, v177, v141
	v_add_f32_e32 v184, v178, v142
	v_add_f32_e32 v185, v179, v143
	v_lshlrev_b32_e32 v186, 16, v160
	v_and_b32_e32 v187, 0xffff0000, v160
	v_lshlrev_b32_e32 v188, 16, v161
	v_and_b32_e32 v189, 0xffff0000, v161
	v_fmac_f32_e32 v182, v164, v186
	v_fmac_f32_e32 v183, v165, v187
	v_fmac_f32_e32 v184, v166, v188
	v_fmac_f32_e32 v185, v167, v189
	v_mul_f32_e32 v186, v182, v182
	v_mul_f32_e32 v187, v183, v183
	v_mul_f32_e32 v188, v184, v184
	v_mul_f32_e32 v189, v185, v185
	v_fmaak_f32 v186, v1, v186, 0x40135761
	v_fmaak_f32 v187, v1, v187, 0x40135761
	v_fmaak_f32 v188, v1, v188, 0x40135761
	v_fmaak_f32 v189, v1, v189, 0x40135761
	v_mul_f32_e32 v186, v182, v186
	v_mul_f32_e32 v187, v183, v187
	v_mul_f32_e32 v188, v184, v188
	v_mul_f32_e32 v189, v185, v189
	v_exp_f32_e64 v186, -v186
	v_exp_f32_e64 v187, -v187
	v_exp_f32_e64 v188, -v188
	v_exp_f32_e64 v189, -v189
	v_add_f32_e32 v186, 1.0, v186
	v_add_f32_e32 v187, 1.0, v187
	v_add_f32_e32 v188, 1.0, v188
	v_add_f32_e32 v189, 1.0, v189
	v_rcp_f32_e32 v186, v186
	v_rcp_f32_e32 v187, v187
	v_rcp_f32_e32 v188, v188
	v_rcp_f32_e32 v189, v189
	v_mul_f32_e32 v182, v182, v186
	v_mul_f32_e32 v183, v183, v187
	v_mul_f32_e32 v184, v184, v188
	v_mul_f32_e32 v185, v185, v189
	v_cvt_pk_bf16_f32 v148, v182, v183
	v_cvt_pk_bf16_f32 v149, v184, v185
	global_store_dwordx2 v159, v[148:149], s[12:13]
	s_add_u32 s12, s12, 65536
	s_addc_u32 s13, s13, 0
	s_add_u32 s14, s14, 2
	s_cmp_lt_u32 s14, 32
	s_cbranch_scc1 .Lssm_tileB_d0m0
	s_waitcnt vmcnt(0) lgkmcnt(0)
	s_branch .Lssm_lat_join
.Lssm_lat_bwd:
	s_add_u32 s28, s24, 64
	s_lshl_b32 s29, s28, 13
	s_add_u32 s29, s29, 0x200000
	s_add_u32 s10, s62, s29
	s_addc_u32 s11, s63, 0
	global_load_dwordx4 v[84:87], v177, s[10:11]
	global_load_dwordx4 v[88:91], v177, s[10:11] offset:16
	s_add_u32 s12, s10, 0x1000
	s_addc_u32 s13, s11, 0
	global_load_dwordx4 v[92:95], v177, s[12:13]
	global_load_dwordx4 v[96:99], v177, s[12:13] offset:16
	s_lshl_b32 s29, s28, 12
	s_add_u32 s29, s29, 0x300000
	s_add_u32 s16, s62, s29
	s_addc_u32 s17, s63, 0
	global_load_dwordx4 v[100:103], v178, s[16:17]
	global_load_dwordx4 v[104:107], v178, s[16:17] offset:1024
	global_load_dwordx4 v[108:111], v178, s[16:17] offset:2048
	global_load_dwordx4 v[112:115], v178, s[16:17] offset:3072
	s_lshl_b32 s29, s28, 9
	s_add_u32 s29, s29, 0x100000
	s_add_u32 s18, s62, s29
	s_addc_u32 s19, s63, 0
	global_load_dwordx2 v[116:117], v179, s[18:19]
	s_lshl_b32 s30, s23, 1
	s_add_u32 s30, s30, 1
	s_lshl_b32 s30, s30, 15
	s_lshl_b32 s31, s24, 8
	s_add_u32 s30, s30, s31
	v_readlane_b32 s34, v254, 10
	v_readlane_b32 s35, v254, 11
	s_nop 3
	s_add_u32 s34, s34, s30
	s_addc_u32 s35, s35, 0
	global_load_dword v120, v180, s[34:35]
	global_load_dword v121, v170, s[34:35]
	v_readlane_b32 s34, v254, 28
	v_readlane_b32 s35, v254, 29
	s_nop 3
	s_lshl_b32 s31, s24, 6
	s_add_u32 s34, s34, s31
	s_addc_u32 s35, s35, 0
	global_load_dwordx4 v[164:167], v181, s[34:35]
	s_lshl_b32 s31, s25, 5
	s_lshl_b32 s29, s24, 19
	s_add_u32 s31, s31, s29
	s_add_u32 s31, s31, 0x16800000
	s_add_u32 s4, s62, s31
	s_addc_u32 s5, s63, 0
	s_lshl_b32 s31, s22, 1
	s_add_u32 s31, s31, 1
	s_lshl_b32 s31, s31, 15
	s_add_u32 s31, s31, 0x4800000
	s_add_u32 s6, s62, s31
	s_addc_u32 s7, s63, 0
	s_add_u32 s34, s4, 31744
	s_addc_u32 s35, s5, 0
	global_load_dwordx4 v[80:83], v150, s[34:35]
	global_load_dwordx4 v[194:197], v193, s[34:35]
	s_mov_b64 s[10:11], s[34:35]
	s_sub_u32 s10, s10, 1024
	s_subb_u32 s11, s11, 0
	global_load_dwordx4 v[144:147], v150, s[10:11]
	global_load_dwordx4 v[168:171], v193, s[10:11]
	s_mov_b64 s[34:35], s[10:11]
	s_sub_u32 s10, s10, 1024
	s_subb_u32 s11, s11, 0
	s_add_u32 s12, s6, 30720
	s_addc_u32 s13, s7, 0
	s_mov_b32 s14, 0
	s_mov_b32 s40, 0xffff0000
	s_waitcnt vmcnt(0)
	v_xor_b32_e32 v118, 0x80000000, v117
.Lssm_tileA_d1m0:
	s_waitcnt vmcnt(6)
	v_cndmask_b32_e64 v124, 0, v80, s[66:67]
	v_cndmask_b32_e64 v125, 0, v81, s[66:67]
	v_cndmask_b32_e64 v126, 0, v82, s[66:67]
	v_cndmask_b32_e64 v127, 0, v83, s[66:67]
	v_cndmask_b32_e64 v132, 0, v194, s[66:67]
	v_cndmask_b32_e64 v133, 0, v195, s[66:67]
	v_cndmask_b32_e64 v134, 0, v196, s[66:67]
	v_cndmask_b32_e64 v135, 0, v197, s[66:67]
	v_mfma_f32_32x32x16_bf16 v[16:31], v[124:127], v[84:87], 0
	v_cndmask_b32_e64 v128, 0, v194, s[68:69]
	v_cndmask_b32_e64 v129, 0, v195, s[68:69]
	v_cndmask_b32_e64 v130, 0, v196, s[68:69]
	v_cndmask_b32_e64 v131, 0, v197, s[68:69]
	v_mfma_f32_32x32x16_bf16 v[32:47], v[124:127], v[88:91], 0
	v_cndmask_b32_e64 v136, 0, v80, s[68:69]
	v_cndmask_b32_e64 v137, 0, v81, s[68:69]
	v_cndmask_b32_e64 v138, 0, v82, s[68:69]
	v_cndmask_b32_e64 v139, 0, v83, s[68:69]
	v_mfma_f32_32x32x16_bf16 v[48:63], v[132:135], v[84:87], 0
	v_mfma_f32_32x32x16_bf16 v[64:79], v[132:135], v[88:91], 0
	v_mfma_f32_32x32x16_bf16 v[16:31], v[128:131], v[92:95], v[16:31]
	v_mfma_f32_32x32x16_bf16 v[32:47], v[128:131], v[96:99], v[32:47]
	v_mfma_f32_32x32x16_bf16 v[48:63], v[136:139], v[92:95], v[48:63]
	v_mfma_f32_32x32x16_bf16 v[64:79], v[136:139], v[96:99], v[64:79]
	s_nop 11
	global_load_dwordx4 v[80:83], v150, s[10:11]
	global_load_dwordx4 v[194:197], v193, s[10:11]
	s_sub_u32 s34, s34, 1024
	s_subb_u32 s35, s35, 0
	s_sub_u32 s10, s10, 1024
	s_subb_u32 s11, s11, 0
	v_fmac_f32_e32 v63, v116, v120
	v_fmac_f32_e32 v79, v116, v121
	v_fmac_f32_e32 v63, v118, v121
	v_fmac_f32_e32 v79, v117, v120
	v_cvt_pk_bf16_f32 v148, v63, v79
	ds_write_b32 v151, v148 offset:8432
	v_fmac_f32_e32 v62, v116, v63
	v_fmac_f32_e32 v78, v116, v79
	v_fmac_f32_e32 v62, v118, v79
	v_fmac_f32_e32 v78, v117, v63
	v_cvt_pk_bf16_f32 v149, v62, v78
	ds_write_b32 v151, v149 offset:8160
	v_fmac_f32_e32 v61, v116, v62
	v_fmac_f32_e32 v77, v116, v78
	v_fmac_f32_e32 v61, v118, v78
	v_fmac_f32_e32 v77, v117, v62
	v_cvt_pk_bf16_f32 v148, v61, v77
	ds_write_b32 v151, v148 offset:7888
	v_fmac_f32_e32 v60, v116, v61
	v_fmac_f32_e32 v76, v116, v77
	v_fmac_f32_e32 v60, v118, v77
	v_fmac_f32_e32 v76, v117, v61
	v_cvt_pk_bf16_f32 v149, v60, v76
	ds_write_b32 v151, v149 offset:7616
	v_fmac_f32_e32 v31, v116, v60
	v_fmac_f32_e32 v47, v116, v76
	v_fmac_f32_e32 v31, v118, v76
	v_fmac_f32_e32 v47, v117, v60
	v_cvt_pk_bf16_f32 v148, v31, v47
	ds_write_b32 v151, v148 offset:7344
	v_fmac_f32_e32 v30, v116, v31
	v_fmac_f32_e32 v46, v116, v47
	v_fmac_f32_e32 v30, v118, v47
	v_fmac_f32_e32 v46, v117, v31
	v_cvt_pk_bf16_f32 v149, v30, v46
	ds_write_b32 v151, v149 offset:7072
	v_fmac_f32_e32 v29, v116, v30
	v_fmac_f32_e32 v45, v116, v46
	v_fmac_f32_e32 v29, v118, v46
	v_fmac_f32_e32 v45, v117, v30
	v_cvt_pk_bf16_f32 v148, v29, v45
	ds_write_b32 v151, v148 offset:6800
	v_fmac_f32_e32 v28, v116, v29
	v_fmac_f32_e32 v44, v116, v45
	v_fmac_f32_e32 v28, v118, v45
	v_fmac_f32_e32 v44, v117, v29
	v_cvt_pk_bf16_f32 v149, v28, v44
	ds_write_b32 v151, v149 offset:6528
	v_fmac_f32_e32 v59, v116, v28
	v_fmac_f32_e32 v75, v116, v44
	v_fmac_f32_e32 v59, v118, v44
	v_fmac_f32_e32 v75, v117, v28
	v_cvt_pk_bf16_f32 v148, v59, v75
	ds_write_b32 v151, v148 offset:6256
	v_fmac_f32_e32 v58, v116, v59
	v_fmac_f32_e32 v74, v116, v75
	v_fmac_f32_e32 v58, v118, v75
	v_fmac_f32_e32 v74, v117, v59
	v_cvt_pk_bf16_f32 v149, v58, v74
	ds_write_b32 v151, v149 offset:5984
	v_fmac_f32_e32 v57, v116, v58
	v_fmac_f32_e32 v73, v116, v74
	v_fmac_f32_e32 v57, v118, v74
	v_fmac_f32_e32 v73, v117, v58
	v_cvt_pk_bf16_f32 v148, v57, v73
	ds_write_b32 v151, v148 offset:5712
	v_fmac_f32_e32 v56, v116, v57
	v_fmac_f32_e32 v72, v116, v73
	v_fmac_f32_e32 v56, v118, v73
	v_fmac_f32_e32 v72, v117, v57
	v_cvt_pk_bf16_f32 v149, v56, v72
	ds_write_b32 v151, v149 offset:5440
	v_fmac_f32_e32 v27, v116, v56
	v_fmac_f32_e32 v43, v116, v72
	v_fmac_f32_e32 v27, v118, v72
	v_fmac_f32_e32 v43, v117, v56
	v_cvt_pk_bf16_f32 v148, v27, v43
	ds_write_b32 v151, v148 offset:5168
	v_fmac_f32_e32 v26, v116, v27
	v_fmac_f32_e32 v42, v116, v43
	v_fmac_f32_e32 v26, v118, v43
	v_fmac_f32_e32 v42, v117, v27
	v_cvt_pk_bf16_f32 v149, v26, v42
	ds_write_b32 v151, v149 offset:4896
	v_fmac_f32_e32 v25, v116, v26
	v_fmac_f32_e32 v41, v116, v42
	v_fmac_f32_e32 v25, v118, v42
	v_fmac_f32_e32 v41, v117, v26
	v_cvt_pk_bf16_f32 v148, v25, v41
	ds_write_b32 v151, v148 offset:4624
	v_fmac_f32_e32 v24, v116, v25
	v_fmac_f32_e32 v40, v116, v41
	v_fmac_f32_e32 v24, v118, v41
	v_fmac_f32_e32 v40, v117, v25
	v_cvt_pk_bf16_f32 v149, v24, v40
	ds_write_b32 v151, v149 offset:4352
	v_fmac_f32_e32 v55, v116, v24
	v_fmac_f32_e32 v71, v116, v40
	v_fmac_f32_e32 v55, v118, v40
	v_fmac_f32_e32 v71, v117, v24
	v_cvt_pk_bf16_f32 v148, v55, v71
	ds_write_b32 v151, v148 offset:4080
	v_fmac_f32_e32 v54, v116, v55
	v_fmac_f32_e32 v70, v116, v71
	v_fmac_f32_e32 v54, v118, v71
	v_fmac_f32_e32 v70, v117, v55
	v_cvt_pk_bf16_f32 v149, v54, v70
	ds_write_b32 v151, v149 offset:3808
	v_fmac_f32_e32 v53, v116, v54
	v_fmac_f32_e32 v69, v116, v70
	v_fmac_f32_e32 v53, v118, v70
	v_fmac_f32_e32 v69, v117, v54
	v_cvt_pk_bf16_f32 v148, v53, v69
	ds_write_b32 v151, v148 offset:3536
	v_fmac_f32_e32 v52, v116, v53
	v_fmac_f32_e32 v68, v116, v69
	v_fmac_f32_e32 v52, v118, v69
	v_fmac_f32_e32 v68, v117, v53
	v_cvt_pk_bf16_f32 v149, v52, v68
	ds_write_b32 v151, v149 offset:3264
	v_fmac_f32_e32 v23, v116, v52
	v_fmac_f32_e32 v39, v116, v68
	v_fmac_f32_e32 v23, v118, v68
	v_fmac_f32_e32 v39, v117, v52
	v_cvt_pk_bf16_f32 v148, v23, v39
	ds_write_b32 v151, v148 offset:2992
	v_fmac_f32_e32 v22, v116, v23
	v_fmac_f32_e32 v38, v116, v39
	v_fmac_f32_e32 v22, v118, v39
	v_fmac_f32_e32 v38, v117, v23
	v_cvt_pk_bf16_f32 v149, v22, v38
	ds_write_b32 v151, v149 offset:2720
	v_fmac_f32_e32 v21, v116, v22
	v_fmac_f32_e32 v37, v116, v38
	v_fmac_f32_e32 v21, v118, v38
	v_fmac_f32_e32 v37, v117, v22
	v_cvt_pk_bf16_f32 v148, v21, v37
	ds_write_b32 v151, v148 offset:2448
	v_fmac_f32_e32 v20, v116, v21
	v_fmac_f32_e32 v36, v116, v37
	v_fmac_f32_e32 v20, v118, v37
	v_fmac_f32_e32 v36, v117, v21
	v_cvt_pk_bf16_f32 v149, v20, v36
	ds_write_b32 v151, v149 offset:2176
	v_fmac_f32_e32 v51, v116, v20
	v_fmac_f32_e32 v67, v116, v36
	v_fmac_f32_e32 v51, v118, v36
	v_fmac_f32_e32 v67, v117, v20
	v_cvt_pk_bf16_f32 v148, v51, v67
	ds_write_b32 v151, v148 offset:1904
	v_fmac_f32_e32 v50, v116, v51
	v_fmac_f32_e32 v66, v116, v67
	v_fmac_f32_e32 v50, v118, v67
	v_fmac_f32_e32 v66, v117, v51
	v_cvt_pk_bf16_f32 v149, v50, v66
	ds_write_b32 v151, v149 offset:1632
	v_fmac_f32_e32 v49, v116, v50
	v_fmac_f32_e32 v65, v116, v66
	v_fmac_f32_e32 v49, v118, v66
	v_fmac_f32_e32 v65, v117, v50
	v_cvt_pk_bf16_f32 v148, v49, v65
	ds_write_b32 v151, v148 offset:1360
	v_fmac_f32_e32 v48, v116, v49
	v_fmac_f32_e32 v64, v116, v65
	v_fmac_f32_e32 v48, v118, v65
	v_fmac_f32_e32 v64, v117, v49
	v_cvt_pk_bf16_f32 v149, v48, v64
	ds_write_b32 v151, v149 offset:1088
	v_fmac_f32_e32 v19, v116, v48
	v_fmac_f32_e32 v35, v116, v64
	v_fmac_f32_e32 v19, v118, v64
	v_fmac_f32_e32 v35, v117, v48
	v_cvt_pk_bf16_f32 v148, v19, v35
	ds_write_b32 v151, v148 offset:816
	v_fmac_f32_e32 v18, v116, v19
	v_fmac_f32_e32 v34, v116, v35
	v_fmac_f32_e32 v18, v118, v35
	v_fmac_f32_e32 v34, v117, v19
	v_cvt_pk_bf16_f32 v149, v18, v34
	ds_write_b32 v151, v149 offset:544
	v_fmac_f32_e32 v17, v116, v18
	v_fmac_f32_e32 v33, v116, v34
	v_fmac_f32_e32 v17, v118, v34
	v_fmac_f32_e32 v33, v117, v18
	v_cvt_pk_bf16_f32 v148, v17, v33
	ds_write_b32 v151, v148 offset:272
	v_fmac_f32_e32 v16, v116, v17
	v_fmac_f32_e32 v32, v116, v33
	v_fmac_f32_e32 v16, v118, v33
	v_fmac_f32_e32 v32, v117, v17
	v_cvt_pk_bf16_f32 v149, v16, v32
	ds_write_b32 v151, v149
	v_mov_b32_e32 v120, v16
	v_mov_b32_e32 v121, v32
	ds_read_b128 v[124:127], v152
	ds_read_b128 v[128:131], v152 offset:64
	ds_read_b128 v[132:135], v152 offset:128
	ds_read_b128 v[136:139], v152 offset:192
	s_waitcnt lgkmcnt(3)
	v_mfma_f32_16x16x32_bf16 v[140:143], v[100:103], v[124:127], 0
	s_waitcnt lgkmcnt(2)
	v_mfma_f32_16x16x32_bf16 v[140:143], v[104:107], v[128:131], v[140:143]
	s_waitcnt lgkmcnt(1)
	v_mfma_f32_16x16x32_bf16 v[140:143], v[108:111], v[132:135], v[140:143]
	s_waitcnt lgkmcnt(0)
	v_mfma_f32_16x16x32_bf16 v[140:143], v[112:115], v[136:139], v[140:143]
	s_nop 9
	global_store_dwordx4 v153, v[140:143], s[12:13]
	s_nop 1
	ds_read_b128 v[124:127], v152 offset:4352
	ds_read_b128 v[128:131], v152 offset:4416
	ds_read_b128 v[132:135], v152 offset:4480
	ds_read_b128 v[136:139], v152 offset:4544
	s_waitcnt lgkmcnt(3)
	v_mfma_f32_16x16x32_bf16 v[140:143], v[100:103], v[124:127], 0
	s_waitcnt lgkmcnt(2)
	v_mfma_f32_16x16x32_bf16 v[140:143], v[104:107], v[128:131], v[140:143]
	s_waitcnt lgkmcnt(1)
	v_mfma_f32_16x16x32_bf16 v[140:143], v[108:111], v[132:135], v[140:143]
	s_waitcnt lgkmcnt(0)
	v_mfma_f32_16x16x32_bf16 v[140:143], v[112:115], v[136:139], v[140:143]
	s_nop 9
	global_store_dwordx4 v157, v[140:143], s[12:13]
	s_nop 1
	s_sub_u32 s12, s12, 2048
	s_subb_u32 s13, s13, 0
	s_waitcnt vmcnt(6)
	v_cndmask_b32_e64 v124, 0, v144, s[66:67]
	v_cndmask_b32_e64 v125, 0, v145, s[66:67]
	v_cndmask_b32_e64 v126, 0, v146, s[66:67]
	v_cndmask_b32_e64 v127, 0, v147, s[66:67]
	v_cndmask_b32_e64 v132, 0, v168, s[66:67]
	v_cndmask_b32_e64 v133, 0, v169, s[66:67]
	v_cndmask_b32_e64 v134, 0, v170, s[66:67]
	v_cndmask_b32_e64 v135, 0, v171, s[66:67]
	v_mfma_f32_32x32x16_bf16 v[16:31], v[124:127], v[84:87], 0
	v_cndmask_b32_e64 v128, 0, v168, s[68:69]
	v_cndmask_b32_e64 v129, 0, v169, s[68:69]
	v_cndmask_b32_e64 v130, 0, v170, s[68:69]
	v_cndmask_b32_e64 v131, 0, v171, s[68:69]
	v_mfma_f32_32x32x16_bf16 v[32:47], v[124:127], v[88:91], 0
	v_cndmask_b32_e64 v136, 0, v144, s[68:69]
	v_cndmask_b32_e64 v137, 0, v145, s[68:69]
	v_cndmask_b32_e64 v138, 0, v146, s[68:69]
	v_cndmask_b32_e64 v139, 0, v147, s[68:69]
	v_mfma_f32_32x32x16_bf16 v[48:63], v[132:135], v[84:87], 0
	v_mfma_f32_32x32x16_bf16 v[64:79], v[132:135], v[88:91], 0
	v_mfma_f32_32x32x16_bf16 v[16:31], v[128:131], v[92:95], v[16:31]
	v_mfma_f32_32x32x16_bf16 v[32:47], v[128:131], v[96:99], v[32:47]
	v_mfma_f32_32x32x16_bf16 v[48:63], v[136:139], v[92:95], v[48:63]
	v_mfma_f32_32x32x16_bf16 v[64:79], v[136:139], v[96:99], v[64:79]
	s_nop 11
	global_load_dwordx4 v[144:147], v150, s[10:11]
	global_load_dwordx4 v[168:171], v193, s[10:11]
	s_sub_u32 s34, s34, 1024
	s_subb_u32 s35, s35, 0
	s_sub_u32 s10, s10, 1024
	s_subb_u32 s11, s11, 0
	v_fmac_f32_e32 v63, v116, v120
	v_fmac_f32_e32 v79, v116, v121
	v_fmac_f32_e32 v63, v118, v121
	v_fmac_f32_e32 v79, v117, v120
	v_cvt_pk_bf16_f32 v148, v63, v79
	ds_write_b32 v151, v148 offset:8432
	v_fmac_f32_e32 v62, v116, v63
	v_fmac_f32_e32 v78, v116, v79
	v_fmac_f32_e32 v62, v118, v79
	v_fmac_f32_e32 v78, v117, v63
	v_cvt_pk_bf16_f32 v149, v62, v78
	ds_write_b32 v151, v149 offset:8160
	v_fmac_f32_e32 v61, v116, v62
	v_fmac_f32_e32 v77, v116, v78
	v_fmac_f32_e32 v61, v118, v78
	v_fmac_f32_e32 v77, v117, v62
	v_cvt_pk_bf16_f32 v148, v61, v77
	ds_write_b32 v151, v148 offset:7888
	v_fmac_f32_e32 v60, v116, v61
	v_fmac_f32_e32 v76, v116, v77
	v_fmac_f32_e32 v60, v118, v77
	v_fmac_f32_e32 v76, v117, v61
	v_cvt_pk_bf16_f32 v149, v60, v76
	ds_write_b32 v151, v149 offset:7616
	v_fmac_f32_e32 v31, v116, v60
	v_fmac_f32_e32 v47, v116, v76
	v_fmac_f32_e32 v31, v118, v76
	v_fmac_f32_e32 v47, v117, v60
	v_cvt_pk_bf16_f32 v148, v31, v47
	ds_write_b32 v151, v148 offset:7344
	v_fmac_f32_e32 v30, v116, v31
	v_fmac_f32_e32 v46, v116, v47
	v_fmac_f32_e32 v30, v118, v47
	v_fmac_f32_e32 v46, v117, v31
	v_cvt_pk_bf16_f32 v149, v30, v46
	ds_write_b32 v151, v149 offset:7072
	v_fmac_f32_e32 v29, v116, v30
	v_fmac_f32_e32 v45, v116, v46
	v_fmac_f32_e32 v29, v118, v46
	v_fmac_f32_e32 v45, v117, v30
	v_cvt_pk_bf16_f32 v148, v29, v45
	ds_write_b32 v151, v148 offset:6800
	v_fmac_f32_e32 v28, v116, v29
	v_fmac_f32_e32 v44, v116, v45
	v_fmac_f32_e32 v28, v118, v45
	v_fmac_f32_e32 v44, v117, v29
	v_cvt_pk_bf16_f32 v149, v28, v44
	ds_write_b32 v151, v149 offset:6528
	v_fmac_f32_e32 v59, v116, v28
	v_fmac_f32_e32 v75, v116, v44
	v_fmac_f32_e32 v59, v118, v44
	v_fmac_f32_e32 v75, v117, v28
	v_cvt_pk_bf16_f32 v148, v59, v75
	ds_write_b32 v151, v148 offset:6256
	v_fmac_f32_e32 v58, v116, v59
	v_fmac_f32_e32 v74, v116, v75
	v_fmac_f32_e32 v58, v118, v75
	v_fmac_f32_e32 v74, v117, v59
	v_cvt_pk_bf16_f32 v149, v58, v74
	ds_write_b32 v151, v149 offset:5984
	v_fmac_f32_e32 v57, v116, v58
	v_fmac_f32_e32 v73, v116, v74
	v_fmac_f32_e32 v57, v118, v74
	v_fmac_f32_e32 v73, v117, v58
	v_cvt_pk_bf16_f32 v148, v57, v73
	ds_write_b32 v151, v148 offset:5712
	v_fmac_f32_e32 v56, v116, v57
	v_fmac_f32_e32 v72, v116, v73
	v_fmac_f32_e32 v56, v118, v73
	v_fmac_f32_e32 v72, v117, v57
	v_cvt_pk_bf16_f32 v149, v56, v72
	ds_write_b32 v151, v149 offset:5440
	v_fmac_f32_e32 v27, v116, v56
	v_fmac_f32_e32 v43, v116, v72
	v_fmac_f32_e32 v27, v118, v72
	v_fmac_f32_e32 v43, v117, v56
	v_cvt_pk_bf16_f32 v148, v27, v43
	ds_write_b32 v151, v148 offset:5168
	v_fmac_f32_e32 v26, v116, v27
	v_fmac_f32_e32 v42, v116, v43
	v_fmac_f32_e32 v26, v118, v43
	v_fmac_f32_e32 v42, v117, v27
	v_cvt_pk_bf16_f32 v149, v26, v42
	ds_write_b32 v151, v149 offset:4896
	v_fmac_f32_e32 v25, v116, v26
	v_fmac_f32_e32 v41, v116, v42
	v_fmac_f32_e32 v25, v118, v42
	v_fmac_f32_e32 v41, v117, v26
	v_cvt_pk_bf16_f32 v148, v25, v41
	ds_write_b32 v151, v148 offset:4624
	v_fmac_f32_e32 v24, v116, v25
	v_fmac_f32_e32 v40, v116, v41
	v_fmac_f32_e32 v24, v118, v41
	v_fmac_f32_e32 v40, v117, v25
	v_cvt_pk_bf16_f32 v149, v24, v40
	ds_write_b32 v151, v149 offset:4352
	v_fmac_f32_e32 v55, v116, v24
	v_fmac_f32_e32 v71, v116, v40
	v_fmac_f32_e32 v55, v118, v40
	v_fmac_f32_e32 v71, v117, v24
	v_cvt_pk_bf16_f32 v148, v55, v71
	ds_write_b32 v151, v148 offset:4080
	v_fmac_f32_e32 v54, v116, v55
	v_fmac_f32_e32 v70, v116, v71
	v_fmac_f32_e32 v54, v118, v71
	v_fmac_f32_e32 v70, v117, v55
	v_cvt_pk_bf16_f32 v149, v54, v70
	ds_write_b32 v151, v149 offset:3808
	v_fmac_f32_e32 v53, v116, v54
	v_fmac_f32_e32 v69, v116, v70
	v_fmac_f32_e32 v53, v118, v70
	v_fmac_f32_e32 v69, v117, v54
	v_cvt_pk_bf16_f32 v148, v53, v69
	ds_write_b32 v151, v148 offset:3536
	v_fmac_f32_e32 v52, v116, v53
	v_fmac_f32_e32 v68, v116, v69
	v_fmac_f32_e32 v52, v118, v69
	v_fmac_f32_e32 v68, v117, v53
	v_cvt_pk_bf16_f32 v149, v52, v68
	ds_write_b32 v151, v149 offset:3264
	v_fmac_f32_e32 v23, v116, v52
	v_fmac_f32_e32 v39, v116, v68
	v_fmac_f32_e32 v23, v118, v68
	v_fmac_f32_e32 v39, v117, v52
	v_cvt_pk_bf16_f32 v148, v23, v39
	ds_write_b32 v151, v148 offset:2992
	v_fmac_f32_e32 v22, v116, v23
	v_fmac_f32_e32 v38, v116, v39
	v_fmac_f32_e32 v22, v118, v39
	v_fmac_f32_e32 v38, v117, v23
	v_cvt_pk_bf16_f32 v149, v22, v38
	ds_write_b32 v151, v149 offset:2720
	v_fmac_f32_e32 v21, v116, v22
	v_fmac_f32_e32 v37, v116, v38
	v_fmac_f32_e32 v21, v118, v38
	v_fmac_f32_e32 v37, v117, v22
	v_cvt_pk_bf16_f32 v148, v21, v37
	ds_write_b32 v151, v148 offset:2448
	v_fmac_f32_e32 v20, v116, v21
	v_fmac_f32_e32 v36, v116, v37
	v_fmac_f32_e32 v20, v118, v37
	v_fmac_f32_e32 v36, v117, v21
	v_cvt_pk_bf16_f32 v149, v20, v36
	ds_write_b32 v151, v149 offset:2176
	v_fmac_f32_e32 v51, v116, v20
	v_fmac_f32_e32 v67, v116, v36
	v_fmac_f32_e32 v51, v118, v36
	v_fmac_f32_e32 v67, v117, v20
	v_cvt_pk_bf16_f32 v148, v51, v67
	ds_write_b32 v151, v148 offset:1904
	v_fmac_f32_e32 v50, v116, v51
	v_fmac_f32_e32 v66, v116, v67
	v_fmac_f32_e32 v50, v118, v67
	v_fmac_f32_e32 v66, v117, v51
	v_cvt_pk_bf16_f32 v149, v50, v66
	ds_write_b32 v151, v149 offset:1632
	v_fmac_f32_e32 v49, v116, v50
	v_fmac_f32_e32 v65, v116, v66
	v_fmac_f32_e32 v49, v118, v66
	v_fmac_f32_e32 v65, v117, v50
	v_cvt_pk_bf16_f32 v148, v49, v65
	ds_write_b32 v151, v148 offset:1360
	v_fmac_f32_e32 v48, v116, v49
	v_fmac_f32_e32 v64, v116, v65
	v_fmac_f32_e32 v48, v118, v65
	v_fmac_f32_e32 v64, v117, v49
	v_cvt_pk_bf16_f32 v149, v48, v64
	ds_write_b32 v151, v149 offset:1088
	v_fmac_f32_e32 v19, v116, v48
	v_fmac_f32_e32 v35, v116, v64
	v_fmac_f32_e32 v19, v118, v64
	v_fmac_f32_e32 v35, v117, v48
	v_cvt_pk_bf16_f32 v148, v19, v35
	ds_write_b32 v151, v148 offset:816
	v_fmac_f32_e32 v18, v116, v19
	v_fmac_f32_e32 v34, v116, v35
	v_fmac_f32_e32 v18, v118, v35
	v_fmac_f32_e32 v34, v117, v19
	v_cvt_pk_bf16_f32 v149, v18, v34
	ds_write_b32 v151, v149 offset:544
	v_fmac_f32_e32 v17, v116, v18
	v_fmac_f32_e32 v33, v116, v34
	v_fmac_f32_e32 v17, v118, v34
	v_fmac_f32_e32 v33, v117, v18
	v_cvt_pk_bf16_f32 v148, v17, v33
	ds_write_b32 v151, v148 offset:272
	v_fmac_f32_e32 v16, v116, v17
	v_fmac_f32_e32 v32, v116, v33
	v_fmac_f32_e32 v16, v118, v33
	v_fmac_f32_e32 v32, v117, v17
	v_cvt_pk_bf16_f32 v149, v16, v32
	ds_write_b32 v151, v149
	v_mov_b32_e32 v120, v16
	v_mov_b32_e32 v121, v32
	ds_read_b128 v[124:127], v152
	ds_read_b128 v[128:131], v152 offset:64
	ds_read_b128 v[132:135], v152 offset:128
	ds_read_b128 v[136:139], v152 offset:192
	s_waitcnt lgkmcnt(3)
	v_mfma_f32_16x16x32_bf16 v[140:143], v[100:103], v[124:127], 0
	s_waitcnt lgkmcnt(2)
	v_mfma_f32_16x16x32_bf16 v[140:143], v[104:107], v[128:131], v[140:143]
	s_waitcnt lgkmcnt(1)
	v_mfma_f32_16x16x32_bf16 v[140:143], v[108:111], v[132:135], v[140:143]
	s_waitcnt lgkmcnt(0)
	v_mfma_f32_16x16x32_bf16 v[140:143], v[112:115], v[136:139], v[140:143]
	s_nop 9
	global_store_dwordx4 v153, v[140:143], s[12:13]
	s_nop 1
	ds_read_b128 v[124:127], v152 offset:4352
	ds_read_b128 v[128:131], v152 offset:4416
	ds_read_b128 v[132:135], v152 offset:4480
	ds_read_b128 v[136:139], v152 offset:4544
	s_waitcnt lgkmcnt(3)
	v_mfma_f32_16x16x32_bf16 v[140:143], v[100:103], v[124:127], 0
	s_waitcnt lgkmcnt(2)
	v_mfma_f32_16x16x32_bf16 v[140:143], v[104:107], v[128:131], v[140:143]
	s_waitcnt lgkmcnt(1)
	v_mfma_f32_16x16x32_bf16 v[140:143], v[108:111], v[132:135], v[140:143]
	s_waitcnt lgkmcnt(0)
	v_mfma_f32_16x16x32_bf16 v[140:143], v[112:115], v[136:139], v[140:143]
	s_nop 9
	global_store_dwordx4 v157, v[140:143], s[12:13]
	s_nop 1
	s_sub_u32 s12, s12, 2048
	s_subb_u32 s13, s13, 0
	s_add_u32 s14, s14, 2
	s_cmp_lt_u32 s14, 16
	s_cbranch_scc1 .Lssm_tileA_d1m0
	s_waitcnt vmcnt(0) lgkmcnt(0)
	s_lshr_b32 s21, s89, 1
	s_lshl_b32 s21, s21, 2
	s_add_u32 s37, s21, 0x21000
	v_mov_b32_e32 v182, s37
	v_mov_b32_e32 v183, 1
	v_cmp_eq_u32_e32 vcc, 0, v191
	s_and_saveexec_b64 s[0:1], vcc
	ds_add_u32 v182, v183
	s_mov_b64 exec, s[0:1]
	s_waitcnt lgkmcnt(0)
	s_mov_b32 s38, 0

.Lssm_tileB_d1m0:
	s_waitcnt vmcnt(8)
	v_cndmask_b32_e64 v124, 0, v80, s[66:67]
	v_cndmask_b32_e64 v125, 0, v81, s[66:67]
	v_cndmask_b32_e64 v126, 0, v82, s[66:67]
	v_cndmask_b32_e64 v127, 0, v83, s[66:67]
	v_cndmask_b32_e64 v132, 0, v194, s[66:67]
	v_cndmask_b32_e64 v133, 0, v195, s[66:67]
	v_cndmask_b32_e64 v134, 0, v196, s[66:67]
	v_cndmask_b32_e64 v135, 0, v197, s[66:67]
	v_mfma_f32_32x32x16_bf16 v[16:31], v[124:127], v[84:87], 0
	v_cndmask_b32_e64 v128, 0, v194, s[68:69]
	v_cndmask_b32_e64 v129, 0, v195, s[68:69]
	v_cndmask_b32_e64 v130, 0, v196, s[68:69]
	v_cndmask_b32_e64 v131, 0, v197, s[68:69]
	v_mfma_f32_32x32x16_bf16 v[32:47], v[124:127], v[88:91], 0
	v_cndmask_b32_e64 v136, 0, v80, s[68:69]
	v_cndmask_b32_e64 v137, 0, v81, s[68:69]
	v_cndmask_b32_e64 v138, 0, v82, s[68:69]
	v_cndmask_b32_e64 v139, 0, v83, s[68:69]
	v_mfma_f32_32x32x16_bf16 v[48:63], v[132:135], v[84:87], 0
	v_mfma_f32_32x32x16_bf16 v[64:79], v[132:135], v[88:91], 0
	v_mfma_f32_32x32x16_bf16 v[16:31], v[128:131], v[92:95], v[16:31]
	v_mfma_f32_32x32x16_bf16 v[32:47], v[128:131], v[96:99], v[32:47]
	v_mfma_f32_32x32x16_bf16 v[48:63], v[136:139], v[92:95], v[48:63]
	v_mfma_f32_32x32x16_bf16 v[64:79], v[136:139], v[96:99], v[64:79]
	ds_write_b128 v162, v[80:83]
	global_load_dwordx4 v[172:175], v153, s[42:43]
	global_load_dwordx4 v[176:179], v157, s[42:43]
	s_sub_u32 s42, s42, 2048
	s_subb_u32 s43, s43, 0
	s_nop 11
	global_load_dwordx4 v[80:83], v150, s[10:11]
	global_load_dwordx4 v[194:197], v193, s[10:11]
	s_sub_u32 s34, s34, 1024
	s_subb_u32 s35, s35, 0
	s_sub_u32 s10, s10, 1024
	s_subb_u32 s11, s11, 0
	v_fmac_f32_e32 v63, v116, v120
	v_fmac_f32_e32 v79, v116, v121
	v_fmac_f32_e32 v63, v118, v121
	v_fmac_f32_e32 v79, v117, v120
	v_cvt_pk_bf16_f32 v148, v63, v79
	ds_write_b32 v151, v148 offset:8432
	v_fmac_f32_e32 v62, v116, v63
	v_fmac_f32_e32 v78, v116, v79
	v_fmac_f32_e32 v62, v118, v79
	v_fmac_f32_e32 v78, v117, v63
	v_cvt_pk_bf16_f32 v149, v62, v78
	ds_write_b32 v151, v149 offset:8160
	v_fmac_f32_e32 v61, v116, v62
	v_fmac_f32_e32 v77, v116, v78
	v_fmac_f32_e32 v61, v118, v78
	v_fmac_f32_e32 v77, v117, v62
	v_cvt_pk_bf16_f32 v148, v61, v77
	ds_write_b32 v151, v148 offset:7888
	v_fmac_f32_e32 v60, v116, v61
	v_fmac_f32_e32 v76, v116, v77
	v_fmac_f32_e32 v60, v118, v77
	v_fmac_f32_e32 v76, v117, v61
	v_cvt_pk_bf16_f32 v149, v60, v76
	ds_write_b32 v151, v149 offset:7616
	v_fmac_f32_e32 v31, v116, v60
	v_fmac_f32_e32 v47, v116, v76
	v_fmac_f32_e32 v31, v118, v76
	v_fmac_f32_e32 v47, v117, v60
	v_cvt_pk_bf16_f32 v148, v31, v47
	ds_write_b32 v151, v148 offset:7344
	v_fmac_f32_e32 v30, v116, v31
	v_fmac_f32_e32 v46, v116, v47
	v_fmac_f32_e32 v30, v118, v47
	v_fmac_f32_e32 v46, v117, v31
	v_cvt_pk_bf16_f32 v149, v30, v46
	ds_write_b32 v151, v149 offset:7072
	v_fmac_f32_e32 v29, v116, v30
	v_fmac_f32_e32 v45, v116, v46
	v_fmac_f32_e32 v29, v118, v46
	v_fmac_f32_e32 v45, v117, v30
	v_cvt_pk_bf16_f32 v148, v29, v45
	ds_write_b32 v151, v148 offset:6800
	v_fmac_f32_e32 v28, v116, v29
	v_fmac_f32_e32 v44, v116, v45
	v_fmac_f32_e32 v28, v118, v45
	v_fmac_f32_e32 v44, v117, v29
	v_cvt_pk_bf16_f32 v149, v28, v44
	ds_write_b32 v151, v149 offset:6528
	v_fmac_f32_e32 v59, v116, v28
	v_fmac_f32_e32 v75, v116, v44
	v_fmac_f32_e32 v59, v118, v44
	v_fmac_f32_e32 v75, v117, v28
	v_cvt_pk_bf16_f32 v148, v59, v75
	ds_write_b32 v151, v148 offset:6256
	v_fmac_f32_e32 v58, v116, v59
	v_fmac_f32_e32 v74, v116, v75
	v_fmac_f32_e32 v58, v118, v75
	v_fmac_f32_e32 v74, v117, v59
	v_cvt_pk_bf16_f32 v149, v58, v74
	ds_write_b32 v151, v149 offset:5984
	v_fmac_f32_e32 v57, v116, v58
	v_fmac_f32_e32 v73, v116, v74
	v_fmac_f32_e32 v57, v118, v74
	v_fmac_f32_e32 v73, v117, v58
	v_cvt_pk_bf16_f32 v148, v57, v73
	ds_write_b32 v151, v148 offset:5712
	v_fmac_f32_e32 v56, v116, v57
	v_fmac_f32_e32 v72, v116, v73
	v_fmac_f32_e32 v56, v118, v73
	v_fmac_f32_e32 v72, v117, v57
	v_cvt_pk_bf16_f32 v149, v56, v72
	ds_write_b32 v151, v149 offset:5440
	v_fmac_f32_e32 v27, v116, v56
	v_fmac_f32_e32 v43, v116, v72
	v_fmac_f32_e32 v27, v118, v72
	v_fmac_f32_e32 v43, v117, v56
	v_cvt_pk_bf16_f32 v148, v27, v43
	ds_write_b32 v151, v148 offset:5168
	v_fmac_f32_e32 v26, v116, v27
	v_fmac_f32_e32 v42, v116, v43
	v_fmac_f32_e32 v26, v118, v43
	v_fmac_f32_e32 v42, v117, v27
	v_cvt_pk_bf16_f32 v149, v26, v42
	ds_write_b32 v151, v149 offset:4896
	v_fmac_f32_e32 v25, v116, v26
	v_fmac_f32_e32 v41, v116, v42
	v_fmac_f32_e32 v25, v118, v42
	v_fmac_f32_e32 v41, v117, v26
	v_cvt_pk_bf16_f32 v148, v25, v41
	ds_write_b32 v151, v148 offset:4624
	v_fmac_f32_e32 v24, v116, v25
	v_fmac_f32_e32 v40, v116, v41
	v_fmac_f32_e32 v24, v118, v41
	v_fmac_f32_e32 v40, v117, v25
	v_cvt_pk_bf16_f32 v149, v24, v40
	ds_write_b32 v151, v149 offset:4352
	v_fmac_f32_e32 v55, v116, v24
	v_fmac_f32_e32 v71, v116, v40
	v_fmac_f32_e32 v55, v118, v40
	v_fmac_f32_e32 v71, v117, v24
	v_cvt_pk_bf16_f32 v148, v55, v71
	ds_write_b32 v151, v148 offset:4080
	v_fmac_f32_e32 v54, v116, v55
	v_fmac_f32_e32 v70, v116, v71
	v_fmac_f32_e32 v54, v118, v71
	v_fmac_f32_e32 v70, v117, v55
	v_cvt_pk_bf16_f32 v149, v54, v70
	ds_write_b32 v151, v149 offset:3808
	v_fmac_f32_e32 v53, v116, v54
	v_fmac_f32_e32 v69, v116, v70
	v_fmac_f32_e32 v53, v118, v70
	v_fmac_f32_e32 v69, v117, v54
	v_cvt_pk_bf16_f32 v148, v53, v69
	ds_write_b32 v151, v148 offset:3536
	v_fmac_f32_e32 v52, v116, v53
	v_fmac_f32_e32 v68, v116, v69
	v_fmac_f32_e32 v52, v118, v69
	v_fmac_f32_e32 v68, v117, v53
	v_cvt_pk_bf16_f32 v149, v52, v68
	ds_write_b32 v151, v149 offset:3264
	v_fmac_f32_e32 v23, v116, v52
	v_fmac_f32_e32 v39, v116, v68
	v_fmac_f32_e32 v23, v118, v68
	v_fmac_f32_e32 v39, v117, v52
	v_cvt_pk_bf16_f32 v148, v23, v39
	ds_write_b32 v151, v148 offset:2992
	v_fmac_f32_e32 v22, v116, v23
	v_fmac_f32_e32 v38, v116, v39
	v_fmac_f32_e32 v22, v118, v39
	v_fmac_f32_e32 v38, v117, v23
	v_cvt_pk_bf16_f32 v149, v22, v38
	ds_write_b32 v151, v149 offset:2720
	v_fmac_f32_e32 v21, v116, v22
	v_fmac_f32_e32 v37, v116, v38
	v_fmac_f32_e32 v21, v118, v38
	v_fmac_f32_e32 v37, v117, v22
	v_cvt_pk_bf16_f32 v148, v21, v37
	ds_write_b32 v151, v148 offset:2448
	v_fmac_f32_e32 v20, v116, v21
	v_fmac_f32_e32 v36, v116, v37
	v_fmac_f32_e32 v20, v118, v37
	v_fmac_f32_e32 v36, v117, v21
	v_cvt_pk_bf16_f32 v149, v20, v36
	ds_write_b32 v151, v149 offset:2176
	v_fmac_f32_e32 v51, v116, v20
	v_fmac_f32_e32 v67, v116, v36
	v_fmac_f32_e32 v51, v118, v36
	v_fmac_f32_e32 v67, v117, v20
	v_cvt_pk_bf16_f32 v148, v51, v67
	ds_write_b32 v151, v148 offset:1904
	v_fmac_f32_e32 v50, v116, v51
	v_fmac_f32_e32 v66, v116, v67
	v_fmac_f32_e32 v50, v118, v67
	v_fmac_f32_e32 v66, v117, v51
	v_cvt_pk_bf16_f32 v149, v50, v66
	ds_write_b32 v151, v149 offset:1632
	v_fmac_f32_e32 v49, v116, v50
	v_fmac_f32_e32 v65, v116, v66
	v_fmac_f32_e32 v49, v118, v66
	v_fmac_f32_e32 v65, v117, v50
	v_cvt_pk_bf16_f32 v148, v49, v65
	ds_write_b32 v151, v148 offset:1360
	v_fmac_f32_e32 v48, v116, v49
	v_fmac_f32_e32 v64, v116, v65
	v_fmac_f32_e32 v48, v118, v65
	v_fmac_f32_e32 v64, v117, v49
	v_cvt_pk_bf16_f32 v149, v48, v64
	ds_write_b32 v151, v149 offset:1088
	v_fmac_f32_e32 v19, v116, v48
	v_fmac_f32_e32 v35, v116, v64
	v_fmac_f32_e32 v19, v118, v64
	v_fmac_f32_e32 v35, v117, v48
	v_cvt_pk_bf16_f32 v148, v19, v35
	ds_write_b32 v151, v148 offset:816
	v_fmac_f32_e32 v18, v116, v19
	v_fmac_f32_e32 v34, v116, v35
	v_fmac_f32_e32 v18, v118, v35
	v_fmac_f32_e32 v34, v117, v19
	v_cvt_pk_bf16_f32 v149, v18, v34
	ds_write_b32 v151, v149 offset:544
	v_fmac_f32_e32 v17, v116, v18
	v_fmac_f32_e32 v33, v116, v34
	v_fmac_f32_e32 v17, v118, v34
	v_fmac_f32_e32 v33, v117, v18
	v_cvt_pk_bf16_f32 v148, v17, v33
	ds_write_b32 v151, v148 offset:272
	v_fmac_f32_e32 v16, v116, v17
	v_fmac_f32_e32 v32, v116, v33
	v_fmac_f32_e32 v16, v118, v33
	v_fmac_f32_e32 v32, v117, v17
	v_cvt_pk_bf16_f32 v149, v16, v32
	ds_write_b32 v151, v149
	v_mov_b32_e32 v120, v16
	v_mov_b32_e32 v121, v32
	ds_read_b128 v[124:127], v152
	ds_read_b128 v[128:131], v152 offset:64
	ds_read_b128 v[132:135], v152 offset:128
	ds_read_b128 v[136:139], v152 offset:192
	ds_read_b64 v[160:161], v163
	s_waitcnt lgkmcnt(4)
	v_mfma_f32_16x16x32_bf16 v[140:143], v[100:103], v[124:127], 0
	s_waitcnt lgkmcnt(3)
	v_mfma_f32_16x16x32_bf16 v[140:143], v[104:107], v[128:131], v[140:143]
	s_waitcnt lgkmcnt(2)
	v_mfma_f32_16x16x32_bf16 v[140:143], v[108:111], v[132:135], v[140:143]
	s_waitcnt lgkmcnt(1)
	v_mfma_f32_16x16x32_bf16 v[140:143], v[112:115], v[136:139], v[140:143]
	s_nop 9
	s_waitcnt vmcnt(9) lgkmcnt(0)
	v_add_f32_e32 v182, v6, v140
	v_add_f32_e32 v183, v7, v141
	v_add_f32_e32 v184, v8, v142
	v_add_f32_e32 v185, v9, v143
	v_lshlrev_b32_e32 v186, 16, v160
	v_and_b32_e32 v187, 0xffff0000, v160
	v_lshlrev_b32_e32 v188, 16, v161
	v_and_b32_e32 v189, 0xffff0000, v161
	v_fmac_f32_e32 v182, v164, v186
	v_fmac_f32_e32 v183, v165, v187
	v_fmac_f32_e32 v184, v166, v188
	v_fmac_f32_e32 v185, v167, v189
	v_mul_f32_e32 v186, v182, v182
	v_mul_f32_e32 v187, v183, v183
	v_mul_f32_e32 v188, v184, v184
	v_mul_f32_e32 v189, v185, v185
	v_fmaak_f32 v186, v1, v186, 0x40135761
	v_fmaak_f32 v187, v1, v187, 0x40135761
	v_fmaak_f32 v188, v1, v188, 0x40135761
	v_fmaak_f32 v189, v1, v189, 0x40135761
	v_mul_f32_e32 v186, v182, v186
	v_mul_f32_e32 v187, v183, v187
	v_mul_f32_e32 v188, v184, v188
	v_mul_f32_e32 v189, v185, v189
	v_exp_f32_e64 v186, -v186
	v_exp_f32_e64 v187, -v187
	v_exp_f32_e64 v188, -v188
	v_exp_f32_e64 v189, -v189
	v_add_f32_e32 v186, 1.0, v186
	v_add_f32_e32 v187, 1.0, v187
	v_add_f32_e32 v188, 1.0, v188
	v_add_f32_e32 v189, 1.0, v189
	v_rcp_f32_e32 v186, v186
	v_rcp_f32_e32 v187, v187
	v_rcp_f32_e32 v188, v188
	v_rcp_f32_e32 v189, v189
	v_mul_f32_e32 v182, v182, v186
	v_mul_f32_e32 v183, v183, v187
	v_mul_f32_e32 v184, v184, v188
	v_mul_f32_e32 v185, v185, v189
	v_cvt_pk_bf16_f32 v148, v182, v183
	v_cvt_pk_bf16_f32 v149, v184, v185
	global_store_dwordx2 v156, v[148:149], s[12:13]
	ds_read_b128 v[124:127], v152 offset:4352
	ds_read_b128 v[128:131], v152 offset:4416
	ds_read_b128 v[132:135], v152 offset:4480
	ds_read_b128 v[136:139], v152 offset:4544
	ds_read_b64 v[160:161], v163 offset:512
	s_waitcnt lgkmcnt(4)
	v_mfma_f32_16x16x32_bf16 v[140:143], v[100:103], v[124:127], 0
	s_waitcnt lgkmcnt(3)
	v_mfma_f32_16x16x32_bf16 v[140:143], v[104:107], v[128:131], v[140:143]
	s_waitcnt lgkmcnt(2)
	v_mfma_f32_16x16x32_bf16 v[140:143], v[108:111], v[132:135], v[140:143]
	s_waitcnt lgkmcnt(1)
	v_mfma_f32_16x16x32_bf16 v[140:143], v[112:115], v[136:139], v[140:143]
	s_nop 9
	s_waitcnt vmcnt(9) lgkmcnt(0)
	v_add_f32_e32 v182, v10, v140
	v_add_f32_e32 v183, v11, v141
	v_add_f32_e32 v184, v12, v142
	v_add_f32_e32 v185, v13, v143
	v_lshlrev_b32_e32 v186, 16, v160
	v_and_b32_e32 v187, 0xffff0000, v160
	v_lshlrev_b32_e32 v188, 16, v161
	v_and_b32_e32 v189, 0xffff0000, v161
	v_fmac_f32_e32 v182, v164, v186
	v_fmac_f32_e32 v183, v165, v187
	v_fmac_f32_e32 v184, v166, v188
	v_fmac_f32_e32 v185, v167, v189
	v_mul_f32_e32 v186, v182, v182
	v_mul_f32_e32 v187, v183, v183
	v_mul_f32_e32 v188, v184, v184
	v_mul_f32_e32 v189, v185, v185
	v_fmaak_f32 v186, v1, v186, 0x40135761
	v_fmaak_f32 v187, v1, v187, 0x40135761
	v_fmaak_f32 v188, v1, v188, 0x40135761
	v_fmaak_f32 v189, v1, v189, 0x40135761
	v_mul_f32_e32 v186, v182, v186
	v_mul_f32_e32 v187, v183, v187
	v_mul_f32_e32 v188, v184, v188
	v_mul_f32_e32 v189, v185, v189
	v_exp_f32_e64 v186, -v186
	v_exp_f32_e64 v187, -v187
	v_exp_f32_e64 v188, -v188
	v_exp_f32_e64 v189, -v189
	v_add_f32_e32 v186, 1.0, v186
	v_add_f32_e32 v187, 1.0, v187
	v_add_f32_e32 v188, 1.0, v188
	v_add_f32_e32 v189, 1.0, v189
	v_rcp_f32_e32 v186, v186
	v_rcp_f32_e32 v187, v187
	v_rcp_f32_e32 v188, v188
	v_rcp_f32_e32 v189, v189
	v_mul_f32_e32 v182, v182, v186
	v_mul_f32_e32 v183, v183, v187
	v_mul_f32_e32 v184, v184, v188
	v_mul_f32_e32 v185, v185, v189
	v_cvt_pk_bf16_f32 v148, v182, v183
	v_cvt_pk_bf16_f32 v149, v184, v185
	global_store_dwordx2 v159, v[148:149], s[12:13]
	s_sub_u32 s12, s12, 65536
	s_subb_u32 s13, s13, 0
	s_waitcnt vmcnt(8)
	v_cndmask_b32_e64 v124, 0, v144, s[66:67]
	v_cndmask_b32_e64 v125, 0, v145, s[66:67]
	v_cndmask_b32_e64 v126, 0, v146, s[66:67]
	v_cndmask_b32_e64 v127, 0, v147, s[66:67]
	v_cndmask_b32_e64 v132, 0, v168, s[66:67]
	v_cndmask_b32_e64 v133, 0, v169, s[66:67]
	v_cndmask_b32_e64 v134, 0, v170, s[66:67]
	v_cndmask_b32_e64 v135, 0, v171, s[66:67]
	v_mfma_f32_32x32x16_bf16 v[16:31], v[124:127], v[84:87], 0
	v_cndmask_b32_e64 v128, 0, v168, s[68:69]
	v_cndmask_b32_e64 v129, 0, v169, s[68:69]
	v_cndmask_b32_e64 v130, 0, v170, s[68:69]
	v_cndmask_b32_e64 v131, 0, v171, s[68:69]
	v_mfma_f32_32x32x16_bf16 v[32:47], v[124:127], v[88:91], 0
	v_cndmask_b32_e64 v136, 0, v144, s[68:69]
	v_cndmask_b32_e64 v137, 0, v145, s[68:69]
	v_cndmask_b32_e64 v138, 0, v146, s[68:69]
	v_cndmask_b32_e64 v139, 0, v147, s[68:69]
	v_mfma_f32_32x32x16_bf16 v[48:63], v[132:135], v[84:87], 0
	v_mfma_f32_32x32x16_bf16 v[64:79], v[132:135], v[88:91], 0
	v_mfma_f32_32x32x16_bf16 v[16:31], v[128:131], v[92:95], v[16:31]
	v_mfma_f32_32x32x16_bf16 v[32:47], v[128:131], v[96:99], v[32:47]
	v_mfma_f32_32x32x16_bf16 v[48:63], v[136:139], v[92:95], v[48:63]
	v_mfma_f32_32x32x16_bf16 v[64:79], v[136:139], v[96:99], v[64:79]
	ds_write_b128 v162, v[144:147]
	global_load_dwordx4 v[6:9], v153, s[42:43]
	global_load_dwordx4 v[10:13], v157, s[42:43]
	s_sub_u32 s42, s42, 2048
	s_subb_u32 s43, s43, 0
	s_nop 11
	global_load_dwordx4 v[144:147], v150, s[10:11]
	global_load_dwordx4 v[168:171], v193, s[10:11]
	s_sub_u32 s34, s34, 1024
	s_subb_u32 s35, s35, 0
	s_sub_u32 s10, s10, 1024
	s_subb_u32 s11, s11, 0
	v_fmac_f32_e32 v63, v116, v120
	v_fmac_f32_e32 v79, v116, v121
	v_fmac_f32_e32 v63, v118, v121
	v_fmac_f32_e32 v79, v117, v120
	v_cvt_pk_bf16_f32 v148, v63, v79
	ds_write_b32 v151, v148 offset:8432
	v_fmac_f32_e32 v62, v116, v63
	v_fmac_f32_e32 v78, v116, v79
	v_fmac_f32_e32 v62, v118, v79
	v_fmac_f32_e32 v78, v117, v63
	v_cvt_pk_bf16_f32 v149, v62, v78
	ds_write_b32 v151, v149 offset:8160
	v_fmac_f32_e32 v61, v116, v62
	v_fmac_f32_e32 v77, v116, v78
	v_fmac_f32_e32 v61, v118, v78
	v_fmac_f32_e32 v77, v117, v62
	v_cvt_pk_bf16_f32 v148, v61, v77
	ds_write_b32 v151, v148 offset:7888
	v_fmac_f32_e32 v60, v116, v61
	v_fmac_f32_e32 v76, v116, v77
	v_fmac_f32_e32 v60, v118, v77
	v_fmac_f32_e32 v76, v117, v61
	v_cvt_pk_bf16_f32 v149, v60, v76
	ds_write_b32 v151, v149 offset:7616
	v_fmac_f32_e32 v31, v116, v60
	v_fmac_f32_e32 v47, v116, v76
	v_fmac_f32_e32 v31, v118, v76
	v_fmac_f32_e32 v47, v117, v60
	v_cvt_pk_bf16_f32 v148, v31, v47
	ds_write_b32 v151, v148 offset:7344
	v_fmac_f32_e32 v30, v116, v31
	v_fmac_f32_e32 v46, v116, v47
	v_fmac_f32_e32 v30, v118, v47
	v_fmac_f32_e32 v46, v117, v31
	v_cvt_pk_bf16_f32 v149, v30, v46
	ds_write_b32 v151, v149 offset:7072
	v_fmac_f32_e32 v29, v116, v30
	v_fmac_f32_e32 v45, v116, v46
	v_fmac_f32_e32 v29, v118, v46
	v_fmac_f32_e32 v45, v117, v30
	v_cvt_pk_bf16_f32 v148, v29, v45
	ds_write_b32 v151, v148 offset:6800
	v_fmac_f32_e32 v28, v116, v29
	v_fmac_f32_e32 v44, v116, v45
	v_fmac_f32_e32 v28, v118, v45
	v_fmac_f32_e32 v44, v117, v29
	v_cvt_pk_bf16_f32 v149, v28, v44
	ds_write_b32 v151, v149 offset:6528
	v_fmac_f32_e32 v59, v116, v28
	v_fmac_f32_e32 v75, v116, v44
	v_fmac_f32_e32 v59, v118, v44
	v_fmac_f32_e32 v75, v117, v28
	v_cvt_pk_bf16_f32 v148, v59, v75
	ds_write_b32 v151, v148 offset:6256
	v_fmac_f32_e32 v58, v116, v59
	v_fmac_f32_e32 v74, v116, v75
	v_fmac_f32_e32 v58, v118, v75
	v_fmac_f32_e32 v74, v117, v59
	v_cvt_pk_bf16_f32 v149, v58, v74
	ds_write_b32 v151, v149 offset:5984
	v_fmac_f32_e32 v57, v116, v58
	v_fmac_f32_e32 v73, v116, v74
	v_fmac_f32_e32 v57, v118, v74
	v_fmac_f32_e32 v73, v117, v58
	v_cvt_pk_bf16_f32 v148, v57, v73
	ds_write_b32 v151, v148 offset:5712
	v_fmac_f32_e32 v56, v116, v57
	v_fmac_f32_e32 v72, v116, v73
	v_fmac_f32_e32 v56, v118, v73
	v_fmac_f32_e32 v72, v117, v57
	v_cvt_pk_bf16_f32 v149, v56, v72
	ds_write_b32 v151, v149 offset:5440
	v_fmac_f32_e32 v27, v116, v56
	v_fmac_f32_e32 v43, v116, v72
	v_fmac_f32_e32 v27, v118, v72
	v_fmac_f32_e32 v43, v117, v56
	v_cvt_pk_bf16_f32 v148, v27, v43
	ds_write_b32 v151, v148 offset:5168
	v_fmac_f32_e32 v26, v116, v27
	v_fmac_f32_e32 v42, v116, v43
	v_fmac_f32_e32 v26, v118, v43
	v_fmac_f32_e32 v42, v117, v27
	v_cvt_pk_bf16_f32 v149, v26, v42
	ds_write_b32 v151, v149 offset:4896
	v_fmac_f32_e32 v25, v116, v26
	v_fmac_f32_e32 v41, v116, v42
	v_fmac_f32_e32 v25, v118, v42
	v_fmac_f32_e32 v41, v117, v26
	v_cvt_pk_bf16_f32 v148, v25, v41
	ds_write_b32 v151, v148 offset:4624
	v_fmac_f32_e32 v24, v116, v25
	v_fmac_f32_e32 v40, v116, v41
	v_fmac_f32_e32 v24, v118, v41
	v_fmac_f32_e32 v40, v117, v25
	v_cvt_pk_bf16_f32 v149, v24, v40
	ds_write_b32 v151, v149 offset:4352
	v_fmac_f32_e32 v55, v116, v24
	v_fmac_f32_e32 v71, v116, v40
	v_fmac_f32_e32 v55, v118, v40
	v_fmac_f32_e32 v71, v117, v24
	v_cvt_pk_bf16_f32 v148, v55, v71
	ds_write_b32 v151, v148 offset:4080
	v_fmac_f32_e32 v54, v116, v55
	v_fmac_f32_e32 v70, v116, v71
	v_fmac_f32_e32 v54, v118, v71
	v_fmac_f32_e32 v70, v117, v55
	v_cvt_pk_bf16_f32 v149, v54, v70
	ds_write_b32 v151, v149 offset:3808
	v_fmac_f32_e32 v53, v116, v54
	v_fmac_f32_e32 v69, v116, v70
	v_fmac_f32_e32 v53, v118, v70
	v_fmac_f32_e32 v69, v117, v54
	v_cvt_pk_bf16_f32 v148, v53, v69
	ds_write_b32 v151, v148 offset:3536
	v_fmac_f32_e32 v52, v116, v53
	v_fmac_f32_e32 v68, v116, v69
	v_fmac_f32_e32 v52, v118, v69
	v_fmac_f32_e32 v68, v117, v53
	v_cvt_pk_bf16_f32 v149, v52, v68
	ds_write_b32 v151, v149 offset:3264
	v_fmac_f32_e32 v23, v116, v52
	v_fmac_f32_e32 v39, v116, v68
	v_fmac_f32_e32 v23, v118, v68
	v_fmac_f32_e32 v39, v117, v52
	v_cvt_pk_bf16_f32 v148, v23, v39
	ds_write_b32 v151, v148 offset:2992
	v_fmac_f32_e32 v22, v116, v23
	v_fmac_f32_e32 v38, v116, v39
	v_fmac_f32_e32 v22, v118, v39
	v_fmac_f32_e32 v38, v117, v23
	v_cvt_pk_bf16_f32 v149, v22, v38
	ds_write_b32 v151, v149 offset:2720
	v_fmac_f32_e32 v21, v116, v22
	v_fmac_f32_e32 v37, v116, v38
	v_fmac_f32_e32 v21, v118, v38
	v_fmac_f32_e32 v37, v117, v22
	v_cvt_pk_bf16_f32 v148, v21, v37
	ds_write_b32 v151, v148 offset:2448
	v_fmac_f32_e32 v20, v116, v21
	v_fmac_f32_e32 v36, v116, v37
	v_fmac_f32_e32 v20, v118, v37
	v_fmac_f32_e32 v36, v117, v21
	v_cvt_pk_bf16_f32 v149, v20, v36
	ds_write_b32 v151, v149 offset:2176
	v_fmac_f32_e32 v51, v116, v20
	v_fmac_f32_e32 v67, v116, v36
	v_fmac_f32_e32 v51, v118, v36
	v_fmac_f32_e32 v67, v117, v20
	v_cvt_pk_bf16_f32 v148, v51, v67
	ds_write_b32 v151, v148 offset:1904
	v_fmac_f32_e32 v50, v116, v51
	v_fmac_f32_e32 v66, v116, v67
	v_fmac_f32_e32 v50, v118, v67
	v_fmac_f32_e32 v66, v117, v51
	v_cvt_pk_bf16_f32 v149, v50, v66
	ds_write_b32 v151, v149 offset:1632
	v_fmac_f32_e32 v49, v116, v50
	v_fmac_f32_e32 v65, v116, v66
	v_fmac_f32_e32 v49, v118, v66
	v_fmac_f32_e32 v65, v117, v50
	v_cvt_pk_bf16_f32 v148, v49, v65
	ds_write_b32 v151, v148 offset:1360
	v_fmac_f32_e32 v48, v116, v49
	v_fmac_f32_e32 v64, v116, v65
	v_fmac_f32_e32 v48, v118, v65
	v_fmac_f32_e32 v64, v117, v49
	v_cvt_pk_bf16_f32 v149, v48, v64
	ds_write_b32 v151, v149 offset:1088
	v_fmac_f32_e32 v19, v116, v48
	v_fmac_f32_e32 v35, v116, v64
	v_fmac_f32_e32 v19, v118, v64
	v_fmac_f32_e32 v35, v117, v48
	v_cvt_pk_bf16_f32 v148, v19, v35
	ds_write_b32 v151, v148 offset:816
	v_fmac_f32_e32 v18, v116, v19
	v_fmac_f32_e32 v34, v116, v35
	v_fmac_f32_e32 v18, v118, v35
	v_fmac_f32_e32 v34, v117, v19
	v_cvt_pk_bf16_f32 v149, v18, v34
	ds_write_b32 v151, v149 offset:544
	v_fmac_f32_e32 v17, v116, v18
	v_fmac_f32_e32 v33, v116, v34
	v_fmac_f32_e32 v17, v118, v34
	v_fmac_f32_e32 v33, v117, v18
	v_cvt_pk_bf16_f32 v148, v17, v33
	ds_write_b32 v151, v148 offset:272
	v_fmac_f32_e32 v16, v116, v17
	v_fmac_f32_e32 v32, v116, v33
	v_fmac_f32_e32 v16, v118, v33
	v_fmac_f32_e32 v32, v117, v17
	v_cvt_pk_bf16_f32 v149, v16, v32
	ds_write_b32 v151, v149
	v_mov_b32_e32 v120, v16
	v_mov_b32_e32 v121, v32
	ds_read_b128 v[124:127], v152
	ds_read_b128 v[128:131], v152 offset:64
	ds_read_b128 v[132:135], v152 offset:128
	ds_read_b128 v[136:139], v152 offset:192
	ds_read_b64 v[160:161], v163
	s_waitcnt lgkmcnt(4)
	v_mfma_f32_16x16x32_bf16 v[140:143], v[100:103], v[124:127], 0
	s_waitcnt lgkmcnt(3)
	v_mfma_f32_16x16x32_bf16 v[140:143], v[104:107], v[128:131], v[140:143]
	s_waitcnt lgkmcnt(2)
	v_mfma_f32_16x16x32_bf16 v[140:143], v[108:111], v[132:135], v[140:143]
	s_waitcnt lgkmcnt(1)
	v_mfma_f32_16x16x32_bf16 v[140:143], v[112:115], v[136:139], v[140:143]
	s_nop 9
	s_waitcnt vmcnt(9) lgkmcnt(0)
	v_add_f32_e32 v182, v172, v140
	v_add_f32_e32 v183, v173, v141
	v_add_f32_e32 v184, v174, v142
	v_add_f32_e32 v185, v175, v143
	v_lshlrev_b32_e32 v186, 16, v160
	v_and_b32_e32 v187, 0xffff0000, v160
	v_lshlrev_b32_e32 v188, 16, v161
	v_and_b32_e32 v189, 0xffff0000, v161
	v_fmac_f32_e32 v182, v164, v186
	v_fmac_f32_e32 v183, v165, v187
	v_fmac_f32_e32 v184, v166, v188
	v_fmac_f32_e32 v185, v167, v189
	v_mul_f32_e32 v186, v182, v182
	v_mul_f32_e32 v187, v183, v183
	v_mul_f32_e32 v188, v184, v184
	v_mul_f32_e32 v189, v185, v185
	v_fmaak_f32 v186, v1, v186, 0x40135761
	v_fmaak_f32 v187, v1, v187, 0x40135761
	v_fmaak_f32 v188, v1, v188, 0x40135761
	v_fmaak_f32 v189, v1, v189, 0x40135761
	v_mul_f32_e32 v186, v182, v186
	v_mul_f32_e32 v187, v183, v187
	v_mul_f32_e32 v188, v184, v188
	v_mul_f32_e32 v189, v185, v189
	v_exp_f32_e64 v186, -v186
	v_exp_f32_e64 v187, -v187
	v_exp_f32_e64 v188, -v188
	v_exp_f32_e64 v189, -v189
	v_add_f32_e32 v186, 1.0, v186
	v_add_f32_e32 v187, 1.0, v187
	v_add_f32_e32 v188, 1.0, v188
	v_add_f32_e32 v189, 1.0, v189
	v_rcp_f32_e32 v186, v186
	v_rcp_f32_e32 v187, v187
	v_rcp_f32_e32 v188, v188
	v_rcp_f32_e32 v189, v189
	v_mul_f32_e32 v182, v182, v186
	v_mul_f32_e32 v183, v183, v187
	v_mul_f32_e32 v184, v184, v188
	v_mul_f32_e32 v185, v185, v189
	v_cvt_pk_bf16_f32 v148, v182, v183
	v_cvt_pk_bf16_f32 v149, v184, v185
	global_store_dwordx2 v156, v[148:149], s[12:13]
	ds_read_b128 v[124:127], v152 offset:4352
	ds_read_b128 v[128:131], v152 offset:4416
	ds_read_b128 v[132:135], v152 offset:4480
	ds_read_b128 v[136:139], v152 offset:4544
	ds_read_b64 v[160:161], v163 offset:512
	s_waitcnt lgkmcnt(4)
	v_mfma_f32_16x16x32_bf16 v[140:143], v[100:103], v[124:127], 0
	s_waitcnt lgkmcnt(3)
	v_mfma_f32_16x16x32_bf16 v[140:143], v[104:107], v[128:131], v[140:143]
	s_waitcnt lgkmcnt(2)
	v_mfma_f32_16x16x32_bf16 v[140:143], v[108:111], v[132:135], v[140:143]
	s_waitcnt lgkmcnt(1)
	v_mfma_f32_16x16x32_bf16 v[140:143], v[112:115], v[136:139], v[140:143]
	s_nop 9
	s_waitcnt vmcnt(9) lgkmcnt(0)
	v_add_f32_e32 v182, v176, v140
	v_add_f32_e32 v183, v177, v141
	v_add_f32_e32 v184, v178, v142
	v_add_f32_e32 v185, v179, v143
	v_lshlrev_b32_e32 v186, 16, v160
	v_and_b32_e32 v187, 0xffff0000, v160
	v_lshlrev_b32_e32 v188, 16, v161
	v_and_b32_e32 v189, 0xffff0000, v161
	v_fmac_f32_e32 v182, v164, v186
	v_fmac_f32_e32 v183, v165, v187
	v_fmac_f32_e32 v184, v166, v188
	v_fmac_f32_e32 v185, v167, v189
	v_mul_f32_e32 v186, v182, v182
	v_mul_f32_e32 v187, v183, v183
	v_mul_f32_e32 v188, v184, v184
	v_mul_f32_e32 v189, v185, v185
	v_fmaak_f32 v186, v1, v186, 0x40135761
	v_fmaak_f32 v187, v1, v187, 0x40135761
	v_fmaak_f32 v188, v1, v188, 0x40135761
	v_fmaak_f32 v189, v1, v189, 0x40135761
	v_mul_f32_e32 v186, v182, v186
	v_mul_f32_e32 v187, v183, v187
	v_mul_f32_e32 v188, v184, v188
	v_mul_f32_e32 v189, v185, v189
	v_exp_f32_e64 v186, -v186
	v_exp_f32_e64 v187, -v187
	v_exp_f32_e64 v188, -v188
	v_exp_f32_e64 v189, -v189
	v_add_f32_e32 v186, 1.0, v186
	v_add_f32_e32 v187, 1.0, v187
	v_add_f32_e32 v188, 1.0, v188
	v_add_f32_e32 v189, 1.0, v189
	v_rcp_f32_e32 v186, v186
	v_rcp_f32_e32 v187, v187
	v_rcp_f32_e32 v188, v188
	v_rcp_f32_e32 v189, v189
	v_mul_f32_e32 v182, v182, v186
	v_mul_f32_e32 v183, v183, v187
	v_mul_f32_e32 v184, v184, v188
	v_mul_f32_e32 v185, v185, v189
	v_cvt_pk_bf16_f32 v148, v182, v183
	v_cvt_pk_bf16_f32 v149, v184, v185
	global_store_dwordx2 v159, v[148:149], s[12:13]
	s_sub_u32 s12, s12, 65536
	s_subb_u32 s13, s13, 0
	s_add_u32 s14, s14, 2
	s_cmp_lt_u32 s14, 32
	s_cbranch_scc1 .Lssm_tileB_d1m0
	s_waitcnt vmcnt(0) lgkmcnt(0)

.Lssm_ctx_loop:
	s_lshl_b32 s22, s2, 3
	s_sub_u32 s21, s89, 4
	s_add_u32 s22, s22, s21
	s_lshl_b32 s21, s27, 2
	s_add_u32 s22, s22, s21
	s_lshr_b32 s23, s22, 6
	s_and_b32 s24, s22, 63
	s_lshl_b32 s25, s23, 8
	s_add_u32 s28, s24, 0
	s_lshl_b32 s29, s28, 13
	s_add_u32 s29, s29, 0x200000
	s_add_u32 s10, s62, s29
	s_addc_u32 s11, s63, 0
	global_load_dwordx4 v[84:87], v177, s[10:11]
	global_load_dwordx4 v[88:91], v177, s[10:11] offset:16
	s_add_u32 s12, s10, 0x1000
	s_addc_u32 s13, s11, 0
	global_load_dwordx4 v[92:95], v177, s[12:13]
	global_load_dwordx4 v[96:99], v177, s[12:13] offset:16
	s_lshl_b32 s29, s28, 12
	s_add_u32 s29, s29, 0x300000
	s_add_u32 s16, s62, s29
	s_addc_u32 s17, s63, 0
	global_load_dwordx4 v[100:103], v178, s[16:17]
	global_load_dwordx4 v[104:107], v178, s[16:17] offset:1024
	global_load_dwordx4 v[108:111], v178, s[16:17] offset:2048
	global_load_dwordx4 v[112:115], v178, s[16:17] offset:3072
	s_lshl_b32 s29, s28, 9
	s_add_u32 s29, s29, 0x100000
	s_add_u32 s18, s62, s29
	s_addc_u32 s19, s63, 0
	global_load_dwordx2 v[116:117], v179, s[18:19]
	s_lshl_b32 s30, s23, 1
	s_lshl_b32 s30, s30, 15
	s_lshl_b32 s31, s24, 8
	s_add_u32 s30, s30, s31
	v_mov_b32_e32 v120, 0
	v_mov_b32_e32 v121, 0
	s_lshl_b32 s31, s25, 5
	s_lshl_b32 s29, s24, 19
	s_add_u32 s31, s31, s29
	s_add_u32 s31, s31, 0x16800000
	s_add_u32 s4, s62, s31
	s_addc_u32 s5, s63, 0
	s_add_u32 s34, s4, 0
	s_addc_u32 s35, s5, 0
	global_load_dwordx4 v[80:83], v150, s[34:35]
	global_load_dwordx4 v[194:197], v193, s[34:35]
	s_mov_b64 s[10:11], s[34:35]
	s_add_u32 s10, s10, 1024
	s_addc_u32 s11, s11, 0
	global_load_dwordx4 v[144:147], v150, s[10:11]
	global_load_dwordx4 v[6:9], v193, s[10:11]
	s_mov_b64 s[34:35], s[10:11]
	s_add_u32 s10, s10, 1024
	s_addc_u32 s11, s11, 0
	s_mov_b32 s36, 0
	s_mov_b32 s14, 0
	s_mov_b32 s40, 0xffff0000
	s_waitcnt vmcnt(0)
	v_xor_b32_e32 v118, 0x80000000, v117
.Lssm_tile_d0m1:
	s_waitcnt vmcnt(2)
	v_cndmask_b32_e64 v124, 0, v80, s[66:67]
	v_cndmask_b32_e64 v125, 0, v81, s[66:67]
	v_cndmask_b32_e64 v126, 0, v82, s[66:67]
	v_cndmask_b32_e64 v127, 0, v83, s[66:67]
	v_cndmask_b32_e64 v132, 0, v194, s[66:67]
	v_cndmask_b32_e64 v133, 0, v195, s[66:67]
	v_cndmask_b32_e64 v134, 0, v196, s[66:67]
	v_cndmask_b32_e64 v135, 0, v197, s[66:67]
	v_mfma_f32_32x32x16_bf16 v[16:31], v[124:127], v[84:87], 0
	v_cndmask_b32_e64 v128, 0, v194, s[68:69]
	v_cndmask_b32_e64 v129, 0, v195, s[68:69]
	v_cndmask_b32_e64 v130, 0, v196, s[68:69]
	v_cndmask_b32_e64 v131, 0, v197, s[68:69]
	v_mfma_f32_32x32x16_bf16 v[32:47], v[124:127], v[88:91], 0
	v_cndmask_b32_e64 v136, 0, v80, s[68:69]
	v_cndmask_b32_e64 v137, 0, v81, s[68:69]
	v_cndmask_b32_e64 v138, 0, v82, s[68:69]
	v_cndmask_b32_e64 v139, 0, v83, s[68:69]
	v_mfma_f32_32x32x16_bf16 v[48:63], v[132:135], v[84:87], 0
	v_mfma_f32_32x32x16_bf16 v[64:79], v[132:135], v[88:91], 0
	v_mfma_f32_32x32x16_bf16 v[16:31], v[128:131], v[92:95], v[16:31]
	v_mfma_f32_32x32x16_bf16 v[32:47], v[128:131], v[96:99], v[32:47]
	v_mfma_f32_32x32x16_bf16 v[48:63], v[136:139], v[92:95], v[48:63]
	v_mfma_f32_32x32x16_bf16 v[64:79], v[136:139], v[96:99], v[64:79]
	v_add_u32_e32 v171, s36, v155
	s_nop 11
	global_load_dwordx4 v[80:83], v150, s[10:11]
	global_load_dwordx4 v[194:197], v193, s[10:11]
	s_add_u32 s34, s34, 1024
	s_addc_u32 s35, s35, 0
	s_add_u32 s10, s10, 1024
	s_addc_u32 s11, s11, 0
	v_fmac_f32_e32 v16, v116, v120
	v_fmac_f32_e32 v32, v116, v121
	v_fmac_f32_e32 v16, v118, v121
	v_fmac_f32_e32 v32, v117, v120
	v_cvt_pk_bf16_f32 v148, v16, v32
	ds_write_b32 v151, v148
	v_fmac_f32_e32 v17, v116, v16
	v_fmac_f32_e32 v33, v116, v32
	v_fmac_f32_e32 v17, v118, v32
	v_fmac_f32_e32 v33, v117, v16
	v_cvt_pk_bf16_f32 v149, v17, v33
	ds_write_b32 v151, v149 offset:272
	v_fmac_f32_e32 v18, v116, v17
	v_fmac_f32_e32 v34, v116, v33
	v_fmac_f32_e32 v18, v118, v33
	v_fmac_f32_e32 v34, v117, v17
	v_cvt_pk_bf16_f32 v148, v18, v34
	ds_write_b32 v151, v148 offset:544
	v_fmac_f32_e32 v19, v116, v18
	v_fmac_f32_e32 v35, v116, v34
	v_fmac_f32_e32 v19, v118, v34
	v_fmac_f32_e32 v35, v117, v18
	v_cvt_pk_bf16_f32 v149, v19, v35
	ds_write_b32 v151, v149 offset:816
	v_fmac_f32_e32 v48, v116, v19
	v_fmac_f32_e32 v64, v116, v35
	v_fmac_f32_e32 v48, v118, v35
	v_fmac_f32_e32 v64, v117, v19
	v_cvt_pk_bf16_f32 v148, v48, v64
	ds_write_b32 v151, v148 offset:1088
	v_fmac_f32_e32 v49, v116, v48
	v_fmac_f32_e32 v65, v116, v64
	v_fmac_f32_e32 v49, v118, v64
	v_fmac_f32_e32 v65, v117, v48
	v_cvt_pk_bf16_f32 v149, v49, v65
	ds_write_b32 v151, v149 offset:1360
	v_fmac_f32_e32 v50, v116, v49
	v_fmac_f32_e32 v66, v116, v65
	v_fmac_f32_e32 v50, v118, v65
	v_fmac_f32_e32 v66, v117, v49
	v_cvt_pk_bf16_f32 v148, v50, v66
	ds_write_b32 v151, v148 offset:1632
	v_fmac_f32_e32 v51, v116, v50
	v_fmac_f32_e32 v67, v116, v66
	v_fmac_f32_e32 v51, v118, v66
	v_fmac_f32_e32 v67, v117, v50
	v_cvt_pk_bf16_f32 v149, v51, v67
	ds_write_b32 v151, v149 offset:1904
	v_fmac_f32_e32 v20, v116, v51
	v_fmac_f32_e32 v36, v116, v67
	v_fmac_f32_e32 v20, v118, v67
	v_fmac_f32_e32 v36, v117, v51
	v_cvt_pk_bf16_f32 v148, v20, v36
	ds_write_b32 v151, v148 offset:2176
	v_fmac_f32_e32 v21, v116, v20
	v_fmac_f32_e32 v37, v116, v36
	v_fmac_f32_e32 v21, v118, v36
	v_fmac_f32_e32 v37, v117, v20
	v_cvt_pk_bf16_f32 v149, v21, v37
	ds_write_b32 v151, v149 offset:2448
	v_fmac_f32_e32 v22, v116, v21
	v_fmac_f32_e32 v38, v116, v37
	v_fmac_f32_e32 v22, v118, v37
	v_fmac_f32_e32 v38, v117, v21
	v_cvt_pk_bf16_f32 v148, v22, v38
	ds_write_b32 v151, v148 offset:2720
	v_fmac_f32_e32 v23, v116, v22
	v_fmac_f32_e32 v39, v116, v38
	v_fmac_f32_e32 v23, v118, v38
	v_fmac_f32_e32 v39, v117, v22
	v_cvt_pk_bf16_f32 v149, v23, v39
	ds_write_b32 v151, v149 offset:2992
	v_fmac_f32_e32 v52, v116, v23
	v_fmac_f32_e32 v68, v116, v39
	v_fmac_f32_e32 v52, v118, v39
	v_fmac_f32_e32 v68, v117, v23
	v_cvt_pk_bf16_f32 v148, v52, v68
	ds_write_b32 v151, v148 offset:3264
	v_fmac_f32_e32 v53, v116, v52
	v_fmac_f32_e32 v69, v116, v68
	v_fmac_f32_e32 v53, v118, v68
	v_fmac_f32_e32 v69, v117, v52
	v_cvt_pk_bf16_f32 v149, v53, v69
	ds_write_b32 v151, v149 offset:3536
	v_fmac_f32_e32 v54, v116, v53
	v_fmac_f32_e32 v70, v116, v69
	v_fmac_f32_e32 v54, v118, v69
	v_fmac_f32_e32 v70, v117, v53
	v_cvt_pk_bf16_f32 v148, v54, v70
	ds_write_b32 v151, v148 offset:3808
	v_fmac_f32_e32 v55, v116, v54
	v_fmac_f32_e32 v71, v116, v70
	v_fmac_f32_e32 v55, v118, v70
	v_fmac_f32_e32 v71, v117, v54
	v_cvt_pk_bf16_f32 v149, v55, v71
	ds_write_b32 v151, v149 offset:4080
	v_fmac_f32_e32 v24, v116, v55
	v_fmac_f32_e32 v40, v116, v71
	v_fmac_f32_e32 v24, v118, v71
	v_fmac_f32_e32 v40, v117, v55
	v_cvt_pk_bf16_f32 v148, v24, v40
	ds_write_b32 v151, v148 offset:4352
	v_fmac_f32_e32 v25, v116, v24
	v_fmac_f32_e32 v41, v116, v40
	v_fmac_f32_e32 v25, v118, v40
	v_fmac_f32_e32 v41, v117, v24
	v_cvt_pk_bf16_f32 v149, v25, v41
	ds_write_b32 v151, v149 offset:4624
	v_fmac_f32_e32 v26, v116, v25
	v_fmac_f32_e32 v42, v116, v41
	v_fmac_f32_e32 v26, v118, v41
	v_fmac_f32_e32 v42, v117, v25
	v_cvt_pk_bf16_f32 v148, v26, v42
	ds_write_b32 v151, v148 offset:4896
	v_fmac_f32_e32 v27, v116, v26
	v_fmac_f32_e32 v43, v116, v42
	v_fmac_f32_e32 v27, v118, v42
	v_fmac_f32_e32 v43, v117, v26
	v_cvt_pk_bf16_f32 v149, v27, v43
	ds_write_b32 v151, v149 offset:5168
	v_fmac_f32_e32 v56, v116, v27
	v_fmac_f32_e32 v72, v116, v43
	v_fmac_f32_e32 v56, v118, v43
	v_fmac_f32_e32 v72, v117, v27
	v_cvt_pk_bf16_f32 v148, v56, v72
	ds_write_b32 v151, v148 offset:5440
	v_fmac_f32_e32 v57, v116, v56
	v_fmac_f32_e32 v73, v116, v72
	v_fmac_f32_e32 v57, v118, v72
	v_fmac_f32_e32 v73, v117, v56
	v_cvt_pk_bf16_f32 v149, v57, v73
	ds_write_b32 v151, v149 offset:5712
	v_fmac_f32_e32 v58, v116, v57
	v_fmac_f32_e32 v74, v116, v73
	v_fmac_f32_e32 v58, v118, v73
	v_fmac_f32_e32 v74, v117, v57
	v_cvt_pk_bf16_f32 v148, v58, v74
	ds_write_b32 v151, v148 offset:5984
	v_fmac_f32_e32 v59, v116, v58
	v_fmac_f32_e32 v75, v116, v74
	v_fmac_f32_e32 v59, v118, v74
	v_fmac_f32_e32 v75, v117, v58
	v_cvt_pk_bf16_f32 v149, v59, v75
	ds_write_b32 v151, v149 offset:6256
	v_fmac_f32_e32 v28, v116, v59
	v_fmac_f32_e32 v44, v116, v75
	v_fmac_f32_e32 v28, v118, v75
	v_fmac_f32_e32 v44, v117, v59
	v_cvt_pk_bf16_f32 v148, v28, v44
	ds_write_b32 v151, v148 offset:6528
	v_fmac_f32_e32 v29, v116, v28
	v_fmac_f32_e32 v45, v116, v44
	v_fmac_f32_e32 v29, v118, v44
	v_fmac_f32_e32 v45, v117, v28
	v_cvt_pk_bf16_f32 v149, v29, v45
	ds_write_b32 v151, v149 offset:6800
	v_fmac_f32_e32 v30, v116, v29
	v_fmac_f32_e32 v46, v116, v45
	v_fmac_f32_e32 v30, v118, v45
	v_fmac_f32_e32 v46, v117, v29
	v_cvt_pk_bf16_f32 v148, v30, v46
	ds_write_b32 v151, v148 offset:7072
	v_fmac_f32_e32 v31, v116, v30
	v_fmac_f32_e32 v47, v116, v46
	v_fmac_f32_e32 v31, v118, v46
	v_fmac_f32_e32 v47, v117, v30
	v_cvt_pk_bf16_f32 v149, v31, v47
	ds_write_b32 v151, v149 offset:7344
	v_fmac_f32_e32 v60, v116, v31
	v_fmac_f32_e32 v76, v116, v47
	v_fmac_f32_e32 v60, v118, v47
	v_fmac_f32_e32 v76, v117, v31
	v_cvt_pk_bf16_f32 v148, v60, v76
	ds_write_b32 v151, v148 offset:7616
	v_fmac_f32_e32 v61, v116, v60
	v_fmac_f32_e32 v77, v116, v76
	v_fmac_f32_e32 v61, v118, v76
	v_fmac_f32_e32 v77, v117, v60
	v_cvt_pk_bf16_f32 v149, v61, v77
	ds_write_b32 v151, v149 offset:7888
	v_fmac_f32_e32 v62, v116, v61
	v_fmac_f32_e32 v78, v116, v77
	v_fmac_f32_e32 v62, v118, v77
	v_fmac_f32_e32 v78, v117, v61
	v_cvt_pk_bf16_f32 v148, v62, v78
	ds_write_b32 v151, v148 offset:8160
	v_fmac_f32_e32 v63, v116, v62
	v_fmac_f32_e32 v79, v116, v78
	v_fmac_f32_e32 v63, v118, v78
	v_fmac_f32_e32 v79, v117, v62
	v_cvt_pk_bf16_f32 v149, v63, v79
	ds_write_b32 v151, v149 offset:8432
	v_mov_b32_e32 v120, v63
	v_mov_b32_e32 v121, v79
	ds_read_b128 v[124:127], v152
	ds_read_b128 v[128:131], v152 offset:64
	ds_read_b128 v[132:135], v152 offset:128
	ds_read_b128 v[136:139], v152 offset:192
	s_waitcnt lgkmcnt(3)
	v_mfma_f32_16x16x32_bf16 v[140:143], v[100:103], v[124:127], 0
	s_waitcnt lgkmcnt(2)
	v_mfma_f32_16x16x32_bf16 v[140:143], v[104:107], v[128:131], v[140:143]
	s_waitcnt lgkmcnt(1)
	v_mfma_f32_16x16x32_bf16 v[140:143], v[108:111], v[132:135], v[140:143]
	s_waitcnt lgkmcnt(0)
	v_mfma_f32_16x16x32_bf16 v[140:143], v[112:115], v[136:139], v[140:143]
	s_nop 9
	v_cvt_pk_bf16_f32 v182, v140, v141
	v_cvt_pk_bf16_f32 v183, v142, v143
	ds_write_b64 v171, v[182:183]
	ds_read_b128 v[124:127], v152 offset:4352
	ds_read_b128 v[128:131], v152 offset:4416
	ds_read_b128 v[132:135], v152 offset:4480
	ds_read_b128 v[136:139], v152 offset:4544
	s_waitcnt lgkmcnt(3)
	v_mfma_f32_16x16x32_bf16 v[140:143], v[100:103], v[124:127], 0
	s_waitcnt lgkmcnt(2)
	v_mfma_f32_16x16x32_bf16 v[140:143], v[104:107], v[128:131], v[140:143]
	s_waitcnt lgkmcnt(1)
	v_mfma_f32_16x16x32_bf16 v[140:143], v[108:111], v[132:135], v[140:143]
	s_waitcnt lgkmcnt(0)
	v_mfma_f32_16x16x32_bf16 v[140:143], v[112:115], v[136:139], v[140:143]
	s_nop 9
	v_cvt_pk_bf16_f32 v182, v140, v141
	v_cvt_pk_bf16_f32 v183, v142, v143
	ds_write_b64 v171, v[182:183] offset:512
	s_add_u32 s36, s36, 1024
	s_waitcnt vmcnt(2)
	v_cndmask_b32_e64 v124, 0, v144, s[66:67]
	v_cndmask_b32_e64 v125, 0, v145, s[66:67]
	v_cndmask_b32_e64 v126, 0, v146, s[66:67]
	v_cndmask_b32_e64 v127, 0, v147, s[66:67]
	v_cndmask_b32_e64 v132, 0, v6, s[66:67]
	v_cndmask_b32_e64 v133, 0, v7, s[66:67]
	v_cndmask_b32_e64 v134, 0, v8, s[66:67]
	v_cndmask_b32_e64 v135, 0, v9, s[66:67]
	v_mfma_f32_32x32x16_bf16 v[16:31], v[124:127], v[84:87], 0
	v_cndmask_b32_e64 v128, 0, v6, s[68:69]
	v_cndmask_b32_e64 v129, 0, v7, s[68:69]
	v_cndmask_b32_e64 v130, 0, v8, s[68:69]
	v_cndmask_b32_e64 v131, 0, v9, s[68:69]
	v_mfma_f32_32x32x16_bf16 v[32:47], v[124:127], v[88:91], 0
	v_cndmask_b32_e64 v136, 0, v144, s[68:69]
	v_cndmask_b32_e64 v137, 0, v145, s[68:69]
	v_cndmask_b32_e64 v138, 0, v146, s[68:69]
	v_cndmask_b32_e64 v139, 0, v147, s[68:69]
	v_mfma_f32_32x32x16_bf16 v[48:63], v[132:135], v[84:87], 0
	v_mfma_f32_32x32x16_bf16 v[64:79], v[132:135], v[88:91], 0
	v_mfma_f32_32x32x16_bf16 v[16:31], v[128:131], v[92:95], v[16:31]
	v_mfma_f32_32x32x16_bf16 v[32:47], v[128:131], v[96:99], v[32:47]
	v_mfma_f32_32x32x16_bf16 v[48:63], v[136:139], v[92:95], v[48:63]
	v_mfma_f32_32x32x16_bf16 v[64:79], v[136:139], v[96:99], v[64:79]
	v_add_u32_e32 v171, s36, v155
	s_nop 11
	global_load_dwordx4 v[144:147], v150, s[10:11]
	global_load_dwordx4 v[6:9], v193, s[10:11]
	s_add_u32 s34, s34, 1024
	s_addc_u32 s35, s35, 0
	s_add_u32 s10, s10, 1024
	s_addc_u32 s11, s11, 0
	v_fmac_f32_e32 v16, v116, v120
	v_fmac_f32_e32 v32, v116, v121
	v_fmac_f32_e32 v16, v118, v121
	v_fmac_f32_e32 v32, v117, v120
	v_cvt_pk_bf16_f32 v148, v16, v32
	ds_write_b32 v151, v148
	v_fmac_f32_e32 v17, v116, v16
	v_fmac_f32_e32 v33, v116, v32
	v_fmac_f32_e32 v17, v118, v32
	v_fmac_f32_e32 v33, v117, v16
	v_cvt_pk_bf16_f32 v149, v17, v33
	ds_write_b32 v151, v149 offset:272
	v_fmac_f32_e32 v18, v116, v17
	v_fmac_f32_e32 v34, v116, v33
	v_fmac_f32_e32 v18, v118, v33
	v_fmac_f32_e32 v34, v117, v17
	v_cvt_pk_bf16_f32 v148, v18, v34
	ds_write_b32 v151, v148 offset:544
	v_fmac_f32_e32 v19, v116, v18
	v_fmac_f32_e32 v35, v116, v34
	v_fmac_f32_e32 v19, v118, v34
	v_fmac_f32_e32 v35, v117, v18
	v_cvt_pk_bf16_f32 v149, v19, v35
	ds_write_b32 v151, v149 offset:816
	v_fmac_f32_e32 v48, v116, v19
	v_fmac_f32_e32 v64, v116, v35
	v_fmac_f32_e32 v48, v118, v35
	v_fmac_f32_e32 v64, v117, v19
	v_cvt_pk_bf16_f32 v148, v48, v64
	ds_write_b32 v151, v148 offset:1088
	v_fmac_f32_e32 v49, v116, v48
	v_fmac_f32_e32 v65, v116, v64
	v_fmac_f32_e32 v49, v118, v64
	v_fmac_f32_e32 v65, v117, v48
	v_cvt_pk_bf16_f32 v149, v49, v65
	ds_write_b32 v151, v149 offset:1360
	v_fmac_f32_e32 v50, v116, v49
	v_fmac_f32_e32 v66, v116, v65
	v_fmac_f32_e32 v50, v118, v65
	v_fmac_f32_e32 v66, v117, v49
	v_cvt_pk_bf16_f32 v148, v50, v66
	ds_write_b32 v151, v148 offset:1632
	v_fmac_f32_e32 v51, v116, v50
	v_fmac_f32_e32 v67, v116, v66
	v_fmac_f32_e32 v51, v118, v66
	v_fmac_f32_e32 v67, v117, v50
	v_cvt_pk_bf16_f32 v149, v51, v67
	ds_write_b32 v151, v149 offset:1904
	v_fmac_f32_e32 v20, v116, v51
	v_fmac_f32_e32 v36, v116, v67
	v_fmac_f32_e32 v20, v118, v67
	v_fmac_f32_e32 v36, v117, v51
	v_cvt_pk_bf16_f32 v148, v20, v36
	ds_write_b32 v151, v148 offset:2176
	v_fmac_f32_e32 v21, v116, v20
	v_fmac_f32_e32 v37, v116, v36
	v_fmac_f32_e32 v21, v118, v36
	v_fmac_f32_e32 v37, v117, v20
	v_cvt_pk_bf16_f32 v149, v21, v37
	ds_write_b32 v151, v149 offset:2448
	v_fmac_f32_e32 v22, v116, v21
	v_fmac_f32_e32 v38, v116, v37
	v_fmac_f32_e32 v22, v118, v37
	v_fmac_f32_e32 v38, v117, v21
	v_cvt_pk_bf16_f32 v148, v22, v38
	ds_write_b32 v151, v148 offset:2720
	v_fmac_f32_e32 v23, v116, v22
	v_fmac_f32_e32 v39, v116, v38
	v_fmac_f32_e32 v23, v118, v38
	v_fmac_f32_e32 v39, v117, v22
	v_cvt_pk_bf16_f32 v149, v23, v39
	ds_write_b32 v151, v149 offset:2992
	v_fmac_f32_e32 v52, v116, v23
	v_fmac_f32_e32 v68, v116, v39
	v_fmac_f32_e32 v52, v118, v39
	v_fmac_f32_e32 v68, v117, v23
	v_cvt_pk_bf16_f32 v148, v52, v68
	ds_write_b32 v151, v148 offset:3264
	v_fmac_f32_e32 v53, v116, v52
	v_fmac_f32_e32 v69, v116, v68
	v_fmac_f32_e32 v53, v118, v68
	v_fmac_f32_e32 v69, v117, v52
	v_cvt_pk_bf16_f32 v149, v53, v69
	ds_write_b32 v151, v149 offset:3536
	v_fmac_f32_e32 v54, v116, v53
	v_fmac_f32_e32 v70, v116, v69
	v_fmac_f32_e32 v54, v118, v69
	v_fmac_f32_e32 v70, v117, v53
	v_cvt_pk_bf16_f32 v148, v54, v70
	ds_write_b32 v151, v148 offset:3808
	v_fmac_f32_e32 v55, v116, v54
	v_fmac_f32_e32 v71, v116, v70
	v_fmac_f32_e32 v55, v118, v70
	v_fmac_f32_e32 v71, v117, v54
	v_cvt_pk_bf16_f32 v149, v55, v71
	ds_write_b32 v151, v149 offset:4080
	v_fmac_f32_e32 v24, v116, v55
	v_fmac_f32_e32 v40, v116, v71
	v_fmac_f32_e32 v24, v118, v71
	v_fmac_f32_e32 v40, v117, v55
	v_cvt_pk_bf16_f32 v148, v24, v40
	ds_write_b32 v151, v148 offset:4352
	v_fmac_f32_e32 v25, v116, v24
	v_fmac_f32_e32 v41, v116, v40
	v_fmac_f32_e32 v25, v118, v40
	v_fmac_f32_e32 v41, v117, v24
	v_cvt_pk_bf16_f32 v149, v25, v41
	ds_write_b32 v151, v149 offset:4624
	v_fmac_f32_e32 v26, v116, v25
	v_fmac_f32_e32 v42, v116, v41
	v_fmac_f32_e32 v26, v118, v41
	v_fmac_f32_e32 v42, v117, v25
	v_cvt_pk_bf16_f32 v148, v26, v42
	ds_write_b32 v151, v148 offset:4896
	v_fmac_f32_e32 v27, v116, v26
	v_fmac_f32_e32 v43, v116, v42
	v_fmac_f32_e32 v27, v118, v42
	v_fmac_f32_e32 v43, v117, v26
	v_cvt_pk_bf16_f32 v149, v27, v43
	ds_write_b32 v151, v149 offset:5168
	v_fmac_f32_e32 v56, v116, v27
	v_fmac_f32_e32 v72, v116, v43
	v_fmac_f32_e32 v56, v118, v43
	v_fmac_f32_e32 v72, v117, v27
	v_cvt_pk_bf16_f32 v148, v56, v72
	ds_write_b32 v151, v148 offset:5440
	v_fmac_f32_e32 v57, v116, v56
	v_fmac_f32_e32 v73, v116, v72
	v_fmac_f32_e32 v57, v118, v72
	v_fmac_f32_e32 v73, v117, v56
	v_cvt_pk_bf16_f32 v149, v57, v73
	ds_write_b32 v151, v149 offset:5712
	v_fmac_f32_e32 v58, v116, v57
	v_fmac_f32_e32 v74, v116, v73
	v_fmac_f32_e32 v58, v118, v73
	v_fmac_f32_e32 v74, v117, v57
	v_cvt_pk_bf16_f32 v148, v58, v74
	ds_write_b32 v151, v148 offset:5984
	v_fmac_f32_e32 v59, v116, v58
	v_fmac_f32_e32 v75, v116, v74
	v_fmac_f32_e32 v59, v118, v74
	v_fmac_f32_e32 v75, v117, v58
	v_cvt_pk_bf16_f32 v149, v59, v75
	ds_write_b32 v151, v149 offset:6256
	v_fmac_f32_e32 v28, v116, v59
	v_fmac_f32_e32 v44, v116, v75
	v_fmac_f32_e32 v28, v118, v75
	v_fmac_f32_e32 v44, v117, v59
	v_cvt_pk_bf16_f32 v148, v28, v44
	ds_write_b32 v151, v148 offset:6528
	v_fmac_f32_e32 v29, v116, v28
	v_fmac_f32_e32 v45, v116, v44
	v_fmac_f32_e32 v29, v118, v44
	v_fmac_f32_e32 v45, v117, v28
	v_cvt_pk_bf16_f32 v149, v29, v45
	ds_write_b32 v151, v149 offset:6800
	v_fmac_f32_e32 v30, v116, v29
	v_fmac_f32_e32 v46, v116, v45
	v_fmac_f32_e32 v30, v118, v45
	v_fmac_f32_e32 v46, v117, v29
	v_cvt_pk_bf16_f32 v148, v30, v46
	ds_write_b32 v151, v148 offset:7072
	v_fmac_f32_e32 v31, v116, v30
	v_fmac_f32_e32 v47, v116, v46
	v_fmac_f32_e32 v31, v118, v46
	v_fmac_f32_e32 v47, v117, v30
	v_cvt_pk_bf16_f32 v149, v31, v47
	ds_write_b32 v151, v149 offset:7344
	v_fmac_f32_e32 v60, v116, v31
	v_fmac_f32_e32 v76, v116, v47
	v_fmac_f32_e32 v60, v118, v47
	v_fmac_f32_e32 v76, v117, v31
	v_cvt_pk_bf16_f32 v148, v60, v76
	ds_write_b32 v151, v148 offset:7616
	v_fmac_f32_e32 v61, v116, v60
	v_fmac_f32_e32 v77, v116, v76
	v_fmac_f32_e32 v61, v118, v76
	v_fmac_f32_e32 v77, v117, v60
	v_cvt_pk_bf16_f32 v149, v61, v77
	ds_write_b32 v151, v149 offset:7888
	v_fmac_f32_e32 v62, v116, v61
	v_fmac_f32_e32 v78, v116, v77
	v_fmac_f32_e32 v62, v118, v77
	v_fmac_f32_e32 v78, v117, v61
	v_cvt_pk_bf16_f32 v148, v62, v78
	ds_write_b32 v151, v148 offset:8160
	v_fmac_f32_e32 v63, v116, v62
	v_fmac_f32_e32 v79, v116, v78
	v_fmac_f32_e32 v63, v118, v78
	v_fmac_f32_e32 v79, v117, v62
	v_cvt_pk_bf16_f32 v149, v63, v79
	ds_write_b32 v151, v149 offset:8432
	v_mov_b32_e32 v120, v63
	v_mov_b32_e32 v121, v79
	ds_read_b128 v[124:127], v152
	ds_read_b128 v[128:131], v152 offset:64
	ds_read_b128 v[132:135], v152 offset:128
	ds_read_b128 v[136:139], v152 offset:192
	s_waitcnt lgkmcnt(3)
	v_mfma_f32_16x16x32_bf16 v[140:143], v[100:103], v[124:127], 0
	s_waitcnt lgkmcnt(2)
	v_mfma_f32_16x16x32_bf16 v[140:143], v[104:107], v[128:131], v[140:143]
	s_waitcnt lgkmcnt(1)
	v_mfma_f32_16x16x32_bf16 v[140:143], v[108:111], v[132:135], v[140:143]
	s_waitcnt lgkmcnt(0)
	v_mfma_f32_16x16x32_bf16 v[140:143], v[112:115], v[136:139], v[140:143]
	s_nop 9
	v_cvt_pk_bf16_f32 v182, v140, v141
	v_cvt_pk_bf16_f32 v183, v142, v143
	ds_write_b64 v171, v[182:183]
	ds_read_b128 v[124:127], v152 offset:4352
	ds_read_b128 v[128:131], v152 offset:4416
	ds_read_b128 v[132:135], v152 offset:4480
	ds_read_b128 v[136:139], v152 offset:4544
	s_waitcnt lgkmcnt(3)
	v_mfma_f32_16x16x32_bf16 v[140:143], v[100:103], v[124:127], 0
	s_waitcnt lgkmcnt(2)
	v_mfma_f32_16x16x32_bf16 v[140:143], v[104:107], v[128:131], v[140:143]
	s_waitcnt lgkmcnt(1)
	v_mfma_f32_16x16x32_bf16 v[140:143], v[108:111], v[132:135], v[140:143]
	s_waitcnt lgkmcnt(0)
	v_mfma_f32_16x16x32_bf16 v[140:143], v[112:115], v[136:139], v[140:143]
	s_nop 9
	v_cvt_pk_bf16_f32 v182, v140, v141
	v_cvt_pk_bf16_f32 v183, v142, v143
	ds_write_b64 v171, v[182:183] offset:512
	s_add_u32 s36, s36, 1024
	s_add_u32 s14, s14, 2
	s_cmp_lt_u32 s14, 8
	s_cbranch_scc1 .Lssm_tile_d0m1
	s_add_u32 s30, s30, 0x8000000
	s_add_u32 s16, s60, s30
	s_addc_u32 s17, s61, 0
	global_store_dword v180, v120, s[16:17]
	global_store_dword v170, v121, s[16:17]
	s_waitcnt vmcnt(0) lgkmcnt(0)
	s_add_u32 s28, s24, 64
	s_lshl_b32 s29, s28, 13
	s_add_u32 s29, s29, 0x200000
	s_add_u32 s10, s62, s29
	s_addc_u32 s11, s63, 0
	global_load_dwordx4 v[84:87], v177, s[10:11]
	global_load_dwordx4 v[88:91], v177, s[10:11] offset:16
	s_add_u32 s12, s10, 0x1000
	s_addc_u32 s13, s11, 0
	global_load_dwordx4 v[92:95], v177, s[12:13]
	global_load_dwordx4 v[96:99], v177, s[12:13] offset:16
	s_lshl_b32 s29, s28, 12
	s_add_u32 s29, s29, 0x300000
	s_add_u32 s16, s62, s29
	s_addc_u32 s17, s63, 0
	global_load_dwordx4 v[100:103], v178, s[16:17]
	global_load_dwordx4 v[104:107], v178, s[16:17] offset:1024
	global_load_dwordx4 v[108:111], v178, s[16:17] offset:2048
	global_load_dwordx4 v[112:115], v178, s[16:17] offset:3072
	s_lshl_b32 s29, s28, 9
	s_add_u32 s29, s29, 0x100000
	s_add_u32 s18, s62, s29
	s_addc_u32 s19, s63, 0
	global_load_dwordx2 v[116:117], v179, s[18:19]
	s_lshl_b32 s30, s23, 1
	s_add_u32 s30, s30, 1
	s_lshl_b32 s30, s30, 15
	s_lshl_b32 s31, s24, 8
	s_add_u32 s30, s30, s31
	v_mov_b32_e32 v120, 0
	v_mov_b32_e32 v121, 0
	v_readlane_b32 s34, v254, 28
	v_readlane_b32 s35, v254, 29
	s_nop 3
	s_lshl_b32 s31, s24, 6
	s_add_u32 s34, s34, s31
	s_addc_u32 s35, s35, 0
	global_load_dwordx4 v[164:167], v181, s[34:35]
	s_lshl_b32 s31, s25, 5
	s_lshl_b32 s29, s24, 19
	s_add_u32 s31, s31, s29
	s_add_u32 s31, s31, 0x16800000
	s_add_u32 s4, s62, s31
	s_addc_u32 s5, s63, 0
	s_lshl_b32 s31, s25, 11
	s_lshl_b32 s29, s24, 5
	s_add_u32 s31, s31, s29
	s_add_u32 s31, s31, 0x14800000
	s_add_u32 s6, s62, s31
	s_addc_u32 s7, s63, 0
	s_add_u32 s34, s4, 7168
	s_addc_u32 s35, s5, 0
	global_load_dwordx4 v[80:83], v150, s[34:35]
	global_load_dwordx4 v[194:197], v193, s[34:35]
	s_mov_b64 s[10:11], s[34:35]
	s_sub_u32 s10, s10, 1024
	s_subb_u32 s11, s11, 0
	global_load_dwordx4 v[144:147], v150, s[10:11]
	global_load_dwordx4 v[6:9], v193, s[10:11]
	s_mov_b64 s[34:35], s[10:11]
	s_sub_u32 s10, s10, 1024
	s_subb_u32 s11, s11, 0
	s_add_u32 s12, s6, 458752
	s_addc_u32 s13, s7, 0
	s_mov_b32 s36, 7168
	s_mov_b32 s14, 0
	s_mov_b32 s40, 0xffff0000
	s_waitcnt vmcnt(0)
	v_xor_b32_e32 v118, 0x80000000, v117
.Lssm_tile_d1m2:
	s_waitcnt vmcnt(6)
	v_cndmask_b32_e64 v124, 0, v80, s[66:67]
	v_cndmask_b32_e64 v125, 0, v81, s[66:67]
	v_cndmask_b32_e64 v126, 0, v82, s[66:67]
	v_cndmask_b32_e64 v127, 0, v83, s[66:67]
	v_cndmask_b32_e64 v132, 0, v194, s[66:67]
	v_cndmask_b32_e64 v133, 0, v195, s[66:67]
	v_cndmask_b32_e64 v134, 0, v196, s[66:67]
	v_cndmask_b32_e64 v135, 0, v197, s[66:67]
	v_mfma_f32_32x32x16_bf16 v[16:31], v[124:127], v[84:87], 0
	v_cndmask_b32_e64 v128, 0, v194, s[68:69]
	v_cndmask_b32_e64 v129, 0, v195, s[68:69]
	v_cndmask_b32_e64 v130, 0, v196, s[68:69]
	v_cndmask_b32_e64 v131, 0, v197, s[68:69]
	v_mfma_f32_32x32x16_bf16 v[32:47], v[124:127], v[88:91], 0
	v_cndmask_b32_e64 v136, 0, v80, s[68:69]
	v_cndmask_b32_e64 v137, 0, v81, s[68:69]
	v_cndmask_b32_e64 v138, 0, v82, s[68:69]
	v_cndmask_b32_e64 v139, 0, v83, s[68:69]
	v_mfma_f32_32x32x16_bf16 v[48:63], v[132:135], v[84:87], 0
	v_mfma_f32_32x32x16_bf16 v[64:79], v[132:135], v[88:91], 0
	v_mfma_f32_32x32x16_bf16 v[16:31], v[128:131], v[92:95], v[16:31]
	v_mfma_f32_32x32x16_bf16 v[32:47], v[128:131], v[96:99], v[32:47]
	v_mfma_f32_32x32x16_bf16 v[48:63], v[136:139], v[92:95], v[48:63]
	v_mfma_f32_32x32x16_bf16 v[64:79], v[136:139], v[96:99], v[64:79]
	v_add_u32_e32 v171, s36, v155
	ds_write_b128 v162, v[80:83]
	s_nop 11
	global_load_dwordx4 v[80:83], v150, s[10:11]
	global_load_dwordx4 v[194:197], v193, s[10:11]
	s_sub_u32 s34, s34, 1024
	s_subb_u32 s35, s35, 0
	s_sub_u32 s10, s10, 1024
	s_subb_u32 s11, s11, 0
	v_fmac_f32_e32 v63, v116, v120
	v_fmac_f32_e32 v79, v116, v121
	v_fmac_f32_e32 v63, v118, v121
	v_fmac_f32_e32 v79, v117, v120
	v_cvt_pk_bf16_f32 v148, v63, v79
	ds_write_b32 v151, v148 offset:8432
	v_fmac_f32_e32 v62, v116, v63
	v_fmac_f32_e32 v78, v116, v79
	v_fmac_f32_e32 v62, v118, v79
	v_fmac_f32_e32 v78, v117, v63
	v_cvt_pk_bf16_f32 v149, v62, v78
	ds_write_b32 v151, v149 offset:8160
	v_fmac_f32_e32 v61, v116, v62
	v_fmac_f32_e32 v77, v116, v78
	v_fmac_f32_e32 v61, v118, v78
	v_fmac_f32_e32 v77, v117, v62
	v_cvt_pk_bf16_f32 v148, v61, v77
	ds_write_b32 v151, v148 offset:7888
	v_fmac_f32_e32 v60, v116, v61
	v_fmac_f32_e32 v76, v116, v77
	v_fmac_f32_e32 v60, v118, v77
	v_fmac_f32_e32 v76, v117, v61
	v_cvt_pk_bf16_f32 v149, v60, v76
	ds_write_b32 v151, v149 offset:7616
	v_fmac_f32_e32 v31, v116, v60
	v_fmac_f32_e32 v47, v116, v76
	v_fmac_f32_e32 v31, v118, v76
	v_fmac_f32_e32 v47, v117, v60
	v_cvt_pk_bf16_f32 v148, v31, v47
	ds_write_b32 v151, v148 offset:7344
	v_fmac_f32_e32 v30, v116, v31
	v_fmac_f32_e32 v46, v116, v47
	v_fmac_f32_e32 v30, v118, v47
	v_fmac_f32_e32 v46, v117, v31
	v_cvt_pk_bf16_f32 v149, v30, v46
	ds_write_b32 v151, v149 offset:7072
	v_fmac_f32_e32 v29, v116, v30
	v_fmac_f32_e32 v45, v116, v46
	v_fmac_f32_e32 v29, v118, v46
	v_fmac_f32_e32 v45, v117, v30
	v_cvt_pk_bf16_f32 v148, v29, v45
	ds_write_b32 v151, v148 offset:6800
	v_fmac_f32_e32 v28, v116, v29
	v_fmac_f32_e32 v44, v116, v45
	v_fmac_f32_e32 v28, v118, v45
	v_fmac_f32_e32 v44, v117, v29
	v_cvt_pk_bf16_f32 v149, v28, v44
	ds_write_b32 v151, v149 offset:6528
	v_fmac_f32_e32 v59, v116, v28
	v_fmac_f32_e32 v75, v116, v44
	v_fmac_f32_e32 v59, v118, v44
	v_fmac_f32_e32 v75, v117, v28
	v_cvt_pk_bf16_f32 v148, v59, v75
	ds_write_b32 v151, v148 offset:6256
	v_fmac_f32_e32 v58, v116, v59
	v_fmac_f32_e32 v74, v116, v75
	v_fmac_f32_e32 v58, v118, v75
	v_fmac_f32_e32 v74, v117, v59
	v_cvt_pk_bf16_f32 v149, v58, v74
	ds_write_b32 v151, v149 offset:5984
	v_fmac_f32_e32 v57, v116, v58
	v_fmac_f32_e32 v73, v116, v74
	v_fmac_f32_e32 v57, v118, v74
	v_fmac_f32_e32 v73, v117, v58
	v_cvt_pk_bf16_f32 v148, v57, v73
	ds_write_b32 v151, v148 offset:5712
	v_fmac_f32_e32 v56, v116, v57
	v_fmac_f32_e32 v72, v116, v73
	v_fmac_f32_e32 v56, v118, v73
	v_fmac_f32_e32 v72, v117, v57
	v_cvt_pk_bf16_f32 v149, v56, v72
	ds_write_b32 v151, v149 offset:5440
	v_fmac_f32_e32 v27, v116, v56
	v_fmac_f32_e32 v43, v116, v72
	v_fmac_f32_e32 v27, v118, v72
	v_fmac_f32_e32 v43, v117, v56
	v_cvt_pk_bf16_f32 v148, v27, v43
	ds_write_b32 v151, v148 offset:5168
	v_fmac_f32_e32 v26, v116, v27
	v_fmac_f32_e32 v42, v116, v43
	v_fmac_f32_e32 v26, v118, v43
	v_fmac_f32_e32 v42, v117, v27
	v_cvt_pk_bf16_f32 v149, v26, v42
	ds_write_b32 v151, v149 offset:4896
	v_fmac_f32_e32 v25, v116, v26
	v_fmac_f32_e32 v41, v116, v42
	v_fmac_f32_e32 v25, v118, v42
	v_fmac_f32_e32 v41, v117, v26
	v_cvt_pk_bf16_f32 v148, v25, v41
	ds_write_b32 v151, v148 offset:4624
	v_fmac_f32_e32 v24, v116, v25
	v_fmac_f32_e32 v40, v116, v41
	v_fmac_f32_e32 v24, v118, v41
	v_fmac_f32_e32 v40, v117, v25
	v_cvt_pk_bf16_f32 v149, v24, v40
	ds_write_b32 v151, v149 offset:4352
	v_fmac_f32_e32 v55, v116, v24
	v_fmac_f32_e32 v71, v116, v40
	v_fmac_f32_e32 v55, v118, v40
	v_fmac_f32_e32 v71, v117, v24
	v_cvt_pk_bf16_f32 v148, v55, v71
	ds_write_b32 v151, v148 offset:4080
	v_fmac_f32_e32 v54, v116, v55
	v_fmac_f32_e32 v70, v116, v71
	v_fmac_f32_e32 v54, v118, v71
	v_fmac_f32_e32 v70, v117, v55
	v_cvt_pk_bf16_f32 v149, v54, v70
	ds_write_b32 v151, v149 offset:3808
	v_fmac_f32_e32 v53, v116, v54
	v_fmac_f32_e32 v69, v116, v70
	v_fmac_f32_e32 v53, v118, v70
	v_fmac_f32_e32 v69, v117, v54
	v_cvt_pk_bf16_f32 v148, v53, v69
	ds_write_b32 v151, v148 offset:3536
	v_fmac_f32_e32 v52, v116, v53
	v_fmac_f32_e32 v68, v116, v69
	v_fmac_f32_e32 v52, v118, v69
	v_fmac_f32_e32 v68, v117, v53
	v_cvt_pk_bf16_f32 v149, v52, v68
	ds_write_b32 v151, v149 offset:3264
	v_fmac_f32_e32 v23, v116, v52
	v_fmac_f32_e32 v39, v116, v68
	v_fmac_f32_e32 v23, v118, v68
	v_fmac_f32_e32 v39, v117, v52
	v_cvt_pk_bf16_f32 v148, v23, v39
	ds_write_b32 v151, v148 offset:2992
	v_fmac_f32_e32 v22, v116, v23
	v_fmac_f32_e32 v38, v116, v39
	v_fmac_f32_e32 v22, v118, v39
	v_fmac_f32_e32 v38, v117, v23
	v_cvt_pk_bf16_f32 v149, v22, v38
	ds_write_b32 v151, v149 offset:2720
	v_fmac_f32_e32 v21, v116, v22
	v_fmac_f32_e32 v37, v116, v38
	v_fmac_f32_e32 v21, v118, v38
	v_fmac_f32_e32 v37, v117, v22
	v_cvt_pk_bf16_f32 v148, v21, v37
	ds_write_b32 v151, v148 offset:2448
	v_fmac_f32_e32 v20, v116, v21
	v_fmac_f32_e32 v36, v116, v37
	v_fmac_f32_e32 v20, v118, v37
	v_fmac_f32_e32 v36, v117, v21
	v_cvt_pk_bf16_f32 v149, v20, v36
	ds_write_b32 v151, v149 offset:2176
	v_fmac_f32_e32 v51, v116, v20
	v_fmac_f32_e32 v67, v116, v36
	v_fmac_f32_e32 v51, v118, v36
	v_fmac_f32_e32 v67, v117, v20
	v_cvt_pk_bf16_f32 v148, v51, v67
	ds_write_b32 v151, v148 offset:1904
	v_fmac_f32_e32 v50, v116, v51
	v_fmac_f32_e32 v66, v116, v67
	v_fmac_f32_e32 v50, v118, v67
	v_fmac_f32_e32 v66, v117, v51
	v_cvt_pk_bf16_f32 v149, v50, v66
	ds_write_b32 v151, v149 offset:1632
	v_fmac_f32_e32 v49, v116, v50
	v_fmac_f32_e32 v65, v116, v66
	v_fmac_f32_e32 v49, v118, v66
	v_fmac_f32_e32 v65, v117, v50
	v_cvt_pk_bf16_f32 v148, v49, v65
	ds_write_b32 v151, v148 offset:1360
	v_fmac_f32_e32 v48, v116, v49
	v_fmac_f32_e32 v64, v116, v65
	v_fmac_f32_e32 v48, v118, v65
	v_fmac_f32_e32 v64, v117, v49
	v_cvt_pk_bf16_f32 v149, v48, v64
	ds_write_b32 v151, v149 offset:1088
	v_fmac_f32_e32 v19, v116, v48
	v_fmac_f32_e32 v35, v116, v64
	v_fmac_f32_e32 v19, v118, v64
	v_fmac_f32_e32 v35, v117, v48
	v_cvt_pk_bf16_f32 v148, v19, v35
	ds_write_b32 v151, v148 offset:816
	v_fmac_f32_e32 v18, v116, v19
	v_fmac_f32_e32 v34, v116, v35
	v_fmac_f32_e32 v18, v118, v35
	v_fmac_f32_e32 v34, v117, v19
	v_cvt_pk_bf16_f32 v149, v18, v34
	ds_write_b32 v151, v149 offset:544
	v_fmac_f32_e32 v17, v116, v18
	v_fmac_f32_e32 v33, v116, v34
	v_fmac_f32_e32 v17, v118, v34
	v_fmac_f32_e32 v33, v117, v18
	v_cvt_pk_bf16_f32 v148, v17, v33
	ds_write_b32 v151, v148 offset:272
	v_fmac_f32_e32 v16, v116, v17
	v_fmac_f32_e32 v32, v116, v33
	v_fmac_f32_e32 v16, v118, v33
	v_fmac_f32_e32 v32, v117, v17
	v_cvt_pk_bf16_f32 v149, v16, v32
	ds_write_b32 v151, v149
	v_mov_b32_e32 v120, v16
	v_mov_b32_e32 v121, v32
	ds_read_b128 v[124:127], v152
	ds_read_b128 v[128:131], v152 offset:64
	ds_read_b128 v[132:135], v152 offset:128
	ds_read_b128 v[136:139], v152 offset:192
	ds_read_b64 v[168:169], v171
	ds_read_b64 v[160:161], v163
	s_waitcnt lgkmcnt(5)
	v_mfma_f32_16x16x32_bf16 v[140:143], v[100:103], v[124:127], 0
	s_waitcnt lgkmcnt(4)
	v_mfma_f32_16x16x32_bf16 v[140:143], v[104:107], v[128:131], v[140:143]
	s_waitcnt lgkmcnt(3)
	v_mfma_f32_16x16x32_bf16 v[140:143], v[108:111], v[132:135], v[140:143]
	s_waitcnt lgkmcnt(2)
	v_mfma_f32_16x16x32_bf16 v[140:143], v[112:115], v[136:139], v[140:143]
	s_nop 9
	s_waitcnt lgkmcnt(0)
	v_lshlrev_b32_e32 v182, 16, v168
	v_and_b32_e32 v183, 0xffff0000, v168
	v_lshlrev_b32_e32 v184, 16, v169
	v_and_b32_e32 v185, 0xffff0000, v169
	v_add_f32_e32 v182, v182, v140
	v_add_f32_e32 v183, v183, v141
	v_add_f32_e32 v184, v184, v142
	v_add_f32_e32 v185, v185, v143
	v_lshlrev_b32_e32 v186, 16, v160
	v_and_b32_e32 v187, 0xffff0000, v160
	v_lshlrev_b32_e32 v188, 16, v161
	v_and_b32_e32 v189, 0xffff0000, v161
	v_fmac_f32_e32 v182, v164, v186
	v_fmac_f32_e32 v183, v165, v187
	v_fmac_f32_e32 v184, v166, v188
	v_fmac_f32_e32 v185, v167, v189
	v_mul_f32_e32 v186, v182, v182
	v_mul_f32_e32 v187, v183, v183
	v_mul_f32_e32 v188, v184, v184
	v_mul_f32_e32 v189, v185, v185
	v_fmaak_f32 v186, v1, v186, 0x40135761
	v_fmaak_f32 v187, v1, v187, 0x40135761
	v_fmaak_f32 v188, v1, v188, 0x40135761
	v_fmaak_f32 v189, v1, v189, 0x40135761
	v_mul_f32_e32 v186, v182, v186
	v_mul_f32_e32 v187, v183, v187
	v_mul_f32_e32 v188, v184, v188
	v_mul_f32_e32 v189, v185, v189
	v_exp_f32_e64 v186, -v186
	v_exp_f32_e64 v187, -v187
	v_exp_f32_e64 v188, -v188
	v_exp_f32_e64 v189, -v189
	v_add_f32_e32 v186, 1.0, v186
	v_add_f32_e32 v187, 1.0, v187
	v_add_f32_e32 v188, 1.0, v188
	v_add_f32_e32 v189, 1.0, v189
	v_rcp_f32_e32 v186, v186
	v_rcp_f32_e32 v187, v187
	v_rcp_f32_e32 v188, v188
	v_rcp_f32_e32 v189, v189
	v_mul_f32_e32 v182, v182, v186
	v_mul_f32_e32 v183, v183, v187
	v_mul_f32_e32 v184, v184, v188
	v_mul_f32_e32 v185, v185, v189
	v_cvt_pk_bf16_f32 v148, v182, v183
	v_cvt_pk_bf16_f32 v149, v184, v185
	global_store_dwordx2 v156, v[148:149], s[12:13]
	ds_read_b128 v[124:127], v152 offset:4352
	ds_read_b128 v[128:131], v152 offset:4416
	ds_read_b128 v[132:135], v152 offset:4480
	ds_read_b128 v[136:139], v152 offset:4544
	ds_read_b64 v[168:169], v171 offset:512
	ds_read_b64 v[160:161], v163 offset:512
	s_waitcnt lgkmcnt(5)
	v_mfma_f32_16x16x32_bf16 v[140:143], v[100:103], v[124:127], 0
	s_waitcnt lgkmcnt(4)
	v_mfma_f32_16x16x32_bf16 v[140:143], v[104:107], v[128:131], v[140:143]
	s_waitcnt lgkmcnt(3)
	v_mfma_f32_16x16x32_bf16 v[140:143], v[108:111], v[132:135], v[140:143]
	s_waitcnt lgkmcnt(2)
	v_mfma_f32_16x16x32_bf16 v[140:143], v[112:115], v[136:139], v[140:143]
	s_nop 9
	s_waitcnt lgkmcnt(0)
	v_lshlrev_b32_e32 v182, 16, v168
	v_and_b32_e32 v183, 0xffff0000, v168
	v_lshlrev_b32_e32 v184, 16, v169
	v_and_b32_e32 v185, 0xffff0000, v169
	v_add_f32_e32 v182, v182, v140
	v_add_f32_e32 v183, v183, v141
	v_add_f32_e32 v184, v184, v142
	v_add_f32_e32 v185, v185, v143
	v_lshlrev_b32_e32 v186, 16, v160
	v_and_b32_e32 v187, 0xffff0000, v160
	v_lshlrev_b32_e32 v188, 16, v161
	v_and_b32_e32 v189, 0xffff0000, v161
	v_fmac_f32_e32 v182, v164, v186
	v_fmac_f32_e32 v183, v165, v187
	v_fmac_f32_e32 v184, v166, v188
	v_fmac_f32_e32 v185, v167, v189
	v_mul_f32_e32 v186, v182, v182
	v_mul_f32_e32 v187, v183, v183
	v_mul_f32_e32 v188, v184, v184
	v_mul_f32_e32 v189, v185, v185
	v_fmaak_f32 v186, v1, v186, 0x40135761
	v_fmaak_f32 v187, v1, v187, 0x40135761
	v_fmaak_f32 v188, v1, v188, 0x40135761
	v_fmaak_f32 v189, v1, v189, 0x40135761
	v_mul_f32_e32 v186, v182, v186
	v_mul_f32_e32 v187, v183, v187
	v_mul_f32_e32 v188, v184, v188
	v_mul_f32_e32 v189, v185, v189
	v_exp_f32_e64 v186, -v186
	v_exp_f32_e64 v187, -v187
	v_exp_f32_e64 v188, -v188
	v_exp_f32_e64 v189, -v189
	v_add_f32_e32 v186, 1.0, v186
	v_add_f32_e32 v187, 1.0, v187
	v_add_f32_e32 v188, 1.0, v188
	v_add_f32_e32 v189, 1.0, v189
	v_rcp_f32_e32 v186, v186
	v_rcp_f32_e32 v187, v187
	v_rcp_f32_e32 v188, v188
	v_rcp_f32_e32 v189, v189
	v_mul_f32_e32 v182, v182, v186
	v_mul_f32_e32 v183, v183, v187
	v_mul_f32_e32 v184, v184, v188
	v_mul_f32_e32 v185, v185, v189
	v_cvt_pk_bf16_f32 v148, v182, v183
	v_cvt_pk_bf16_f32 v149, v184, v185
	global_store_dwordx2 v159, v[148:149], s[12:13]
	s_sub_u32 s12, s12, 65536
	s_subb_u32 s13, s13, 0
	s_sub_u32 s36, s36, 1024
	s_waitcnt vmcnt(6)
	v_cndmask_b32_e64 v124, 0, v144, s[66:67]
	v_cndmask_b32_e64 v125, 0, v145, s[66:67]
	v_cndmask_b32_e64 v126, 0, v146, s[66:67]
	v_cndmask_b32_e64 v127, 0, v147, s[66:67]
	v_cndmask_b32_e64 v132, 0, v6, s[66:67]
	v_cndmask_b32_e64 v133, 0, v7, s[66:67]
	v_cndmask_b32_e64 v134, 0, v8, s[66:67]
	v_cndmask_b32_e64 v135, 0, v9, s[66:67]
	v_mfma_f32_32x32x16_bf16 v[16:31], v[124:127], v[84:87], 0
	v_cndmask_b32_e64 v128, 0, v6, s[68:69]
	v_cndmask_b32_e64 v129, 0, v7, s[68:69]
	v_cndmask_b32_e64 v130, 0, v8, s[68:69]
	v_cndmask_b32_e64 v131, 0, v9, s[68:69]
	v_mfma_f32_32x32x16_bf16 v[32:47], v[124:127], v[88:91], 0
	v_cndmask_b32_e64 v136, 0, v144, s[68:69]
	v_cndmask_b32_e64 v137, 0, v145, s[68:69]
	v_cndmask_b32_e64 v138, 0, v146, s[68:69]
	v_cndmask_b32_e64 v139, 0, v147, s[68:69]
	v_mfma_f32_32x32x16_bf16 v[48:63], v[132:135], v[84:87], 0
	v_mfma_f32_32x32x16_bf16 v[64:79], v[132:135], v[88:91], 0
	v_mfma_f32_32x32x16_bf16 v[16:31], v[128:131], v[92:95], v[16:31]
	v_mfma_f32_32x32x16_bf16 v[32:47], v[128:131], v[96:99], v[32:47]
	v_mfma_f32_32x32x16_bf16 v[48:63], v[136:139], v[92:95], v[48:63]
	v_mfma_f32_32x32x16_bf16 v[64:79], v[136:139], v[96:99], v[64:79]
	v_add_u32_e32 v171, s36, v155
	ds_write_b128 v162, v[144:147]
	s_nop 11
	global_load_dwordx4 v[144:147], v150, s[10:11]
	global_load_dwordx4 v[6:9], v193, s[10:11]
	s_sub_u32 s34, s34, 1024
	s_subb_u32 s35, s35, 0
	s_sub_u32 s10, s10, 1024
	s_subb_u32 s11, s11, 0
	v_fmac_f32_e32 v63, v116, v120
	v_fmac_f32_e32 v79, v116, v121
	v_fmac_f32_e32 v63, v118, v121
	v_fmac_f32_e32 v79, v117, v120
	v_cvt_pk_bf16_f32 v148, v63, v79
	ds_write_b32 v151, v148 offset:8432
	v_fmac_f32_e32 v62, v116, v63
	v_fmac_f32_e32 v78, v116, v79
	v_fmac_f32_e32 v62, v118, v79
	v_fmac_f32_e32 v78, v117, v63
	v_cvt_pk_bf16_f32 v149, v62, v78
	ds_write_b32 v151, v149 offset:8160
	v_fmac_f32_e32 v61, v116, v62
	v_fmac_f32_e32 v77, v116, v78
	v_fmac_f32_e32 v61, v118, v78
	v_fmac_f32_e32 v77, v117, v62
	v_cvt_pk_bf16_f32 v148, v61, v77
	ds_write_b32 v151, v148 offset:7888
	v_fmac_f32_e32 v60, v116, v61
	v_fmac_f32_e32 v76, v116, v77
	v_fmac_f32_e32 v60, v118, v77
	v_fmac_f32_e32 v76, v117, v61
	v_cvt_pk_bf16_f32 v149, v60, v76
	ds_write_b32 v151, v149 offset:7616
	v_fmac_f32_e32 v31, v116, v60
	v_fmac_f32_e32 v47, v116, v76
	v_fmac_f32_e32 v31, v118, v76
	v_fmac_f32_e32 v47, v117, v60
	v_cvt_pk_bf16_f32 v148, v31, v47
	ds_write_b32 v151, v148 offset:7344
	v_fmac_f32_e32 v30, v116, v31
	v_fmac_f32_e32 v46, v116, v47
	v_fmac_f32_e32 v30, v118, v47
	v_fmac_f32_e32 v46, v117, v31
	v_cvt_pk_bf16_f32 v149, v30, v46
	ds_write_b32 v151, v149 offset:7072
	v_fmac_f32_e32 v29, v116, v30
	v_fmac_f32_e32 v45, v116, v46
	v_fmac_f32_e32 v29, v118, v46
	v_fmac_f32_e32 v45, v117, v30
	v_cvt_pk_bf16_f32 v148, v29, v45
	ds_write_b32 v151, v148 offset:6800
	v_fmac_f32_e32 v28, v116, v29
	v_fmac_f32_e32 v44, v116, v45
	v_fmac_f32_e32 v28, v118, v45
	v_fmac_f32_e32 v44, v117, v29
	v_cvt_pk_bf16_f32 v149, v28, v44
	ds_write_b32 v151, v149 offset:6528
	v_fmac_f32_e32 v59, v116, v28
	v_fmac_f32_e32 v75, v116, v44
	v_fmac_f32_e32 v59, v118, v44
	v_fmac_f32_e32 v75, v117, v28
	v_cvt_pk_bf16_f32 v148, v59, v75
	ds_write_b32 v151, v148 offset:6256
	v_fmac_f32_e32 v58, v116, v59
	v_fmac_f32_e32 v74, v116, v75
	v_fmac_f32_e32 v58, v118, v75
	v_fmac_f32_e32 v74, v117, v59
	v_cvt_pk_bf16_f32 v149, v58, v74
	ds_write_b32 v151, v149 offset:5984
	v_fmac_f32_e32 v57, v116, v58
	v_fmac_f32_e32 v73, v116, v74
	v_fmac_f32_e32 v57, v118, v74
	v_fmac_f32_e32 v73, v117, v58
	v_cvt_pk_bf16_f32 v148, v57, v73
	ds_write_b32 v151, v148 offset:5712
	v_fmac_f32_e32 v56, v116, v57
	v_fmac_f32_e32 v72, v116, v73
	v_fmac_f32_e32 v56, v118, v73
	v_fmac_f32_e32 v72, v117, v57
	v_cvt_pk_bf16_f32 v149, v56, v72
	ds_write_b32 v151, v149 offset:5440
	v_fmac_f32_e32 v27, v116, v56
	v_fmac_f32_e32 v43, v116, v72
	v_fmac_f32_e32 v27, v118, v72
	v_fmac_f32_e32 v43, v117, v56
	v_cvt_pk_bf16_f32 v148, v27, v43
	ds_write_b32 v151, v148 offset:5168
	v_fmac_f32_e32 v26, v116, v27
	v_fmac_f32_e32 v42, v116, v43
	v_fmac_f32_e32 v26, v118, v43
	v_fmac_f32_e32 v42, v117, v27
	v_cvt_pk_bf16_f32 v149, v26, v42
	ds_write_b32 v151, v149 offset:4896
	v_fmac_f32_e32 v25, v116, v26
	v_fmac_f32_e32 v41, v116, v42
	v_fmac_f32_e32 v25, v118, v42
	v_fmac_f32_e32 v41, v117, v26
	v_cvt_pk_bf16_f32 v148, v25, v41
	ds_write_b32 v151, v148 offset:4624
	v_fmac_f32_e32 v24, v116, v25
	v_fmac_f32_e32 v40, v116, v41
	v_fmac_f32_e32 v24, v118, v41
	v_fmac_f32_e32 v40, v117, v25
	v_cvt_pk_bf16_f32 v149, v24, v40
	ds_write_b32 v151, v149 offset:4352
	v_fmac_f32_e32 v55, v116, v24
	v_fmac_f32_e32 v71, v116, v40
	v_fmac_f32_e32 v55, v118, v40
	v_fmac_f32_e32 v71, v117, v24
	v_cvt_pk_bf16_f32 v148, v55, v71
	ds_write_b32 v151, v148 offset:4080
	v_fmac_f32_e32 v54, v116, v55
	v_fmac_f32_e32 v70, v116, v71
	v_fmac_f32_e32 v54, v118, v71
	v_fmac_f32_e32 v70, v117, v55
	v_cvt_pk_bf16_f32 v149, v54, v70
	ds_write_b32 v151, v149 offset:3808
	v_fmac_f32_e32 v53, v116, v54
	v_fmac_f32_e32 v69, v116, v70
	v_fmac_f32_e32 v53, v118, v70
	v_fmac_f32_e32 v69, v117, v54
	v_cvt_pk_bf16_f32 v148, v53, v69
	ds_write_b32 v151, v148 offset:3536
	v_fmac_f32_e32 v52, v116, v53
	v_fmac_f32_e32 v68, v116, v69
	v_fmac_f32_e32 v52, v118, v69
	v_fmac_f32_e32 v68, v117, v53
	v_cvt_pk_bf16_f32 v149, v52, v68
	ds_write_b32 v151, v149 offset:3264
	v_fmac_f32_e32 v23, v116, v52
	v_fmac_f32_e32 v39, v116, v68
	v_fmac_f32_e32 v23, v118, v68
	v_fmac_f32_e32 v39, v117, v52
	v_cvt_pk_bf16_f32 v148, v23, v39
	ds_write_b32 v151, v148 offset:2992
	v_fmac_f32_e32 v22, v116, v23
	v_fmac_f32_e32 v38, v116, v39
	v_fmac_f32_e32 v22, v118, v39
	v_fmac_f32_e32 v38, v117, v23
	v_cvt_pk_bf16_f32 v149, v22, v38
	ds_write_b32 v151, v149 offset:2720
	v_fmac_f32_e32 v21, v116, v22
	v_fmac_f32_e32 v37, v116, v38
	v_fmac_f32_e32 v21, v118, v38
	v_fmac_f32_e32 v37, v117, v22
	v_cvt_pk_bf16_f32 v148, v21, v37
	ds_write_b32 v151, v148 offset:2448
	v_fmac_f32_e32 v20, v116, v21
	v_fmac_f32_e32 v36, v116, v37
	v_fmac_f32_e32 v20, v118, v37
	v_fmac_f32_e32 v36, v117, v21
	v_cvt_pk_bf16_f32 v149, v20, v36
	ds_write_b32 v151, v149 offset:2176
	v_fmac_f32_e32 v51, v116, v20
	v_fmac_f32_e32 v67, v116, v36
	v_fmac_f32_e32 v51, v118, v36
	v_fmac_f32_e32 v67, v117, v20
	v_cvt_pk_bf16_f32 v148, v51, v67
	ds_write_b32 v151, v148 offset:1904
	v_fmac_f32_e32 v50, v116, v51
	v_fmac_f32_e32 v66, v116, v67
	v_fmac_f32_e32 v50, v118, v67
	v_fmac_f32_e32 v66, v117, v51
	v_cvt_pk_bf16_f32 v149, v50, v66
	ds_write_b32 v151, v149 offset:1632
	v_fmac_f32_e32 v49, v116, v50
	v_fmac_f32_e32 v65, v116, v66
	v_fmac_f32_e32 v49, v118, v66
	v_fmac_f32_e32 v65, v117, v50
	v_cvt_pk_bf16_f32 v148, v49, v65
	ds_write_b32 v151, v148 offset:1360
	v_fmac_f32_e32 v48, v116, v49
	v_fmac_f32_e32 v64, v116, v65
	v_fmac_f32_e32 v48, v118, v65
	v_fmac_f32_e32 v64, v117, v49
	v_cvt_pk_bf16_f32 v149, v48, v64
	ds_write_b32 v151, v149 offset:1088
	v_fmac_f32_e32 v19, v116, v48
	v_fmac_f32_e32 v35, v116, v64
	v_fmac_f32_e32 v19, v118, v64
	v_fmac_f32_e32 v35, v117, v48
	v_cvt_pk_bf16_f32 v148, v19, v35
	ds_write_b32 v151, v148 offset:816
	v_fmac_f32_e32 v18, v116, v19
	v_fmac_f32_e32 v34, v116, v35
	v_fmac_f32_e32 v18, v118, v35
	v_fmac_f32_e32 v34, v117, v19
	v_cvt_pk_bf16_f32 v149, v18, v34
	ds_write_b32 v151, v149 offset:544
	v_fmac_f32_e32 v17, v116, v18
	v_fmac_f32_e32 v33, v116, v34
	v_fmac_f32_e32 v17, v118, v34
	v_fmac_f32_e32 v33, v117, v18
	v_cvt_pk_bf16_f32 v148, v17, v33
	ds_write_b32 v151, v148 offset:272
	v_fmac_f32_e32 v16, v116, v17
	v_fmac_f32_e32 v32, v116, v33
	v_fmac_f32_e32 v16, v118, v33
	v_fmac_f32_e32 v32, v117, v17
	v_cvt_pk_bf16_f32 v149, v16, v32
	ds_write_b32 v151, v149
	v_mov_b32_e32 v120, v16
	v_mov_b32_e32 v121, v32
	ds_read_b128 v[124:127], v152
	ds_read_b128 v[128:131], v152 offset:64
	ds_read_b128 v[132:135], v152 offset:128
	ds_read_b128 v[136:139], v152 offset:192
	ds_read_b64 v[168:169], v171
	ds_read_b64 v[160:161], v163
	s_waitcnt lgkmcnt(5)
	v_mfma_f32_16x16x32_bf16 v[140:143], v[100:103], v[124:127], 0
	s_waitcnt lgkmcnt(4)
	v_mfma_f32_16x16x32_bf16 v[140:143], v[104:107], v[128:131], v[140:143]
	s_waitcnt lgkmcnt(3)
	v_mfma_f32_16x16x32_bf16 v[140:143], v[108:111], v[132:135], v[140:143]
	s_waitcnt lgkmcnt(2)
	v_mfma_f32_16x16x32_bf16 v[140:143], v[112:115], v[136:139], v[140:143]
	s_nop 9
	s_waitcnt lgkmcnt(0)
	v_lshlrev_b32_e32 v182, 16, v168
	v_and_b32_e32 v183, 0xffff0000, v168
	v_lshlrev_b32_e32 v184, 16, v169
	v_and_b32_e32 v185, 0xffff0000, v169
	v_add_f32_e32 v182, v182, v140
	v_add_f32_e32 v183, v183, v141
	v_add_f32_e32 v184, v184, v142
	v_add_f32_e32 v185, v185, v143
	v_lshlrev_b32_e32 v186, 16, v160
	v_and_b32_e32 v187, 0xffff0000, v160
	v_lshlrev_b32_e32 v188, 16, v161
	v_and_b32_e32 v189, 0xffff0000, v161
	v_fmac_f32_e32 v182, v164, v186
	v_fmac_f32_e32 v183, v165, v187
	v_fmac_f32_e32 v184, v166, v188
	v_fmac_f32_e32 v185, v167, v189
	v_mul_f32_e32 v186, v182, v182
	v_mul_f32_e32 v187, v183, v183
	v_mul_f32_e32 v188, v184, v184
	v_mul_f32_e32 v189, v185, v185
	v_fmaak_f32 v186, v1, v186, 0x40135761
	v_fmaak_f32 v187, v1, v187, 0x40135761
	v_fmaak_f32 v188, v1, v188, 0x40135761
	v_fmaak_f32 v189, v1, v189, 0x40135761
	v_mul_f32_e32 v186, v182, v186
	v_mul_f32_e32 v187, v183, v187
	v_mul_f32_e32 v188, v184, v188
	v_mul_f32_e32 v189, v185, v189
	v_exp_f32_e64 v186, -v186
	v_exp_f32_e64 v187, -v187
	v_exp_f32_e64 v188, -v188
	v_exp_f32_e64 v189, -v189
	v_add_f32_e32 v186, 1.0, v186
	v_add_f32_e32 v187, 1.0, v187
	v_add_f32_e32 v188, 1.0, v188
	v_add_f32_e32 v189, 1.0, v189
	v_rcp_f32_e32 v186, v186
	v_rcp_f32_e32 v187, v187
	v_rcp_f32_e32 v188, v188
	v_rcp_f32_e32 v189, v189
	v_mul_f32_e32 v182, v182, v186
	v_mul_f32_e32 v183, v183, v187
	v_mul_f32_e32 v184, v184, v188
	v_mul_f32_e32 v185, v185, v189
	v_cvt_pk_bf16_f32 v148, v182, v183
	v_cvt_pk_bf16_f32 v149, v184, v185
	global_store_dwordx2 v156, v[148:149], s[12:13]
	ds_read_b128 v[124:127], v152 offset:4352
	ds_read_b128 v[128:131], v152 offset:4416
	ds_read_b128 v[132:135], v152 offset:4480
	ds_read_b128 v[136:139], v152 offset:4544
	ds_read_b64 v[168:169], v171 offset:512
	ds_read_b64 v[160:161], v163 offset:512
	s_waitcnt lgkmcnt(5)
	v_mfma_f32_16x16x32_bf16 v[140:143], v[100:103], v[124:127], 0
	s_waitcnt lgkmcnt(4)
	v_mfma_f32_16x16x32_bf16 v[140:143], v[104:107], v[128:131], v[140:143]
	s_waitcnt lgkmcnt(3)
	v_mfma_f32_16x16x32_bf16 v[140:143], v[108:111], v[132:135], v[140:143]
	s_waitcnt lgkmcnt(2)
	v_mfma_f32_16x16x32_bf16 v[140:143], v[112:115], v[136:139], v[140:143]
	s_nop 9
	s_waitcnt lgkmcnt(0)
	v_lshlrev_b32_e32 v182, 16, v168
	v_and_b32_e32 v183, 0xffff0000, v168
	v_lshlrev_b32_e32 v184, 16, v169
	v_and_b32_e32 v185, 0xffff0000, v169
	v_add_f32_e32 v182, v182, v140
	v_add_f32_e32 v183, v183, v141
	v_add_f32_e32 v184, v184, v142
	v_add_f32_e32 v185, v185, v143
	v_lshlrev_b32_e32 v186, 16, v160
	v_and_b32_e32 v187, 0xffff0000, v160
	v_lshlrev_b32_e32 v188, 16, v161
	v_and_b32_e32 v189, 0xffff0000, v161
	v_fmac_f32_e32 v182, v164, v186
	v_fmac_f32_e32 v183, v165, v187
	v_fmac_f32_e32 v184, v166, v188
	v_fmac_f32_e32 v185, v167, v189
	v_mul_f32_e32 v186, v182, v182
	v_mul_f32_e32 v187, v183, v183
	v_mul_f32_e32 v188, v184, v184
	v_mul_f32_e32 v189, v185, v185
	v_fmaak_f32 v186, v1, v186, 0x40135761
	v_fmaak_f32 v187, v1, v187, 0x40135761
	v_fmaak_f32 v188, v1, v188, 0x40135761
	v_fmaak_f32 v189, v1, v189, 0x40135761
	v_mul_f32_e32 v186, v182, v186
	v_mul_f32_e32 v187, v183, v187
	v_mul_f32_e32 v188, v184, v188
	v_mul_f32_e32 v189, v185, v189
	v_exp_f32_e64 v186, -v186
	v_exp_f32_e64 v187, -v187
	v_exp_f32_e64 v188, -v188
	v_exp_f32_e64 v189, -v189
	v_add_f32_e32 v186, 1.0, v186
	v_add_f32_e32 v187, 1.0, v187
	v_add_f32_e32 v188, 1.0, v188
	v_add_f32_e32 v189, 1.0, v189
	v_rcp_f32_e32 v186, v186
	v_rcp_f32_e32 v187, v187
	v_rcp_f32_e32 v188, v188
	v_rcp_f32_e32 v189, v189
	v_mul_f32_e32 v182, v182, v186
	v_mul_f32_e32 v183, v183, v187
	v_mul_f32_e32 v184, v184, v188
	v_mul_f32_e32 v185, v185, v189
	v_cvt_pk_bf16_f32 v148, v182, v183
	v_cvt_pk_bf16_f32 v149, v184, v185
	global_store_dwordx2 v159, v[148:149], s[12:13]
	s_sub_u32 s12, s12, 65536
	s_subb_u32 s13, s13, 0
	s_sub_u32 s36, s36, 1024
	s_add_u32 s14, s14, 2
	s_cmp_lt_u32 s14, 8
	s_cbranch_scc1 .Lssm_tile_d1m2
	s_add_u32 s30, s30, 0x8000000
	s_add_u32 s16, s60, s30
	s_addc_u32 s17, s61, 0
	global_store_dword v180, v120, s[16:17]
	global_store_dword v170, v121, s[16:17]
	s_waitcnt vmcnt(0) lgkmcnt(0)
	s_add_u32 s27, s27, 1
	s_cmp_lt_u32 s27, 2
	s_cbranch_scc1 .Lssm_ctx_loop
